# K-loop back-edge rotation, SALU only: counter/pointer increments and exit compare moved before the closing barrier of the last MFMA segment (9 of 11 loops)
# baseline (speedup 1.0000x reference)
; #define PG8_STAGE(bufoff, gbase, voff) do { _Pragma("unroll") for (int _i = 0; _i < 2; ++_i) \
;         __builtin_amdgcn_global_load_lds((const unsigned*)((const char*)(gbase) + (voff)[_i]), (PG8_LAS unsigned*)(lds + (bufoff) + ldsw + _i * 8192), 16, 0, 0); } while (0)
; #define PG8_LDA(dst, b, h) do { _Pragma("unroll") for (int m = 0; m < 4; ++m) _Pragma("unroll") for (int k = 0; k < 2; ++k) dst[m][k] = *(const PG8_LAS bf16x8*)(lds + PG8_SA(b, h) + aoff + m * 2048 + k * 1024); } while (0)
; #define PG8_LDB(dst, b, h) do { _Pragma("unroll") for (int n = 0; n < 2; ++n) _Pragma("unroll") for (int k = 0; k < 2; ++k) dst[n][k] = *(const PG8_LAS bf16x8*)(lds + PG8_SB(b, h) + boff + n * 2048 + k * 1024); } while (0)
; #define PG8_MMA(ai, bj, At, Bt) do { __builtin_amdgcn_s_setprio(1); _Pragma("unroll") for (int m = 0; m < 4; ++m) _Pragma("unroll") for (int n = 0; n < 2; ++n) _Pragma("unroll") for (int k = 0; k < 2; ++k) \
;         acc[ai][bj][m][n] = __builtin_amdgcn_mfma_f32_16x16x32_bf16(Bt[n][k], At[m][k], acc[ai][bj][m][n], 0, 0, 0); __builtin_amdgcn_s_setprio(0); } while (0)
; #define PG8_WAIT_V(n) asm volatile("s_waitcnt vmcnt(" #n ")" ::: "memory")
; #define PG8_WAIT_L(n) asm volatile("s_waitcnt lgkmcnt(" #n ")" ::: "memory")
; template <class Epi, class Sched, bool ALIGN_EPI = false, bool SP2 = false>
; __device__ __forceinline__ void gemm_phase(PG8_LAS unsigned char* lds, const Gemm g, const Sched& S, const Epi& E) {
;     ...
;             const bool last = (t == nt - 2);
;             const char* a1 = cA + (size_t)(t + 1) * kstep;
;             const char* a2 = last ? nA : cA + (size_t)(t + 2) * kstep; const char* b2 = last ? nB : cB + (size_t)(t + 2) * kstep;
;             const char* a3 = a2 + kstep; const char* b3 = b2 + kstep;
;             if (last && has_next) S.a_ready(nxt);
;             if constexpr (SP2) {
;             PG8_LDB(B0, 0, 0); PG8_LDB(B1, 0, 1); PG8_SCHED; PG8_LDA(At, 0, 0); PG8_STAGE(PG8_SA(1, 1), a1 + hstepA, voffA);
;             PG8_WAIT_V(8); PG8_WAIT_L(0); PG8_BAR; PG8_MMA(0, 0, At, B0); PG8_MMA(0, 1, At, B1); PG8_BAR; PG8_SCHED;
;             PG8_LDA(At, 0, 1); PG8_STAGE(PG8_SB(0, 0), b2, voffB); PG8_STAGE(PG8_SB(0, 1), b2 + hstepB, voffB); PG8_STAGE(PG8_SA(0, 0), a2, voffA);
;             PG8_WAIT_V(8); PG8_WAIT_L(0); PG8_BAR; PG8_MMA(1, 0, At, B0); PG8_MMA(1, 1, At, B1); PG8_BAR; PG8_SCHED;
.LBB0_311:
	ds_read_b128 v[148:151], v176
	ds_read_b128 v[152:155], v176 offset:1024
	ds_read_b128 v[156:159], v176 offset:2048
	ds_read_b128 v[180:183], v176 offset:3072
	ds_read_b128 v[184:187], v177
	ds_read_b128 v[188:191], v177 offset:1024
	ds_read_b128 v[192:195], v177 offset:2048
	ds_read_b128 v[196:199], v177 offset:3072
	s_add_u32 s68, s6, 0xfff80080
	s_addc_u32 s69, s7, -1
	s_cmp_eq_u32 s78, 28
	s_cselect_b32 s71, s20, s69
	s_cselect_b32 s70, s33, s68
	s_cselect_b32 s69, s55, s77
	s_cselect_b32 s68, s61, s76
	s_add_i32 m0, s9, 0xc000
	ds_read_b128 v[200:203], v178
	ds_read_b128 v[204:207], v178 offset:1024
	ds_read_b128 v[208:211], v178 offset:2048
	ds_read_b128 v[212:215], v178 offset:3072
	ds_read_b128 v[216:219], v178 offset:4096
	ds_read_b128 v[220:223], v178 offset:5120
	ds_read_b128 v[224:227], v178 offset:6144
	ds_read_b128 v[228:231], v178 offset:7168
	global_load_lds_dwordx4 v140, s[6:7]
	s_add_i32 m0, s9, 0xe000
	s_nop 0
	global_load_lds_dwordx4 v142, s[6:7]
	s_waitcnt vmcnt(8)
	s_waitcnt lgkmcnt(0)
	s_barrier
	s_setprio 0
	s_waitcnt lgkmcnt(0)
	v_mfma_f32_16x16x32_bf16 v[124:127], v[148:151], v[200:203], v[124:127]
	v_mfma_f32_16x16x32_bf16 v[120:123], v[156:159], v[200:203], v[120:123]
	v_mfma_f32_16x16x32_bf16 v[108:111], v[148:151], v[208:211], v[108:111]
	v_mfma_f32_16x16x32_bf16 v[104:107], v[156:159], v[208:211], v[104:107]
	v_mfma_f32_16x16x32_bf16 v[92:95], v[148:151], v[216:219], v[92:95]
	v_mfma_f32_16x16x32_bf16 v[88:91], v[156:159], v[216:219], v[88:91]
	v_mfma_f32_16x16x32_bf16 v[76:79], v[148:151], v[224:227], v[76:79]
	v_mfma_f32_16x16x32_bf16 v[72:75], v[156:159], v[224:227], v[72:75]
	v_mfma_f32_16x16x32_bf16 v[124:127], v[152:155], v[204:207], v[124:127]
	v_mfma_f32_16x16x32_bf16 v[120:123], v[180:183], v[204:207], v[120:123]
	v_mfma_f32_16x16x32_bf16 v[108:111], v[152:155], v[212:215], v[108:111]
	v_mfma_f32_16x16x32_bf16 v[104:107], v[180:183], v[212:215], v[104:107]
	v_mfma_f32_16x16x32_bf16 v[92:95], v[152:155], v[220:223], v[92:95]
	v_mfma_f32_16x16x32_bf16 v[88:91], v[180:183], v[220:223], v[88:91]
	v_mfma_f32_16x16x32_bf16 v[76:79], v[152:155], v[228:231], v[76:79]
	v_mfma_f32_16x16x32_bf16 v[72:75], v[180:183], v[228:231], v[72:75]
	v_mfma_f32_16x16x32_bf16 v[116:119], v[184:187], v[200:203], v[116:119]
	v_mfma_f32_16x16x32_bf16 v[112:115], v[192:195], v[200:203], v[112:115]
	v_mfma_f32_16x16x32_bf16 v[100:103], v[184:187], v[208:211], v[100:103]
	v_mfma_f32_16x16x32_bf16 v[96:99], v[192:195], v[208:211], v[96:99]
	v_mfma_f32_16x16x32_bf16 v[84:87], v[184:187], v[216:219], v[84:87]
	v_mfma_f32_16x16x32_bf16 v[80:83], v[192:195], v[216:219], v[80:83]
	v_mfma_f32_16x16x32_bf16 v[68:71], v[184:187], v[224:227], v[68:71]
	v_mfma_f32_16x16x32_bf16 v[64:67], v[192:195], v[224:227], v[64:67]
	v_mfma_f32_16x16x32_bf16 v[116:119], v[188:191], v[204:207], v[116:119]
	v_mfma_f32_16x16x32_bf16 v[112:115], v[196:199], v[204:207], v[112:115]
	v_mfma_f32_16x16x32_bf16 v[100:103], v[188:191], v[212:215], v[100:103]
	v_mfma_f32_16x16x32_bf16 v[96:99], v[196:199], v[212:215], v[96:99]
	v_mfma_f32_16x16x32_bf16 v[84:87], v[188:191], v[220:223], v[84:87]
	v_mfma_f32_16x16x32_bf16 v[80:83], v[196:199], v[220:223], v[80:83]
	v_mfma_f32_16x16x32_bf16 v[68:71], v[188:191], v[228:231], v[68:71]
	v_mfma_f32_16x16x32_bf16 v[64:67], v[196:199], v[228:231], v[64:67]
	s_setprio 1
	s_barrier
	s_add_i32 s79, s72, s28
	v_lshl_add_u64 v[160:161], s[68:69], 0, v[130:131]
	s_mov_b32 m0, s79
	ds_read_b128 v[200:203], v178 offset:16384
	ds_read_b128 v[204:207], v178 offset:17408
	ds_read_b128 v[208:211], v178 offset:18432
	ds_read_b128 v[212:215], v178 offset:19456
	ds_read_b128 v[216:219], v178 offset:20480
	ds_read_b128 v[220:223], v178 offset:21504
	ds_read_b128 v[224:227], v178 offset:22528
	ds_read_b128 v[228:231], v178 offset:23552
	global_load_lds_dwordx4 v130, s[68:69]
	s_add_i32 m0, s79, 0x2000
	s_add_u32 s80, s68, 0x80000
	v_lshl_add_u64 v[232:233], s[68:69], 0, v[134:135]
	s_addc_u32 s81, s69, 0
	s_add_i32 s79, s73, s28
	global_load_lds_dwordx4 v134, s[68:69]
	s_mov_b32 m0, s79
	v_lshl_add_u64 v[236:237], s[70:71], 0, v[132:133]
	global_load_lds_dwordx4 v130, s[80:81]
	s_add_i32 m0, s79, 0x2000
	s_nop 0
	global_load_lds_dwordx4 v134, s[80:81]
	v_lshl_add_u64 v[234:235], s[70:71], 0, v[128:129]
	s_mov_b32 m0, s9
	s_nop 0
	global_load_lds_dwordx4 v128, s[70:71]
	s_mov_b32 m0, s19
	s_nop 0
	global_load_lds_dwordx4 v132, s[70:71]
	s_waitcnt vmcnt(8)
	s_waitcnt lgkmcnt(0)
	s_barrier
	s_setprio 0
	s_waitcnt lgkmcnt(0)
	v_mfma_f32_16x16x32_bf16 v[60:63], v[148:151], v[200:203], v[60:63]
	v_mfma_f32_16x16x32_bf16 v[56:59], v[156:159], v[200:203], v[56:59]
	v_mfma_f32_16x16x32_bf16 v[44:47], v[148:151], v[208:211], v[44:47]
	v_mfma_f32_16x16x32_bf16 v[40:43], v[156:159], v[208:211], v[40:43]
	v_mfma_f32_16x16x32_bf16 v[28:31], v[148:151], v[216:219], v[28:31]
	v_mfma_f32_16x16x32_bf16 v[24:27], v[156:159], v[216:219], v[24:27]
	v_mfma_f32_16x16x32_bf16 v[12:15], v[148:151], v[224:227], v[12:15]
	v_mfma_f32_16x16x32_bf16 v[8:11], v[156:159], v[224:227], v[8:11]
	v_mfma_f32_16x16x32_bf16 v[60:63], v[152:155], v[204:207], v[60:63]
	v_mfma_f32_16x16x32_bf16 v[56:59], v[180:183], v[204:207], v[56:59]
	v_mfma_f32_16x16x32_bf16 v[44:47], v[152:155], v[212:215], v[44:47]
	v_mfma_f32_16x16x32_bf16 v[40:43], v[180:183], v[212:215], v[40:43]
	v_mfma_f32_16x16x32_bf16 v[28:31], v[152:155], v[220:223], v[28:31]
	v_mfma_f32_16x16x32_bf16 v[24:27], v[180:183], v[220:223], v[24:27]
	v_mfma_f32_16x16x32_bf16 v[12:15], v[152:155], v[228:231], v[12:15]
	v_mfma_f32_16x16x32_bf16 v[8:11], v[180:183], v[228:231], v[8:11]
	v_mfma_f32_16x16x32_bf16 v[52:55], v[184:187], v[200:203], v[52:55]
	v_mfma_f32_16x16x32_bf16 v[48:51], v[192:195], v[200:203], v[48:51]
	v_mfma_f32_16x16x32_bf16 v[36:39], v[184:187], v[208:211], v[36:39]
	v_mfma_f32_16x16x32_bf16 v[32:35], v[192:195], v[208:211], v[32:35]
	v_mfma_f32_16x16x32_bf16 v[20:23], v[184:187], v[216:219], v[20:23]
	v_mfma_f32_16x16x32_bf16 v[16:19], v[192:195], v[216:219], v[16:19]
	v_mfma_f32_16x16x32_bf16 v[4:7], v[184:187], v[224:227], v[4:7]
	v_mfma_f32_16x16x32_bf16 v[0:3], v[192:195], v[224:227], v[0:3]
	v_mfma_f32_16x16x32_bf16 v[52:55], v[188:191], v[204:207], v[52:55]
	v_mfma_f32_16x16x32_bf16 v[48:51], v[196:199], v[204:207], v[48:51]
	v_mfma_f32_16x16x32_bf16 v[36:39], v[188:191], v[212:215], v[36:39]
	v_mfma_f32_16x16x32_bf16 v[32:35], v[196:199], v[212:215], v[32:35]
	v_mfma_f32_16x16x32_bf16 v[20:23], v[188:191], v[220:223], v[20:23]
	v_mfma_f32_16x16x32_bf16 v[16:19], v[196:199], v[220:223], v[16:19]
	v_mfma_f32_16x16x32_bf16 v[4:7], v[188:191], v[228:231], v[4:7]
	v_mfma_f32_16x16x32_bf16 v[0:3], v[196:199], v[228:231], v[0:3]
	s_setprio 1
	s_barrier
; #define PG8_STAGE(bufoff, gbase, voff) do { _Pragma("unroll") for (int _i = 0; _i < 2; ++_i) \
;         __builtin_amdgcn_global_load_lds((const unsigned*)((const char*)(gbase) + (voff)[_i]), (PG8_LAS unsigned*)(lds + (bufoff) + ldsw + _i * 8192), 16, 0, 0); } while (0)
; #define PG8_LDA(dst, b, h) do { _Pragma("unroll") for (int m = 0; m < 4; ++m) _Pragma("unroll") for (int k = 0; k < 2; ++k) dst[m][k] = *(const PG8_LAS bf16x8*)(lds + PG8_SA(b, h) + aoff + m * 2048 + k * 1024); } while (0)
; #define PG8_LDB(dst, b, h) do { _Pragma("unroll") for (int n = 0; n < 2; ++n) _Pragma("unroll") for (int k = 0; k < 2; ++k) dst[n][k] = *(const PG8_LAS bf16x8*)(lds + PG8_SB(b, h) + boff + n * 2048 + k * 1024); } while (0)
; #define PG8_MMA(ai, bj, At, Bt) do { __builtin_amdgcn_s_setprio(1); _Pragma("unroll") for (int m = 0; m < 4; ++m) _Pragma("unroll") for (int n = 0; n < 2; ++n) _Pragma("unroll") for (int k = 0; k < 2; ++k) \
;         acc[ai][bj][m][n] = __builtin_amdgcn_mfma_f32_16x16x32_bf16(Bt[n][k], At[m][k], acc[ai][bj][m][n], 0, 0, 0); __builtin_amdgcn_s_setprio(0); } while (0)
; #define PG8_WAIT_V(n) asm volatile("s_waitcnt vmcnt(" #n ")" ::: "memory")
; #define PG8_WAIT_L(n) asm volatile("s_waitcnt lgkmcnt(" #n ")" ::: "memory")
; #define PG8_BAR __builtin_amdgcn_s_barrier()
; #define PG8_SCHED __builtin_amdgcn_sched_barrier(0)
; template <class Epi, class Sched, bool ALIGN_EPI = false, bool SP2 = false>
; __device__ __forceinline__ void gemm_phase(PG8_LAS unsigned char* lds, const Gemm g, const Sched& S, const Epi& E) {
;     ...
;         for (int t = 0; t < nt; t += 2) {
;     ...
;             PG8_LDB(B0, 1, 0); PG8_LDB(B1, 1, 1); PG8_SCHED; PG8_LDA(At, 1, 0); PG8_STAGE(PG8_SA(0, 1), a2 + hstepA, voffA);
;             PG8_WAIT_V(8); PG8_WAIT_L(0); PG8_BAR; PG8_MMA(0, 0, At, B0); PG8_MMA(0, 1, At, B1); PG8_BAR; PG8_SCHED;
;             PG8_LDA(At, 1, 1); PG8_STAGE(PG8_SB(1, 0), b3, voffB); PG8_STAGE(PG8_SB(1, 1), b3 + hstepB, voffB); PG8_STAGE(PG8_SA(1, 0), a3, voffA);
;             PG8_WAIT_V(8); PG8_WAIT_L(0); PG8_BAR; PG8_MMA(1, 0, At, B0); PG8_MMA(1, 1, At, B1); PG8_BAR; PG8_SCHED;
	s_add_i32 s79, 0, 0x18000
	v_add_u32_e32 v138, s79, v174
	s_add_i32 s80, 0, 0x1c000
	ds_read_b128 v[148:151], v138
	ds_read_b128 v[152:155], v138 offset:1024
	ds_read_b128 v[156:159], v138 offset:2048
	ds_read_b128 v[180:183], v138 offset:3072
	v_add_u32_e32 v138, s80, v174
	ds_read_b128 v[184:187], v138
	ds_read_b128 v[188:191], v138 offset:1024
	ds_read_b128 v[192:195], v138 offset:2048
	ds_read_b128 v[196:199], v138 offset:3072
	s_add_u32 s70, s70, 0x80000
	s_addc_u32 s71, s71, 0
	s_mov_b32 m0, s29
	ds_read_b128 v[200:203], v178 offset:32768
	ds_read_b128 v[204:207], v178 offset:33792
	ds_read_b128 v[208:211], v178 offset:34816
	ds_read_b128 v[212:215], v178 offset:35840
	ds_read_b128 v[216:219], v178 offset:36864
	ds_read_b128 v[220:223], v178 offset:37888
	ds_read_b128 v[224:227], v178 offset:38912
	ds_read_b128 v[228:231], v178 offset:39936
	global_load_lds_dwordx4 v128, s[70:71]
	s_mov_b32 m0, s30
	s_nop 0
	global_load_lds_dwordx4 v132, s[70:71]
	s_waitcnt vmcnt(8)
	s_waitcnt lgkmcnt(0)
	s_barrier
	s_setprio 0
	s_waitcnt lgkmcnt(0)
	v_mfma_f32_16x16x32_bf16 v[124:127], v[148:151], v[200:203], v[124:127]
	v_mfma_f32_16x16x32_bf16 v[120:123], v[156:159], v[200:203], v[120:123]
	v_mfma_f32_16x16x32_bf16 v[108:111], v[148:151], v[208:211], v[108:111]
	v_mfma_f32_16x16x32_bf16 v[104:107], v[156:159], v[208:211], v[104:107]
	v_mfma_f32_16x16x32_bf16 v[92:95], v[148:151], v[216:219], v[92:95]
	v_mfma_f32_16x16x32_bf16 v[88:91], v[156:159], v[216:219], v[88:91]
	v_mfma_f32_16x16x32_bf16 v[76:79], v[148:151], v[224:227], v[76:79]
	v_mfma_f32_16x16x32_bf16 v[72:75], v[156:159], v[224:227], v[72:75]
	v_mfma_f32_16x16x32_bf16 v[124:127], v[152:155], v[204:207], v[124:127]
	v_mfma_f32_16x16x32_bf16 v[120:123], v[180:183], v[204:207], v[120:123]
	v_mfma_f32_16x16x32_bf16 v[108:111], v[152:155], v[212:215], v[108:111]
	v_mfma_f32_16x16x32_bf16 v[104:107], v[180:183], v[212:215], v[104:107]
	v_mfma_f32_16x16x32_bf16 v[92:95], v[152:155], v[220:223], v[92:95]
	v_mfma_f32_16x16x32_bf16 v[88:91], v[180:183], v[220:223], v[88:91]
	v_mfma_f32_16x16x32_bf16 v[76:79], v[152:155], v[228:231], v[76:79]
	v_mfma_f32_16x16x32_bf16 v[72:75], v[180:183], v[228:231], v[72:75]
	v_mfma_f32_16x16x32_bf16 v[116:119], v[184:187], v[200:203], v[116:119]
	v_mfma_f32_16x16x32_bf16 v[112:115], v[192:195], v[200:203], v[112:115]
	v_mfma_f32_16x16x32_bf16 v[100:103], v[184:187], v[208:211], v[100:103]
	v_mfma_f32_16x16x32_bf16 v[96:99], v[192:195], v[208:211], v[96:99]
	v_mfma_f32_16x16x32_bf16 v[84:87], v[184:187], v[216:219], v[84:87]
	v_mfma_f32_16x16x32_bf16 v[80:83], v[192:195], v[216:219], v[80:83]
	v_mfma_f32_16x16x32_bf16 v[68:71], v[184:187], v[224:227], v[68:71]
	v_mfma_f32_16x16x32_bf16 v[64:67], v[192:195], v[224:227], v[64:67]
	v_mfma_f32_16x16x32_bf16 v[116:119], v[188:191], v[204:207], v[116:119]
	v_mfma_f32_16x16x32_bf16 v[112:115], v[196:199], v[204:207], v[112:115]
	v_mfma_f32_16x16x32_bf16 v[100:103], v[188:191], v[212:215], v[100:103]
	v_mfma_f32_16x16x32_bf16 v[96:99], v[196:199], v[212:215], v[96:99]
	v_mfma_f32_16x16x32_bf16 v[84:87], v[188:191], v[220:223], v[84:87]
	v_mfma_f32_16x16x32_bf16 v[80:83], v[196:199], v[220:223], v[80:83]
	v_mfma_f32_16x16x32_bf16 v[68:71], v[188:191], v[228:231], v[68:71]
	v_mfma_f32_16x16x32_bf16 v[64:67], v[196:199], v[228:231], v[64:67]
	s_setprio 1
	s_barrier
	s_add_i32 s70, s79, s28
	v_lshl_add_u64 v[160:161], v[160:161], 0, s[46:47]
	s_mov_b32 m0, s70
	ds_read_b128 v[200:203], v178 offset:49152
	ds_read_b128 v[204:207], v178 offset:50176
	ds_read_b128 v[208:211], v178 offset:51200
	ds_read_b128 v[212:215], v178 offset:52224
	ds_read_b128 v[216:219], v178 offset:53248
	ds_read_b128 v[220:223], v178 offset:54272
	ds_read_b128 v[224:227], v178 offset:55296
	ds_read_b128 v[228:231], v178 offset:56320
	global_load_lds_dwordx4 v[160:161], off
	s_add_i32 m0, s70, 0x2000
	s_add_u32 s68, s68, 0x80080
	v_lshl_add_u64 v[160:161], v[232:233], 0, s[46:47]
	s_addc_u32 s69, s69, 0
	s_add_i32 s70, s80, s28
	global_load_lds_dwordx4 v[160:161], off
	s_mov_b32 m0, s70
	s_nop 0
	global_load_lds_dwordx4 v130, s[68:69]
	s_add_i32 m0, s70, 0x2000
	s_nop 0
	global_load_lds_dwordx4 v134, s[68:69]
	v_lshl_add_u64 v[160:161], v[234:235], 0, s[46:47]
	s_mov_b32 m0, s34
	s_nop 0
	global_load_lds_dwordx4 v[160:161], off
	v_lshl_add_u64 v[160:161], v[236:237], 0, s[46:47]
	s_mov_b32 m0, s35
	s_nop 0
	global_load_lds_dwordx4 v[160:161], off
	s_waitcnt vmcnt(8)
	s_waitcnt lgkmcnt(0)
	s_barrier
	s_setprio 0
	s_waitcnt lgkmcnt(0)
	v_mfma_f32_16x16x32_bf16 v[60:63], v[148:151], v[200:203], v[60:63]
	v_mfma_f32_16x16x32_bf16 v[56:59], v[156:159], v[200:203], v[56:59]
	v_mfma_f32_16x16x32_bf16 v[44:47], v[148:151], v[208:211], v[44:47]
	v_mfma_f32_16x16x32_bf16 v[40:43], v[156:159], v[208:211], v[40:43]
	v_mfma_f32_16x16x32_bf16 v[28:31], v[148:151], v[216:219], v[28:31]
	v_mfma_f32_16x16x32_bf16 v[24:27], v[156:159], v[216:219], v[24:27]
	v_mfma_f32_16x16x32_bf16 v[12:15], v[148:151], v[224:227], v[12:15]
	v_mfma_f32_16x16x32_bf16 v[8:11], v[156:159], v[224:227], v[8:11]
	v_mfma_f32_16x16x32_bf16 v[60:63], v[152:155], v[204:207], v[60:63]
	v_mfma_f32_16x16x32_bf16 v[56:59], v[180:183], v[204:207], v[56:59]
	v_mfma_f32_16x16x32_bf16 v[44:47], v[152:155], v[212:215], v[44:47]
	v_mfma_f32_16x16x32_bf16 v[40:43], v[180:183], v[212:215], v[40:43]
	v_mfma_f32_16x16x32_bf16 v[28:31], v[152:155], v[220:223], v[28:31]
	v_mfma_f32_16x16x32_bf16 v[24:27], v[180:183], v[220:223], v[24:27]
	v_mfma_f32_16x16x32_bf16 v[12:15], v[152:155], v[228:231], v[12:15]
	v_mfma_f32_16x16x32_bf16 v[8:11], v[180:183], v[228:231], v[8:11]
	v_mfma_f32_16x16x32_bf16 v[52:55], v[184:187], v[200:203], v[52:55]
	v_mfma_f32_16x16x32_bf16 v[48:51], v[192:195], v[200:203], v[48:51]
	v_mfma_f32_16x16x32_bf16 v[36:39], v[184:187], v[208:211], v[36:39]
	v_mfma_f32_16x16x32_bf16 v[32:35], v[192:195], v[208:211], v[32:35]
	v_mfma_f32_16x16x32_bf16 v[20:23], v[184:187], v[216:219], v[20:23]
	v_mfma_f32_16x16x32_bf16 v[16:19], v[192:195], v[216:219], v[16:19]
	v_mfma_f32_16x16x32_bf16 v[4:7], v[184:187], v[224:227], v[4:7]
	v_mfma_f32_16x16x32_bf16 v[0:3], v[192:195], v[224:227], v[0:3]
	v_mfma_f32_16x16x32_bf16 v[52:55], v[188:191], v[204:207], v[52:55]
	v_mfma_f32_16x16x32_bf16 v[48:51], v[196:199], v[204:207], v[48:51]
	v_mfma_f32_16x16x32_bf16 v[36:39], v[188:191], v[212:215], v[36:39]
	v_mfma_f32_16x16x32_bf16 v[32:35], v[196:199], v[212:215], v[32:35]
	v_mfma_f32_16x16x32_bf16 v[20:23], v[188:191], v[220:223], v[20:23]
	v_mfma_f32_16x16x32_bf16 v[16:19], v[196:199], v[220:223], v[16:19]
	v_mfma_f32_16x16x32_bf16 v[4:7], v[188:191], v[228:231], v[4:7]
	v_mfma_f32_16x16x32_bf16 v[0:3], v[196:199], v[228:231], v[0:3]
	s_add_i32 s78, s78, 2
	s_add_u32 s6, s6, 0x100
	s_addc_u32 s7, s7, 0
	s_add_u32 s76, s76, 0x100
	s_addc_u32 s77, s77, 0
	s_cmp_gt_u32 s78, 29
	s_setprio 1
	s_barrier
	s_cbranch_scc0 .LBB0_311
	s_and_b64 vcc, exec, s[48:49]
	s_cbranch_vccz .LBB0_314
	s_barrier

; #define PG8_STAGE(bufoff, gbase, voff) do { _Pragma("unroll") for (int _i = 0; _i < 2; ++_i) \
;         __builtin_amdgcn_global_load_lds((const unsigned*)((const char*)(gbase) + (voff)[_i]), (PG8_LAS unsigned*)(lds + (bufoff) + ldsw + _i * 8192), 16, 0, 0); } while (0)
; #define PG8_LDA(dst, b, h) do { _Pragma("unroll") for (int m = 0; m < 4; ++m) _Pragma("unroll") for (int k = 0; k < 2; ++k) dst[m][k] = *(const PG8_LAS bf16x8*)(lds + PG8_SA(b, h) + aoff + m * 2048 + k * 1024); } while (0)
; #define PG8_LDB(dst, b, h) do { _Pragma("unroll") for (int n = 0; n < 2; ++n) _Pragma("unroll") for (int k = 0; k < 2; ++k) dst[n][k] = *(const PG8_LAS bf16x8*)(lds + PG8_SB(b, h) + boff + n * 2048 + k * 1024); } while (0)
; #define PG8_MMA(ai, bj, At, Bt) do { __builtin_amdgcn_s_setprio(1); _Pragma("unroll") for (int m = 0; m < 4; ++m) _Pragma("unroll") for (int n = 0; n < 2; ++n) _Pragma("unroll") for (int k = 0; k < 2; ++k) \
;         acc[ai][bj][m][n] = __builtin_amdgcn_mfma_f32_16x16x32_bf16(Bt[n][k], At[m][k], acc[ai][bj][m][n], 0, 0, 0); __builtin_amdgcn_s_setprio(0); } while (0)
; #define PG8_WAIT_V(n) asm volatile("s_waitcnt vmcnt(" #n ")" ::: "memory")
; #define PG8_WAIT_L(n) asm volatile("s_waitcnt lgkmcnt(" #n ")" ::: "memory")
; template <class Epi, class Sched, bool ALIGN_EPI = false, bool SP2 = false>
; __device__ __forceinline__ void gemm_phase(PG8_LAS unsigned char* lds, const Gemm g, const Sched& S, const Epi& E) {
;     ...
;             const bool last = (t == nt - 2);
;             const char* a1 = cA + (size_t)(t + 1) * kstep;
;             const char* a2 = last ? nA : cA + (size_t)(t + 2) * kstep; const char* b2 = last ? nB : cB + (size_t)(t + 2) * kstep;
;             const char* a3 = a2 + kstep; const char* b3 = b2 + kstep;
;             if (last && has_next) S.a_ready(nxt);
;             if constexpr (SP2) {
;             PG8_LDB(B0, 0, 0); PG8_LDB(B1, 0, 1); PG8_SCHED; PG8_LDA(At, 0, 0); PG8_STAGE(PG8_SA(1, 1), a1 + hstepA, voffA);
;             PG8_WAIT_V(8); PG8_WAIT_L(0); PG8_BAR; PG8_MMA(0, 0, At, B0); PG8_MMA(0, 1, At, B1); PG8_BAR; PG8_SCHED;
;             PG8_LDA(At, 0, 1); PG8_STAGE(PG8_SB(0, 0), b2, voffB); PG8_STAGE(PG8_SB(0, 1), b2 + hstepB, voffB); PG8_STAGE(PG8_SA(0, 0), a2, voffA);
;             PG8_WAIT_V(8); PG8_WAIT_L(0); PG8_BAR; PG8_MMA(1, 0, At, B0); PG8_MMA(1, 1, At, B1); PG8_BAR; PG8_SCHED;
.LBB0_497:
	ds_read_b128 v[146:149], v155
	ds_read_b128 v[158:161], v155 offset:1024
	ds_read_b128 v[168:171], v155 offset:2048
	ds_read_b128 v[172:175], v155 offset:3072
	ds_read_b128 v[176:179], v156
	ds_read_b128 v[180:183], v156 offset:1024
	ds_read_b128 v[184:187], v156 offset:2048
	ds_read_b128 v[188:191], v156 offset:3072
	s_add_u32 s41, s54, 0xfff80080
	s_addc_u32 s43, s55, -1
	s_cmp_eq_u32 s34, 28
	s_cselect_b32 s63, s7, s43
	s_cselect_b32 s62, s28, s41
	s_cselect_b32 s61, s29, s33
	s_cselect_b32 s60, s30, s31
	s_add_i32 m0, s69, 0xc000
	ds_read_b128 v[192:195], v157
	ds_read_b128 v[196:199], v157 offset:1024
	ds_read_b128 v[200:203], v157 offset:2048
	ds_read_b128 v[204:207], v157 offset:3072
	ds_read_b128 v[208:211], v157 offset:4096
	ds_read_b128 v[212:215], v157 offset:5120
	ds_read_b128 v[216:219], v157 offset:6144
	ds_read_b128 v[220:223], v157 offset:7168
	global_load_lds_dwordx4 v138, s[54:55]
	s_add_i32 m0, s69, 0xe000
	s_nop 0
	global_load_lds_dwordx4 v140, s[54:55]
	s_waitcnt vmcnt(8)
	s_waitcnt lgkmcnt(0)
	s_barrier
	s_setprio 0
	s_waitcnt lgkmcnt(0)
	v_mfma_f32_16x16x32_bf16 v[124:127], v[146:149], v[192:195], v[124:127]
	v_mfma_f32_16x16x32_bf16 v[120:123], v[168:171], v[192:195], v[120:123]
	v_mfma_f32_16x16x32_bf16 v[108:111], v[146:149], v[200:203], v[108:111]
	v_mfma_f32_16x16x32_bf16 v[104:107], v[168:171], v[200:203], v[104:107]
	v_mfma_f32_16x16x32_bf16 v[92:95], v[146:149], v[208:211], v[92:95]
	v_mfma_f32_16x16x32_bf16 v[88:91], v[168:171], v[208:211], v[88:91]
	v_mfma_f32_16x16x32_bf16 v[76:79], v[146:149], v[216:219], v[76:79]
	v_mfma_f32_16x16x32_bf16 v[72:75], v[168:171], v[216:219], v[72:75]
	v_mfma_f32_16x16x32_bf16 v[124:127], v[158:161], v[196:199], v[124:127]
	v_mfma_f32_16x16x32_bf16 v[120:123], v[172:175], v[196:199], v[120:123]
	v_mfma_f32_16x16x32_bf16 v[108:111], v[158:161], v[204:207], v[108:111]
	v_mfma_f32_16x16x32_bf16 v[104:107], v[172:175], v[204:207], v[104:107]
	v_mfma_f32_16x16x32_bf16 v[92:95], v[158:161], v[212:215], v[92:95]
	v_mfma_f32_16x16x32_bf16 v[88:91], v[172:175], v[212:215], v[88:91]
	v_mfma_f32_16x16x32_bf16 v[76:79], v[158:161], v[220:223], v[76:79]
	v_mfma_f32_16x16x32_bf16 v[72:75], v[172:175], v[220:223], v[72:75]
	v_mfma_f32_16x16x32_bf16 v[116:119], v[176:179], v[192:195], v[116:119]
	v_mfma_f32_16x16x32_bf16 v[112:115], v[184:187], v[192:195], v[112:115]
	v_mfma_f32_16x16x32_bf16 v[100:103], v[176:179], v[200:203], v[100:103]
	v_mfma_f32_16x16x32_bf16 v[96:99], v[184:187], v[200:203], v[96:99]
	v_mfma_f32_16x16x32_bf16 v[84:87], v[176:179], v[208:211], v[84:87]
	v_mfma_f32_16x16x32_bf16 v[80:83], v[184:187], v[208:211], v[80:83]
	v_mfma_f32_16x16x32_bf16 v[68:71], v[176:179], v[216:219], v[68:71]
	v_mfma_f32_16x16x32_bf16 v[64:67], v[184:187], v[216:219], v[64:67]
	v_mfma_f32_16x16x32_bf16 v[116:119], v[180:183], v[196:199], v[116:119]
	v_mfma_f32_16x16x32_bf16 v[112:115], v[188:191], v[196:199], v[112:115]
	v_mfma_f32_16x16x32_bf16 v[100:103], v[180:183], v[204:207], v[100:103]
	v_mfma_f32_16x16x32_bf16 v[96:99], v[188:191], v[204:207], v[96:99]
	v_mfma_f32_16x16x32_bf16 v[84:87], v[180:183], v[212:215], v[84:87]
	v_mfma_f32_16x16x32_bf16 v[80:83], v[188:191], v[212:215], v[80:83]
	v_mfma_f32_16x16x32_bf16 v[68:71], v[180:183], v[220:223], v[68:71]
	v_mfma_f32_16x16x32_bf16 v[64:67], v[188:191], v[220:223], v[64:67]
	s_setprio 1
	s_barrier
	s_add_i32 s41, s81, s68
	v_lshl_add_u64 v[150:151], s[60:61], 0, v[130:131]
	s_mov_b32 m0, s41
	ds_read_b128 v[192:195], v157 offset:16384
	ds_read_b128 v[196:199], v157 offset:17408
	ds_read_b128 v[200:203], v157 offset:18432
	ds_read_b128 v[204:207], v157 offset:19456
	ds_read_b128 v[208:211], v157 offset:20480
	ds_read_b128 v[212:215], v157 offset:21504
	ds_read_b128 v[216:219], v157 offset:22528
	ds_read_b128 v[220:223], v157 offset:23552
	global_load_lds_dwordx4 v130, s[60:61]
	s_add_i32 m0, s41, 0x2000
	s_add_u32 s84, s60, 0x80000
	v_lshl_add_u64 v[224:225], s[60:61], 0, v[134:135]
	s_addc_u32 s85, s61, 0
	s_add_i32 s41, s82, s68
	global_load_lds_dwordx4 v134, s[60:61]
	s_mov_b32 m0, s41
	v_lshl_add_u64 v[228:229], s[62:63], 0, v[132:133]
	global_load_lds_dwordx4 v130, s[84:85]
	s_add_i32 m0, s41, 0x2000
	s_nop 0
	global_load_lds_dwordx4 v134, s[84:85]
	v_lshl_add_u64 v[226:227], s[62:63], 0, v[128:129]
	s_mov_b32 m0, s69
	s_nop 0
	global_load_lds_dwordx4 v128, s[62:63]
	s_mov_b32 m0, s70
	s_nop 0
	global_load_lds_dwordx4 v132, s[62:63]
	s_waitcnt vmcnt(8)
	s_waitcnt lgkmcnt(0)
	s_barrier
	s_setprio 0
	s_waitcnt lgkmcnt(0)
	v_mfma_f32_16x16x32_bf16 v[60:63], v[146:149], v[192:195], v[60:63]
	v_mfma_f32_16x16x32_bf16 v[56:59], v[168:171], v[192:195], v[56:59]
	v_mfma_f32_16x16x32_bf16 v[44:47], v[146:149], v[200:203], v[44:47]
	v_mfma_f32_16x16x32_bf16 v[40:43], v[168:171], v[200:203], v[40:43]
	v_mfma_f32_16x16x32_bf16 v[28:31], v[146:149], v[208:211], v[28:31]
	v_mfma_f32_16x16x32_bf16 v[24:27], v[168:171], v[208:211], v[24:27]
	v_mfma_f32_16x16x32_bf16 v[12:15], v[146:149], v[216:219], v[12:15]
	v_mfma_f32_16x16x32_bf16 v[8:11], v[168:171], v[216:219], v[8:11]
	v_mfma_f32_16x16x32_bf16 v[60:63], v[158:161], v[196:199], v[60:63]
	v_mfma_f32_16x16x32_bf16 v[56:59], v[172:175], v[196:199], v[56:59]
	v_mfma_f32_16x16x32_bf16 v[44:47], v[158:161], v[204:207], v[44:47]
	v_mfma_f32_16x16x32_bf16 v[40:43], v[172:175], v[204:207], v[40:43]
	v_mfma_f32_16x16x32_bf16 v[28:31], v[158:161], v[212:215], v[28:31]
	v_mfma_f32_16x16x32_bf16 v[24:27], v[172:175], v[212:215], v[24:27]
	v_mfma_f32_16x16x32_bf16 v[12:15], v[158:161], v[220:223], v[12:15]
	v_mfma_f32_16x16x32_bf16 v[8:11], v[172:175], v[220:223], v[8:11]
	v_mfma_f32_16x16x32_bf16 v[52:55], v[176:179], v[192:195], v[52:55]
	v_mfma_f32_16x16x32_bf16 v[48:51], v[184:187], v[192:195], v[48:51]
	v_mfma_f32_16x16x32_bf16 v[36:39], v[176:179], v[200:203], v[36:39]
	v_mfma_f32_16x16x32_bf16 v[32:35], v[184:187], v[200:203], v[32:35]
	v_mfma_f32_16x16x32_bf16 v[20:23], v[176:179], v[208:211], v[20:23]
	v_mfma_f32_16x16x32_bf16 v[16:19], v[184:187], v[208:211], v[16:19]
	v_mfma_f32_16x16x32_bf16 v[4:7], v[176:179], v[216:219], v[4:7]
	v_mfma_f32_16x16x32_bf16 v[0:3], v[184:187], v[216:219], v[0:3]
	v_mfma_f32_16x16x32_bf16 v[52:55], v[180:183], v[196:199], v[52:55]
	v_mfma_f32_16x16x32_bf16 v[48:51], v[188:191], v[196:199], v[48:51]
	v_mfma_f32_16x16x32_bf16 v[36:39], v[180:183], v[204:207], v[36:39]
	v_mfma_f32_16x16x32_bf16 v[32:35], v[188:191], v[204:207], v[32:35]
	v_mfma_f32_16x16x32_bf16 v[20:23], v[180:183], v[212:215], v[20:23]
	v_mfma_f32_16x16x32_bf16 v[16:19], v[188:191], v[212:215], v[16:19]
	v_mfma_f32_16x16x32_bf16 v[4:7], v[180:183], v[220:223], v[4:7]
	v_mfma_f32_16x16x32_bf16 v[0:3], v[188:191], v[220:223], v[0:3]
	s_setprio 1
	s_barrier
; #define PG8_STAGE(bufoff, gbase, voff) do { _Pragma("unroll") for (int _i = 0; _i < 2; ++_i) \
;         __builtin_amdgcn_global_load_lds((const unsigned*)((const char*)(gbase) + (voff)[_i]), (PG8_LAS unsigned*)(lds + (bufoff) + ldsw + _i * 8192), 16, 0, 0); } while (0)
; #define PG8_LDA(dst, b, h) do { _Pragma("unroll") for (int m = 0; m < 4; ++m) _Pragma("unroll") for (int k = 0; k < 2; ++k) dst[m][k] = *(const PG8_LAS bf16x8*)(lds + PG8_SA(b, h) + aoff + m * 2048 + k * 1024); } while (0)
; #define PG8_LDB(dst, b, h) do { _Pragma("unroll") for (int n = 0; n < 2; ++n) _Pragma("unroll") for (int k = 0; k < 2; ++k) dst[n][k] = *(const PG8_LAS bf16x8*)(lds + PG8_SB(b, h) + boff + n * 2048 + k * 1024); } while (0)
; #define PG8_MMA(ai, bj, At, Bt) do { __builtin_amdgcn_s_setprio(1); _Pragma("unroll") for (int m = 0; m < 4; ++m) _Pragma("unroll") for (int n = 0; n < 2; ++n) _Pragma("unroll") for (int k = 0; k < 2; ++k) \
;         acc[ai][bj][m][n] = __builtin_amdgcn_mfma_f32_16x16x32_bf16(Bt[n][k], At[m][k], acc[ai][bj][m][n], 0, 0, 0); __builtin_amdgcn_s_setprio(0); } while (0)
; #define PG8_WAIT_V(n) asm volatile("s_waitcnt vmcnt(" #n ")" ::: "memory")
; #define PG8_WAIT_L(n) asm volatile("s_waitcnt lgkmcnt(" #n ")" ::: "memory")
; #define PG8_BAR __builtin_amdgcn_s_barrier()
; #define PG8_SCHED __builtin_amdgcn_sched_barrier(0)
; template <class Epi, class Sched, bool ALIGN_EPI = false, bool SP2 = false>
; __device__ __forceinline__ void gemm_phase(PG8_LAS unsigned char* lds, const Gemm g, const Sched& S, const Epi& E) {
;     ...
;         for (int t = 0; t < nt; t += 2) {
;     ...
;             PG8_LDB(B0, 1, 0); PG8_LDB(B1, 1, 1); PG8_SCHED; PG8_LDA(At, 1, 0); PG8_STAGE(PG8_SA(0, 1), a2 + hstepA, voffA);
;             PG8_WAIT_V(8); PG8_WAIT_L(0); PG8_BAR; PG8_MMA(0, 0, At, B0); PG8_MMA(0, 1, At, B1); PG8_BAR; PG8_SCHED;
;             PG8_LDA(At, 1, 1); PG8_STAGE(PG8_SB(1, 0), b3, voffB); PG8_STAGE(PG8_SB(1, 1), b3 + hstepB, voffB); PG8_STAGE(PG8_SA(1, 0), a3, voffA);
;             PG8_WAIT_V(8); PG8_WAIT_L(0); PG8_BAR; PG8_MMA(1, 0, At, B0); PG8_MMA(1, 1, At, B1); PG8_BAR; PG8_SCHED;
	s_add_i32 s41, 0, 0x18000
	v_add_u32_e32 v136, s41, v153
	s_add_i32 s43, 0, 0x1c000
	ds_read_b128 v[146:149], v136
	ds_read_b128 v[158:161], v136 offset:1024
	ds_read_b128 v[168:171], v136 offset:2048
	ds_read_b128 v[172:175], v136 offset:3072
	v_add_u32_e32 v136, s43, v153
	ds_read_b128 v[176:179], v136
	ds_read_b128 v[180:183], v136 offset:1024
	ds_read_b128 v[184:187], v136 offset:2048
	ds_read_b128 v[188:191], v136 offset:3072
	s_add_u32 s62, s62, 0x80000
	s_addc_u32 s63, s63, 0
	s_mov_b32 m0, s71
	ds_read_b128 v[192:195], v157 offset:32768
	ds_read_b128 v[196:199], v157 offset:33792
	ds_read_b128 v[200:203], v157 offset:34816
	ds_read_b128 v[204:207], v157 offset:35840
	ds_read_b128 v[208:211], v157 offset:36864
	ds_read_b128 v[212:215], v157 offset:37888
	ds_read_b128 v[216:219], v157 offset:38912
	ds_read_b128 v[220:223], v157 offset:39936
	global_load_lds_dwordx4 v128, s[62:63]
	s_mov_b32 m0, s72
	s_nop 0
	global_load_lds_dwordx4 v132, s[62:63]
	s_waitcnt vmcnt(8)
	s_waitcnt lgkmcnt(0)
	s_barrier
	s_setprio 0
	s_waitcnt lgkmcnt(0)
	v_mfma_f32_16x16x32_bf16 v[124:127], v[146:149], v[192:195], v[124:127]
	v_mfma_f32_16x16x32_bf16 v[120:123], v[168:171], v[192:195], v[120:123]
	v_mfma_f32_16x16x32_bf16 v[108:111], v[146:149], v[200:203], v[108:111]
	v_mfma_f32_16x16x32_bf16 v[104:107], v[168:171], v[200:203], v[104:107]
	v_mfma_f32_16x16x32_bf16 v[92:95], v[146:149], v[208:211], v[92:95]
	v_mfma_f32_16x16x32_bf16 v[88:91], v[168:171], v[208:211], v[88:91]
	v_mfma_f32_16x16x32_bf16 v[76:79], v[146:149], v[216:219], v[76:79]
	v_mfma_f32_16x16x32_bf16 v[72:75], v[168:171], v[216:219], v[72:75]
	v_mfma_f32_16x16x32_bf16 v[124:127], v[158:161], v[196:199], v[124:127]
	v_mfma_f32_16x16x32_bf16 v[120:123], v[172:175], v[196:199], v[120:123]
	v_mfma_f32_16x16x32_bf16 v[108:111], v[158:161], v[204:207], v[108:111]
	v_mfma_f32_16x16x32_bf16 v[104:107], v[172:175], v[204:207], v[104:107]
	v_mfma_f32_16x16x32_bf16 v[92:95], v[158:161], v[212:215], v[92:95]
	v_mfma_f32_16x16x32_bf16 v[88:91], v[172:175], v[212:215], v[88:91]
	v_mfma_f32_16x16x32_bf16 v[76:79], v[158:161], v[220:223], v[76:79]
	v_mfma_f32_16x16x32_bf16 v[72:75], v[172:175], v[220:223], v[72:75]
	v_mfma_f32_16x16x32_bf16 v[116:119], v[176:179], v[192:195], v[116:119]
	v_mfma_f32_16x16x32_bf16 v[112:115], v[184:187], v[192:195], v[112:115]
	v_mfma_f32_16x16x32_bf16 v[100:103], v[176:179], v[200:203], v[100:103]
	v_mfma_f32_16x16x32_bf16 v[96:99], v[184:187], v[200:203], v[96:99]
	v_mfma_f32_16x16x32_bf16 v[84:87], v[176:179], v[208:211], v[84:87]
	v_mfma_f32_16x16x32_bf16 v[80:83], v[184:187], v[208:211], v[80:83]
	v_mfma_f32_16x16x32_bf16 v[68:71], v[176:179], v[216:219], v[68:71]
	v_mfma_f32_16x16x32_bf16 v[64:67], v[184:187], v[216:219], v[64:67]
	v_mfma_f32_16x16x32_bf16 v[116:119], v[180:183], v[196:199], v[116:119]
	v_mfma_f32_16x16x32_bf16 v[112:115], v[188:191], v[196:199], v[112:115]
	v_mfma_f32_16x16x32_bf16 v[100:103], v[180:183], v[204:207], v[100:103]
	v_mfma_f32_16x16x32_bf16 v[96:99], v[188:191], v[204:207], v[96:99]
	v_mfma_f32_16x16x32_bf16 v[84:87], v[180:183], v[212:215], v[84:87]
	v_mfma_f32_16x16x32_bf16 v[80:83], v[188:191], v[212:215], v[80:83]
	v_mfma_f32_16x16x32_bf16 v[68:71], v[180:183], v[220:223], v[68:71]
	v_mfma_f32_16x16x32_bf16 v[64:67], v[188:191], v[220:223], v[64:67]
	s_setprio 1
	s_barrier
	s_add_i32 s41, s41, s68
	v_lshl_add_u64 v[150:151], v[150:151], 0, s[20:21]
	s_mov_b32 m0, s41
	ds_read_b128 v[192:195], v157 offset:49152
	ds_read_b128 v[196:199], v157 offset:50176
	ds_read_b128 v[200:203], v157 offset:51200
	ds_read_b128 v[204:207], v157 offset:52224
	ds_read_b128 v[208:211], v157 offset:53248
	ds_read_b128 v[212:215], v157 offset:54272
	ds_read_b128 v[216:219], v157 offset:55296
	ds_read_b128 v[220:223], v157 offset:56320
	global_load_lds_dwordx4 v[150:151], off
	s_add_i32 m0, s41, 0x2000
	s_add_u32 s60, s60, 0x80080
	v_lshl_add_u64 v[150:151], v[224:225], 0, s[20:21]
	s_addc_u32 s61, s61, 0
	s_add_i32 s41, s43, s68
	global_load_lds_dwordx4 v[150:151], off
	s_mov_b32 m0, s41
	s_nop 0
	global_load_lds_dwordx4 v130, s[60:61]
	s_add_i32 m0, s41, 0x2000
	s_nop 0
	global_load_lds_dwordx4 v134, s[60:61]
	v_lshl_add_u64 v[150:151], v[226:227], 0, s[20:21]
	s_mov_b32 m0, s78
	s_nop 0
	global_load_lds_dwordx4 v[150:151], off
	v_lshl_add_u64 v[150:151], v[228:229], 0, s[20:21]
	s_mov_b32 m0, s79
	s_nop 0
	global_load_lds_dwordx4 v[150:151], off
	s_waitcnt vmcnt(8)
	s_waitcnt lgkmcnt(0)
	s_barrier
	s_setprio 0
	s_waitcnt lgkmcnt(0)
	v_mfma_f32_16x16x32_bf16 v[60:63], v[146:149], v[192:195], v[60:63]
	v_mfma_f32_16x16x32_bf16 v[56:59], v[168:171], v[192:195], v[56:59]
	v_mfma_f32_16x16x32_bf16 v[44:47], v[146:149], v[200:203], v[44:47]
	v_mfma_f32_16x16x32_bf16 v[40:43], v[168:171], v[200:203], v[40:43]
	v_mfma_f32_16x16x32_bf16 v[28:31], v[146:149], v[208:211], v[28:31]
	v_mfma_f32_16x16x32_bf16 v[24:27], v[168:171], v[208:211], v[24:27]
	v_mfma_f32_16x16x32_bf16 v[12:15], v[146:149], v[216:219], v[12:15]
	v_mfma_f32_16x16x32_bf16 v[8:11], v[168:171], v[216:219], v[8:11]
	v_mfma_f32_16x16x32_bf16 v[60:63], v[158:161], v[196:199], v[60:63]
	v_mfma_f32_16x16x32_bf16 v[56:59], v[172:175], v[196:199], v[56:59]
	v_mfma_f32_16x16x32_bf16 v[44:47], v[158:161], v[204:207], v[44:47]
	v_mfma_f32_16x16x32_bf16 v[40:43], v[172:175], v[204:207], v[40:43]
	v_mfma_f32_16x16x32_bf16 v[28:31], v[158:161], v[212:215], v[28:31]
	v_mfma_f32_16x16x32_bf16 v[24:27], v[172:175], v[212:215], v[24:27]
	v_mfma_f32_16x16x32_bf16 v[12:15], v[158:161], v[220:223], v[12:15]
	v_mfma_f32_16x16x32_bf16 v[8:11], v[172:175], v[220:223], v[8:11]
	v_mfma_f32_16x16x32_bf16 v[52:55], v[176:179], v[192:195], v[52:55]
	v_mfma_f32_16x16x32_bf16 v[48:51], v[184:187], v[192:195], v[48:51]
	v_mfma_f32_16x16x32_bf16 v[36:39], v[176:179], v[200:203], v[36:39]
	v_mfma_f32_16x16x32_bf16 v[32:35], v[184:187], v[200:203], v[32:35]
	v_mfma_f32_16x16x32_bf16 v[20:23], v[176:179], v[208:211], v[20:23]
	v_mfma_f32_16x16x32_bf16 v[16:19], v[184:187], v[208:211], v[16:19]
	v_mfma_f32_16x16x32_bf16 v[4:7], v[176:179], v[216:219], v[4:7]
	v_mfma_f32_16x16x32_bf16 v[0:3], v[184:187], v[216:219], v[0:3]
	v_mfma_f32_16x16x32_bf16 v[52:55], v[180:183], v[196:199], v[52:55]
	v_mfma_f32_16x16x32_bf16 v[48:51], v[188:191], v[196:199], v[48:51]
	v_mfma_f32_16x16x32_bf16 v[36:39], v[180:183], v[204:207], v[36:39]
	v_mfma_f32_16x16x32_bf16 v[32:35], v[188:191], v[204:207], v[32:35]
	v_mfma_f32_16x16x32_bf16 v[20:23], v[180:183], v[212:215], v[20:23]
	v_mfma_f32_16x16x32_bf16 v[16:19], v[188:191], v[212:215], v[16:19]
	v_mfma_f32_16x16x32_bf16 v[4:7], v[180:183], v[220:223], v[4:7]
	v_mfma_f32_16x16x32_bf16 v[0:3], v[188:191], v[220:223], v[0:3]
	s_add_i32 s34, s34, 2
	s_add_u32 s54, s54, 0x100
	s_addc_u32 s55, s55, 0
	s_add_u32 s31, s31, 0x100
	s_addc_u32 s33, s33, 0
	s_cmp_gt_u32 s34, 29
	s_setprio 1
	s_barrier
	s_cbranch_scc0 .LBB0_497
	s_and_b64 vcc, exec, s[22:23]
	s_cbranch_vccz .LBB0_500
	s_barrier

; #define PG8_STAGE(bufoff, gbase, voff) do { _Pragma("unroll") for (int _i = 0; _i < 2; ++_i) \
;         __builtin_amdgcn_global_load_lds((const unsigned*)((const char*)(gbase) + (voff)[_i]), (PG8_LAS unsigned*)(lds + (bufoff) + ldsw + _i * 8192), 16, 0, 0); } while (0)
; #define PG8_LDA(dst, b, h) do { _Pragma("unroll") for (int m = 0; m < 4; ++m) _Pragma("unroll") for (int k = 0; k < 2; ++k) dst[m][k] = *(const PG8_LAS bf16x8*)(lds + PG8_SA(b, h) + aoff + m * 2048 + k * 1024); } while (0)
; #define PG8_LDB(dst, b, h) do { _Pragma("unroll") for (int n = 0; n < 2; ++n) _Pragma("unroll") for (int k = 0; k < 2; ++k) dst[n][k] = *(const PG8_LAS bf16x8*)(lds + PG8_SB(b, h) + boff + n * 2048 + k * 1024); } while (0)
; #define PG8_MMA(ai, bj, At, Bt) do { __builtin_amdgcn_s_setprio(1); _Pragma("unroll") for (int m = 0; m < 4; ++m) _Pragma("unroll") for (int n = 0; n < 2; ++n) _Pragma("unroll") for (int k = 0; k < 2; ++k) \
;         acc[ai][bj][m][n] = __builtin_amdgcn_mfma_f32_16x16x32_bf16(Bt[n][k], At[m][k], acc[ai][bj][m][n], 0, 0, 0); __builtin_amdgcn_s_setprio(0); } while (0)
; #define PG8_WAIT_V(n) asm volatile("s_waitcnt vmcnt(" #n ")" ::: "memory")
; #define PG8_WAIT_L(n) asm volatile("s_waitcnt lgkmcnt(" #n ")" ::: "memory")
; template <class Epi, class Sched, bool ALIGN_EPI = false, bool SP2 = false>
; __device__ __forceinline__ void gemm_phase(PG8_LAS unsigned char* lds, const Gemm g, const Sched& S, const Epi& E) {
;     ...
;             const bool last = (t == nt - 2);
;             const char* a1 = cA + (size_t)(t + 1) * kstep;
;             const char* a2 = last ? nA : cA + (size_t)(t + 2) * kstep; const char* b2 = last ? nB : cB + (size_t)(t + 2) * kstep;
;             const char* a3 = a2 + kstep; const char* b3 = b2 + kstep;
;             if (last && has_next) S.a_ready(nxt);
;             if constexpr (SP2) {
;             PG8_LDB(B0, 0, 0); PG8_LDB(B1, 0, 1); PG8_SCHED; PG8_LDA(At, 0, 0); PG8_STAGE(PG8_SA(1, 1), a1 + hstepA, voffA);
;             PG8_WAIT_V(8); PG8_WAIT_L(0); PG8_BAR; PG8_MMA(0, 0, At, B0); PG8_MMA(0, 1, At, B1); PG8_BAR; PG8_SCHED;
;             PG8_LDA(At, 0, 1); PG8_STAGE(PG8_SB(0, 0), b2, voffB); PG8_STAGE(PG8_SB(0, 1), b2 + hstepB, voffB); PG8_STAGE(PG8_SA(0, 0), a2, voffA);
;             PG8_WAIT_V(8); PG8_WAIT_L(0); PG8_BAR; PG8_MMA(1, 0, At, B0); PG8_MMA(1, 1, At, B1); PG8_BAR; PG8_SCHED;
.LBB0_829:
	ds_read_b128 v[144:147], v153
	ds_read_b128 v[158:161], v153 offset:1024
	ds_read_b128 v[166:169], v153 offset:2048
	ds_read_b128 v[170:173], v153 offset:3072
	ds_read_b128 v[174:177], v154
	ds_read_b128 v[178:181], v154 offset:1024
	ds_read_b128 v[182:185], v154 offset:2048
	ds_read_b128 v[186:189], v154 offset:3072
	s_add_u32 s40, s0, 0xffdc0080
	s_addc_u32 s41, s1, -1
	s_cmp_eq_u32 s58, 12
	s_cselect_b32 s43, s21, s41
	s_cselect_b32 s42, s20, s40
	s_cselect_b32 s41, s19, s57
	s_cselect_b32 s40, s55, s56
	s_add_i32 m0, s33, 0xc000
	ds_read_b128 v[190:193], v155
	ds_read_b128 v[194:197], v155 offset:1024
	ds_read_b128 v[198:201], v155 offset:2048
	ds_read_b128 v[202:205], v155 offset:3072
	ds_read_b128 v[206:209], v155 offset:4096
	ds_read_b128 v[210:213], v155 offset:5120
	ds_read_b128 v[214:217], v155 offset:6144
	ds_read_b128 v[218:221], v155 offset:7168
	global_load_lds_dwordx4 v136, s[0:1]
	s_add_i32 m0, s33, 0xe000
	s_nop 0
	global_load_lds_dwordx4 v138, s[0:1]
	s_waitcnt vmcnt(8)
	s_waitcnt lgkmcnt(0)
	s_barrier
	s_setprio 0
	s_waitcnt lgkmcnt(0)
	v_mfma_f32_16x16x32_bf16 v[124:127], v[144:147], v[190:193], v[124:127]
	v_mfma_f32_16x16x32_bf16 v[120:123], v[166:169], v[190:193], v[120:123]
	v_mfma_f32_16x16x32_bf16 v[108:111], v[144:147], v[198:201], v[108:111]
	v_mfma_f32_16x16x32_bf16 v[104:107], v[166:169], v[198:201], v[104:107]
	v_mfma_f32_16x16x32_bf16 v[92:95], v[144:147], v[206:209], v[92:95]
	v_mfma_f32_16x16x32_bf16 v[88:91], v[166:169], v[206:209], v[88:91]
	v_mfma_f32_16x16x32_bf16 v[76:79], v[144:147], v[214:217], v[76:79]
	v_mfma_f32_16x16x32_bf16 v[72:75], v[166:169], v[214:217], v[72:75]
	v_mfma_f32_16x16x32_bf16 v[124:127], v[158:161], v[194:197], v[124:127]
	v_mfma_f32_16x16x32_bf16 v[120:123], v[170:173], v[194:197], v[120:123]
	v_mfma_f32_16x16x32_bf16 v[108:111], v[158:161], v[202:205], v[108:111]
	v_mfma_f32_16x16x32_bf16 v[104:107], v[170:173], v[202:205], v[104:107]
	v_mfma_f32_16x16x32_bf16 v[92:95], v[158:161], v[210:213], v[92:95]
	v_mfma_f32_16x16x32_bf16 v[88:91], v[170:173], v[210:213], v[88:91]
	v_mfma_f32_16x16x32_bf16 v[76:79], v[158:161], v[218:221], v[76:79]
	v_mfma_f32_16x16x32_bf16 v[72:75], v[170:173], v[218:221], v[72:75]
	v_mfma_f32_16x16x32_bf16 v[116:119], v[174:177], v[190:193], v[116:119]
	v_mfma_f32_16x16x32_bf16 v[112:115], v[182:185], v[190:193], v[112:115]
	v_mfma_f32_16x16x32_bf16 v[100:103], v[174:177], v[198:201], v[100:103]
	v_mfma_f32_16x16x32_bf16 v[96:99], v[182:185], v[198:201], v[96:99]
	v_mfma_f32_16x16x32_bf16 v[84:87], v[174:177], v[206:209], v[84:87]
	v_mfma_f32_16x16x32_bf16 v[80:83], v[182:185], v[206:209], v[80:83]
	v_mfma_f32_16x16x32_bf16 v[68:71], v[174:177], v[214:217], v[68:71]
	v_mfma_f32_16x16x32_bf16 v[64:67], v[182:185], v[214:217], v[64:67]
	v_mfma_f32_16x16x32_bf16 v[116:119], v[178:181], v[194:197], v[116:119]
	v_mfma_f32_16x16x32_bf16 v[112:115], v[186:189], v[194:197], v[112:115]
	v_mfma_f32_16x16x32_bf16 v[100:103], v[178:181], v[202:205], v[100:103]
	v_mfma_f32_16x16x32_bf16 v[96:99], v[186:189], v[202:205], v[96:99]
	v_mfma_f32_16x16x32_bf16 v[84:87], v[178:181], v[210:213], v[84:87]
	v_mfma_f32_16x16x32_bf16 v[80:83], v[186:189], v[210:213], v[80:83]
	v_mfma_f32_16x16x32_bf16 v[68:71], v[178:181], v[218:221], v[68:71]
	v_mfma_f32_16x16x32_bf16 v[64:67], v[186:189], v[218:221], v[64:67]
	s_setprio 1
	s_barrier
	s_add_i32 s59, s49, s30
	v_lshl_add_u64 v[148:149], s[40:41], 0, v[132:133]
	s_mov_b32 m0, s59
	ds_read_b128 v[190:193], v155 offset:16384
	ds_read_b128 v[194:197], v155 offset:17408
	ds_read_b128 v[198:201], v155 offset:18432
	ds_read_b128 v[202:205], v155 offset:19456
	ds_read_b128 v[206:209], v155 offset:20480
	ds_read_b128 v[210:213], v155 offset:21504
	ds_read_b128 v[214:217], v155 offset:22528
	ds_read_b128 v[218:221], v155 offset:23552
	global_load_lds_dwordx4 v132, s[40:41]
	s_add_i32 m0, s59, 0x2000
	s_add_u32 s60, s40, 0x40000
	v_lshl_add_u64 v[222:223], s[40:41], 0, v[128:129]
	s_addc_u32 s61, s41, 0
	s_add_i32 s59, s50, s30
	global_load_lds_dwordx4 v128, s[40:41]
	s_mov_b32 m0, s59
	v_lshl_add_u64 v[226:227], s[42:43], 0, v[130:131]
	global_load_lds_dwordx4 v132, s[60:61]
	s_add_i32 m0, s59, 0x2000
	s_nop 0
	global_load_lds_dwordx4 v128, s[60:61]
	v_lshl_add_u64 v[224:225], s[42:43], 0, v[134:135]
	s_mov_b32 m0, s33
	s_nop 0
	global_load_lds_dwordx4 v134, s[42:43]
	s_mov_b32 m0, s34
	s_nop 0
	global_load_lds_dwordx4 v130, s[42:43]
	s_waitcnt vmcnt(8)
	s_waitcnt lgkmcnt(0)
	s_barrier
	s_setprio 0
	s_waitcnt lgkmcnt(0)
	v_mfma_f32_16x16x32_bf16 v[60:63], v[144:147], v[190:193], v[60:63]
	v_mfma_f32_16x16x32_bf16 v[56:59], v[166:169], v[190:193], v[56:59]
	v_mfma_f32_16x16x32_bf16 v[44:47], v[144:147], v[198:201], v[44:47]
	v_mfma_f32_16x16x32_bf16 v[40:43], v[166:169], v[198:201], v[40:43]
	v_mfma_f32_16x16x32_bf16 v[28:31], v[144:147], v[206:209], v[28:31]
	v_mfma_f32_16x16x32_bf16 v[24:27], v[166:169], v[206:209], v[24:27]
	v_mfma_f32_16x16x32_bf16 v[12:15], v[144:147], v[214:217], v[12:15]
	v_mfma_f32_16x16x32_bf16 v[8:11], v[166:169], v[214:217], v[8:11]
	v_mfma_f32_16x16x32_bf16 v[60:63], v[158:161], v[194:197], v[60:63]
	v_mfma_f32_16x16x32_bf16 v[56:59], v[170:173], v[194:197], v[56:59]
	v_mfma_f32_16x16x32_bf16 v[44:47], v[158:161], v[202:205], v[44:47]
	v_mfma_f32_16x16x32_bf16 v[40:43], v[170:173], v[202:205], v[40:43]
	v_mfma_f32_16x16x32_bf16 v[28:31], v[158:161], v[210:213], v[28:31]
	v_mfma_f32_16x16x32_bf16 v[24:27], v[170:173], v[210:213], v[24:27]
	v_mfma_f32_16x16x32_bf16 v[12:15], v[158:161], v[218:221], v[12:15]
	v_mfma_f32_16x16x32_bf16 v[8:11], v[170:173], v[218:221], v[8:11]
	v_mfma_f32_16x16x32_bf16 v[52:55], v[174:177], v[190:193], v[52:55]
	v_mfma_f32_16x16x32_bf16 v[48:51], v[182:185], v[190:193], v[48:51]
	v_mfma_f32_16x16x32_bf16 v[36:39], v[174:177], v[198:201], v[36:39]
	v_mfma_f32_16x16x32_bf16 v[32:35], v[182:185], v[198:201], v[32:35]
	v_mfma_f32_16x16x32_bf16 v[20:23], v[174:177], v[206:209], v[20:23]
	v_mfma_f32_16x16x32_bf16 v[16:19], v[182:185], v[206:209], v[16:19]
	v_mfma_f32_16x16x32_bf16 v[4:7], v[174:177], v[214:217], v[4:7]
	v_mfma_f32_16x16x32_bf16 v[0:3], v[182:185], v[214:217], v[0:3]
	v_mfma_f32_16x16x32_bf16 v[52:55], v[178:181], v[194:197], v[52:55]
	v_mfma_f32_16x16x32_bf16 v[48:51], v[186:189], v[194:197], v[48:51]
	v_mfma_f32_16x16x32_bf16 v[36:39], v[178:181], v[202:205], v[36:39]
	v_mfma_f32_16x16x32_bf16 v[32:35], v[186:189], v[202:205], v[32:35]
	v_mfma_f32_16x16x32_bf16 v[20:23], v[178:181], v[210:213], v[20:23]
	v_mfma_f32_16x16x32_bf16 v[16:19], v[186:189], v[210:213], v[16:19]
	v_mfma_f32_16x16x32_bf16 v[4:7], v[178:181], v[218:221], v[4:7]
	v_mfma_f32_16x16x32_bf16 v[0:3], v[186:189], v[218:221], v[0:3]
	s_setprio 1
	s_barrier
; #define PG8_STAGE(bufoff, gbase, voff) do { _Pragma("unroll") for (int _i = 0; _i < 2; ++_i) \
;         __builtin_amdgcn_global_load_lds((const unsigned*)((const char*)(gbase) + (voff)[_i]), (PG8_LAS unsigned*)(lds + (bufoff) + ldsw + _i * 8192), 16, 0, 0); } while (0)
; #define PG8_LDA(dst, b, h) do { _Pragma("unroll") for (int m = 0; m < 4; ++m) _Pragma("unroll") for (int k = 0; k < 2; ++k) dst[m][k] = *(const PG8_LAS bf16x8*)(lds + PG8_SA(b, h) + aoff + m * 2048 + k * 1024); } while (0)
; #define PG8_LDB(dst, b, h) do { _Pragma("unroll") for (int n = 0; n < 2; ++n) _Pragma("unroll") for (int k = 0; k < 2; ++k) dst[n][k] = *(const PG8_LAS bf16x8*)(lds + PG8_SB(b, h) + boff + n * 2048 + k * 1024); } while (0)
; #define PG8_MMA(ai, bj, At, Bt) do { __builtin_amdgcn_s_setprio(1); _Pragma("unroll") for (int m = 0; m < 4; ++m) _Pragma("unroll") for (int n = 0; n < 2; ++n) _Pragma("unroll") for (int k = 0; k < 2; ++k) \
;         acc[ai][bj][m][n] = __builtin_amdgcn_mfma_f32_16x16x32_bf16(Bt[n][k], At[m][k], acc[ai][bj][m][n], 0, 0, 0); __builtin_amdgcn_s_setprio(0); } while (0)
; #define PG8_WAIT_V(n) asm volatile("s_waitcnt vmcnt(" #n ")" ::: "memory")
; #define PG8_WAIT_L(n) asm volatile("s_waitcnt lgkmcnt(" #n ")" ::: "memory")
; #define PG8_BAR __builtin_amdgcn_s_barrier()
; #define PG8_SCHED __builtin_amdgcn_sched_barrier(0)
; template <class Epi, class Sched, bool ALIGN_EPI = false, bool SP2 = false>
; __device__ __forceinline__ void gemm_phase(PG8_LAS unsigned char* lds, const Gemm g, const Sched& S, const Epi& E) {
;     ...
;         for (int t = 0; t < nt; t += 2) {
;     ...
;             PG8_LDB(B0, 1, 0); PG8_LDB(B1, 1, 1); PG8_SCHED; PG8_LDA(At, 1, 0); PG8_STAGE(PG8_SA(0, 1), a2 + hstepA, voffA);
;             PG8_WAIT_V(8); PG8_WAIT_L(0); PG8_BAR; PG8_MMA(0, 0, At, B0); PG8_MMA(0, 1, At, B1); PG8_BAR; PG8_SCHED;
;             PG8_LDA(At, 1, 1); PG8_STAGE(PG8_SB(1, 0), b3, voffB); PG8_STAGE(PG8_SB(1, 1), b3 + hstepB, voffB); PG8_STAGE(PG8_SA(1, 0), a3, voffA);
;             PG8_WAIT_V(8); PG8_WAIT_L(0); PG8_BAR; PG8_MMA(1, 0, At, B0); PG8_MMA(1, 1, At, B1); PG8_BAR; PG8_SCHED;
	s_add_i32 s59, 0, 0x18000
	v_add_u32_e32 v157, s59, v151
	s_add_i32 s60, 0, 0x1c000
	ds_read_b128 v[144:147], v157
	ds_read_b128 v[158:161], v157 offset:1024
	ds_read_b128 v[166:169], v157 offset:2048
	ds_read_b128 v[170:173], v157 offset:3072
	v_add_u32_e32 v157, s60, v151
	ds_read_b128 v[174:177], v157
	ds_read_b128 v[178:181], v157 offset:1024
	ds_read_b128 v[182:185], v157 offset:2048
	ds_read_b128 v[186:189], v157 offset:3072
	s_add_u32 s42, s42, 0x240000
	s_addc_u32 s43, s43, 0
	s_mov_b32 m0, s35
	ds_read_b128 v[190:193], v155 offset:32768
	ds_read_b128 v[194:197], v155 offset:33792
	ds_read_b128 v[198:201], v155 offset:34816
	ds_read_b128 v[202:205], v155 offset:35840
	ds_read_b128 v[206:209], v155 offset:36864
	ds_read_b128 v[210:213], v155 offset:37888
	ds_read_b128 v[214:217], v155 offset:38912
	ds_read_b128 v[218:221], v155 offset:39936
	global_load_lds_dwordx4 v134, s[42:43]
	s_mov_b32 m0, s44
	s_nop 0
	global_load_lds_dwordx4 v130, s[42:43]
	s_waitcnt vmcnt(8)
	s_waitcnt lgkmcnt(0)
	s_barrier
	s_setprio 0
	s_waitcnt lgkmcnt(0)
	v_mfma_f32_16x16x32_bf16 v[124:127], v[144:147], v[190:193], v[124:127]
	v_mfma_f32_16x16x32_bf16 v[120:123], v[166:169], v[190:193], v[120:123]
	v_mfma_f32_16x16x32_bf16 v[108:111], v[144:147], v[198:201], v[108:111]
	v_mfma_f32_16x16x32_bf16 v[104:107], v[166:169], v[198:201], v[104:107]
	v_mfma_f32_16x16x32_bf16 v[92:95], v[144:147], v[206:209], v[92:95]
	v_mfma_f32_16x16x32_bf16 v[88:91], v[166:169], v[206:209], v[88:91]
	v_mfma_f32_16x16x32_bf16 v[76:79], v[144:147], v[214:217], v[76:79]
	v_mfma_f32_16x16x32_bf16 v[72:75], v[166:169], v[214:217], v[72:75]
	v_mfma_f32_16x16x32_bf16 v[124:127], v[158:161], v[194:197], v[124:127]
	v_mfma_f32_16x16x32_bf16 v[120:123], v[170:173], v[194:197], v[120:123]
	v_mfma_f32_16x16x32_bf16 v[108:111], v[158:161], v[202:205], v[108:111]
	v_mfma_f32_16x16x32_bf16 v[104:107], v[170:173], v[202:205], v[104:107]
	v_mfma_f32_16x16x32_bf16 v[92:95], v[158:161], v[210:213], v[92:95]
	v_mfma_f32_16x16x32_bf16 v[88:91], v[170:173], v[210:213], v[88:91]
	v_mfma_f32_16x16x32_bf16 v[76:79], v[158:161], v[218:221], v[76:79]
	v_mfma_f32_16x16x32_bf16 v[72:75], v[170:173], v[218:221], v[72:75]
	v_mfma_f32_16x16x32_bf16 v[116:119], v[174:177], v[190:193], v[116:119]
	v_mfma_f32_16x16x32_bf16 v[112:115], v[182:185], v[190:193], v[112:115]
	v_mfma_f32_16x16x32_bf16 v[100:103], v[174:177], v[198:201], v[100:103]
	v_mfma_f32_16x16x32_bf16 v[96:99], v[182:185], v[198:201], v[96:99]
	v_mfma_f32_16x16x32_bf16 v[84:87], v[174:177], v[206:209], v[84:87]
	v_mfma_f32_16x16x32_bf16 v[80:83], v[182:185], v[206:209], v[80:83]
	v_mfma_f32_16x16x32_bf16 v[68:71], v[174:177], v[214:217], v[68:71]
	v_mfma_f32_16x16x32_bf16 v[64:67], v[182:185], v[214:217], v[64:67]
	v_mfma_f32_16x16x32_bf16 v[116:119], v[178:181], v[194:197], v[116:119]
	v_mfma_f32_16x16x32_bf16 v[112:115], v[186:189], v[194:197], v[112:115]
	v_mfma_f32_16x16x32_bf16 v[100:103], v[178:181], v[202:205], v[100:103]
	v_mfma_f32_16x16x32_bf16 v[96:99], v[186:189], v[202:205], v[96:99]
	v_mfma_f32_16x16x32_bf16 v[84:87], v[178:181], v[210:213], v[84:87]
	v_mfma_f32_16x16x32_bf16 v[80:83], v[186:189], v[210:213], v[80:83]
	v_mfma_f32_16x16x32_bf16 v[68:71], v[178:181], v[218:221], v[68:71]
	v_mfma_f32_16x16x32_bf16 v[64:67], v[186:189], v[218:221], v[64:67]
	s_setprio 1
	s_barrier
	s_add_i32 s42, s59, s30
	v_lshl_add_u64 v[148:149], v[148:149], 0, s[10:11]
	s_mov_b32 m0, s42
	ds_read_b128 v[190:193], v155 offset:49152
	ds_read_b128 v[194:197], v155 offset:50176
	ds_read_b128 v[198:201], v155 offset:51200
	ds_read_b128 v[202:205], v155 offset:52224
	ds_read_b128 v[206:209], v155 offset:53248
	ds_read_b128 v[210:213], v155 offset:54272
	ds_read_b128 v[214:217], v155 offset:55296
	ds_read_b128 v[218:221], v155 offset:56320
	global_load_lds_dwordx4 v[148:149], off
	s_add_i32 m0, s42, 0x2000
	s_add_u32 s40, s40, 0x40080
	v_lshl_add_u64 v[148:149], v[222:223], 0, s[10:11]
	s_addc_u32 s41, s41, 0
	s_add_i32 s42, s60, s30
	global_load_lds_dwordx4 v[148:149], off
	s_mov_b32 m0, s42
	s_nop 0
	global_load_lds_dwordx4 v132, s[40:41]
	s_add_i32 m0, s42, 0x2000
	s_nop 0
	global_load_lds_dwordx4 v128, s[40:41]
	v_lshl_add_u64 v[148:149], v[224:225], 0, s[10:11]
	s_mov_b32 m0, s47
	s_nop 0
	global_load_lds_dwordx4 v[148:149], off
	v_lshl_add_u64 v[148:149], v[226:227], 0, s[10:11]
	s_mov_b32 m0, s48
	s_nop 0
	global_load_lds_dwordx4 v[148:149], off
	s_waitcnt vmcnt(8)
	s_waitcnt lgkmcnt(0)
	s_barrier
	s_setprio 0
	s_waitcnt lgkmcnt(0)
	v_mfma_f32_16x16x32_bf16 v[60:63], v[144:147], v[190:193], v[60:63]
	v_mfma_f32_16x16x32_bf16 v[56:59], v[166:169], v[190:193], v[56:59]
	v_mfma_f32_16x16x32_bf16 v[44:47], v[144:147], v[198:201], v[44:47]
	v_mfma_f32_16x16x32_bf16 v[40:43], v[166:169], v[198:201], v[40:43]
	v_mfma_f32_16x16x32_bf16 v[28:31], v[144:147], v[206:209], v[28:31]
	v_mfma_f32_16x16x32_bf16 v[24:27], v[166:169], v[206:209], v[24:27]
	v_mfma_f32_16x16x32_bf16 v[12:15], v[144:147], v[214:217], v[12:15]
	v_mfma_f32_16x16x32_bf16 v[8:11], v[166:169], v[214:217], v[8:11]
	v_mfma_f32_16x16x32_bf16 v[60:63], v[158:161], v[194:197], v[60:63]
	v_mfma_f32_16x16x32_bf16 v[56:59], v[170:173], v[194:197], v[56:59]
	v_mfma_f32_16x16x32_bf16 v[44:47], v[158:161], v[202:205], v[44:47]
	v_mfma_f32_16x16x32_bf16 v[40:43], v[170:173], v[202:205], v[40:43]
	v_mfma_f32_16x16x32_bf16 v[28:31], v[158:161], v[210:213], v[28:31]
	v_mfma_f32_16x16x32_bf16 v[24:27], v[170:173], v[210:213], v[24:27]
	v_mfma_f32_16x16x32_bf16 v[12:15], v[158:161], v[218:221], v[12:15]
	v_mfma_f32_16x16x32_bf16 v[8:11], v[170:173], v[218:221], v[8:11]
	v_mfma_f32_16x16x32_bf16 v[52:55], v[174:177], v[190:193], v[52:55]
	v_mfma_f32_16x16x32_bf16 v[48:51], v[182:185], v[190:193], v[48:51]
	v_mfma_f32_16x16x32_bf16 v[36:39], v[174:177], v[198:201], v[36:39]
	v_mfma_f32_16x16x32_bf16 v[32:35], v[182:185], v[198:201], v[32:35]
	v_mfma_f32_16x16x32_bf16 v[20:23], v[174:177], v[206:209], v[20:23]
	v_mfma_f32_16x16x32_bf16 v[16:19], v[182:185], v[206:209], v[16:19]
	v_mfma_f32_16x16x32_bf16 v[4:7], v[174:177], v[214:217], v[4:7]
	v_mfma_f32_16x16x32_bf16 v[0:3], v[182:185], v[214:217], v[0:3]
	v_mfma_f32_16x16x32_bf16 v[52:55], v[178:181], v[194:197], v[52:55]
	v_mfma_f32_16x16x32_bf16 v[48:51], v[186:189], v[194:197], v[48:51]
	v_mfma_f32_16x16x32_bf16 v[36:39], v[178:181], v[202:205], v[36:39]
	v_mfma_f32_16x16x32_bf16 v[32:35], v[186:189], v[202:205], v[32:35]
	v_mfma_f32_16x16x32_bf16 v[20:23], v[178:181], v[210:213], v[20:23]
	v_mfma_f32_16x16x32_bf16 v[16:19], v[186:189], v[210:213], v[16:19]
	v_mfma_f32_16x16x32_bf16 v[4:7], v[178:181], v[218:221], v[4:7]
	v_mfma_f32_16x16x32_bf16 v[0:3], v[186:189], v[218:221], v[0:3]
	s_add_i32 s58, s58, 2
	s_add_u32 s0, s0, 0x100
	s_addc_u32 s1, s1, 0
	s_add_u32 s56, s56, 0x100
	s_addc_u32 s57, s57, 0
	s_cmp_gt_u32 s58, 13
	s_setprio 1
	s_barrier
	s_cbranch_scc0 .LBB0_829
	s_and_b64 vcc, exec, s[16:17]
	s_cbranch_vccz .LBB0_832
	s_barrier

; #define PG8_STAGE(bufoff, gbase, voff) do { _Pragma("unroll") for (int _i = 0; _i < 2; ++_i) \
;         __builtin_amdgcn_global_load_lds((const unsigned*)((const char*)(gbase) + (voff)[_i]), (PG8_LAS unsigned*)(lds + (bufoff) + ldsw + _i * 8192), 16, 0, 0); } while (0)
; #define PG8_LDA(dst, b, h) do { _Pragma("unroll") for (int m = 0; m < 4; ++m) _Pragma("unroll") for (int k = 0; k < 2; ++k) dst[m][k] = *(const PG8_LAS bf16x8*)(lds + PG8_SA(b, h) + aoff + m * 2048 + k * 1024); } while (0)
; #define PG8_LDB(dst, b, h) do { _Pragma("unroll") for (int n = 0; n < 2; ++n) _Pragma("unroll") for (int k = 0; k < 2; ++k) dst[n][k] = *(const PG8_LAS bf16x8*)(lds + PG8_SB(b, h) + boff + n * 2048 + k * 1024); } while (0)
; #define PG8_MMA(ai, bj, At, Bt) do { __builtin_amdgcn_s_setprio(1); _Pragma("unroll") for (int m = 0; m < 4; ++m) _Pragma("unroll") for (int n = 0; n < 2; ++n) _Pragma("unroll") for (int k = 0; k < 2; ++k) \
;         acc[ai][bj][m][n] = __builtin_amdgcn_mfma_f32_16x16x32_bf16(Bt[n][k], At[m][k], acc[ai][bj][m][n], 0, 0, 0); __builtin_amdgcn_s_setprio(0); } while (0)
; #define PG8_WAIT_V(n) asm volatile("s_waitcnt vmcnt(" #n ")" ::: "memory")
; #define PG8_WAIT_L(n) asm volatile("s_waitcnt lgkmcnt(" #n ")" ::: "memory")
; template <class Epi, class Sched, bool ALIGN_EPI = false, bool SP2 = false>
; __device__ __forceinline__ void gemm_phase(PG8_LAS unsigned char* lds, const Gemm g, const Sched& S, const Epi& E) {
;     ...
;             const bool last = (t == nt - 2);
;             const char* a1 = cA + (size_t)(t + 1) * kstep;
;             const char* a2 = last ? nA : cA + (size_t)(t + 2) * kstep; const char* b2 = last ? nB : cB + (size_t)(t + 2) * kstep;
;             const char* a3 = a2 + kstep; const char* b3 = b2 + kstep;
;             if (last && has_next) S.a_ready(nxt);
;             if constexpr (SP2) {
;             PG8_LDB(B0, 0, 0); PG8_LDB(B1, 0, 1); PG8_SCHED; PG8_LDA(At, 0, 0); PG8_STAGE(PG8_SA(1, 1), a1 + hstepA, voffA);
;             PG8_WAIT_V(8); PG8_WAIT_L(0); PG8_BAR; PG8_MMA(0, 0, At, B0); PG8_MMA(0, 1, At, B1); PG8_BAR; PG8_SCHED;
;             PG8_LDA(At, 0, 1); PG8_STAGE(PG8_SB(0, 0), b2, voffB); PG8_STAGE(PG8_SB(0, 1), b2 + hstepB, voffB); PG8_STAGE(PG8_SA(0, 0), a2, voffA);
;             PG8_WAIT_V(8); PG8_WAIT_L(0); PG8_BAR; PG8_MMA(1, 0, At, B0); PG8_MMA(1, 1, At, B1); PG8_BAR; PG8_SCHED;
.LBB0_848:
	ds_read_b128 v[144:147], v155
	ds_read_b128 v[148:151], v155 offset:1024
	ds_read_b128 v[166:169], v155 offset:2048
	ds_read_b128 v[170:173], v155 offset:3072
	ds_read_b128 v[174:177], v156
	ds_read_b128 v[178:181], v156 offset:1024
	ds_read_b128 v[182:185], v156 offset:2048
	ds_read_b128 v[186:189], v156 offset:3072
	s_add_u32 s42, s0, 0xffdc0080
	s_addc_u32 s43, s1, -1
	s_cmp_eq_u32 s58, 12
	s_cselect_b32 s45, s23, s43
	s_cselect_b32 s44, s22, s42
	s_cselect_b32 s43, s21, s34
	s_cselect_b32 s42, s30, s31
	s_add_i32 m0, s46, 0xc000
	ds_read_b128 v[190:193], v157
	ds_read_b128 v[194:197], v157 offset:1024
	ds_read_b128 v[198:201], v157 offset:2048
	ds_read_b128 v[202:205], v157 offset:3072
	ds_read_b128 v[206:209], v157 offset:4096
	ds_read_b128 v[210:213], v157 offset:5120
	ds_read_b128 v[214:217], v157 offset:6144
	ds_read_b128 v[218:221], v157 offset:7168
	global_load_lds_dwordx4 v136, s[0:1]
	s_add_i32 m0, s46, 0xe000
	s_nop 0
	global_load_lds_dwordx4 v138, s[0:1]
	s_waitcnt vmcnt(8)
	s_waitcnt lgkmcnt(0)
	s_barrier
	s_setprio 0
	s_waitcnt lgkmcnt(0)
	v_mfma_f32_16x16x32_bf16 v[124:127], v[144:147], v[190:193], v[124:127]
	v_mfma_f32_16x16x32_bf16 v[120:123], v[166:169], v[190:193], v[120:123]
	v_mfma_f32_16x16x32_bf16 v[108:111], v[144:147], v[198:201], v[108:111]
	v_mfma_f32_16x16x32_bf16 v[104:107], v[166:169], v[198:201], v[104:107]
	v_mfma_f32_16x16x32_bf16 v[92:95], v[144:147], v[206:209], v[92:95]
	v_mfma_f32_16x16x32_bf16 v[88:91], v[166:169], v[206:209], v[88:91]
	v_mfma_f32_16x16x32_bf16 v[76:79], v[144:147], v[214:217], v[76:79]
	v_mfma_f32_16x16x32_bf16 v[72:75], v[166:169], v[214:217], v[72:75]
	v_mfma_f32_16x16x32_bf16 v[124:127], v[148:151], v[194:197], v[124:127]
	v_mfma_f32_16x16x32_bf16 v[120:123], v[170:173], v[194:197], v[120:123]
	v_mfma_f32_16x16x32_bf16 v[108:111], v[148:151], v[202:205], v[108:111]
	v_mfma_f32_16x16x32_bf16 v[104:107], v[170:173], v[202:205], v[104:107]
	v_mfma_f32_16x16x32_bf16 v[92:95], v[148:151], v[210:213], v[92:95]
	v_mfma_f32_16x16x32_bf16 v[88:91], v[170:173], v[210:213], v[88:91]
	v_mfma_f32_16x16x32_bf16 v[76:79], v[148:151], v[218:221], v[76:79]
	v_mfma_f32_16x16x32_bf16 v[72:75], v[170:173], v[218:221], v[72:75]
	v_mfma_f32_16x16x32_bf16 v[116:119], v[174:177], v[190:193], v[116:119]
	v_mfma_f32_16x16x32_bf16 v[112:115], v[182:185], v[190:193], v[112:115]
	v_mfma_f32_16x16x32_bf16 v[100:103], v[174:177], v[198:201], v[100:103]
	v_mfma_f32_16x16x32_bf16 v[96:99], v[182:185], v[198:201], v[96:99]
	v_mfma_f32_16x16x32_bf16 v[84:87], v[174:177], v[206:209], v[84:87]
	v_mfma_f32_16x16x32_bf16 v[80:83], v[182:185], v[206:209], v[80:83]
	v_mfma_f32_16x16x32_bf16 v[68:71], v[174:177], v[214:217], v[68:71]
	v_mfma_f32_16x16x32_bf16 v[64:67], v[182:185], v[214:217], v[64:67]
	v_mfma_f32_16x16x32_bf16 v[116:119], v[178:181], v[194:197], v[116:119]
	v_mfma_f32_16x16x32_bf16 v[112:115], v[186:189], v[194:197], v[112:115]
	v_mfma_f32_16x16x32_bf16 v[100:103], v[178:181], v[202:205], v[100:103]
	v_mfma_f32_16x16x32_bf16 v[96:99], v[186:189], v[202:205], v[96:99]
	v_mfma_f32_16x16x32_bf16 v[84:87], v[178:181], v[210:213], v[84:87]
	v_mfma_f32_16x16x32_bf16 v[80:83], v[186:189], v[210:213], v[80:83]
	v_mfma_f32_16x16x32_bf16 v[68:71], v[178:181], v[218:221], v[68:71]
	v_mfma_f32_16x16x32_bf16 v[64:67], v[186:189], v[218:221], v[64:67]
	s_setprio 1
	s_barrier
	s_add_i32 s59, s54, s33
	v_lshl_add_u64 v[160:161], s[42:43], 0, v[132:133]
	s_mov_b32 m0, s59
	ds_read_b128 v[190:193], v157 offset:16384
	ds_read_b128 v[194:197], v157 offset:17408
	ds_read_b128 v[198:201], v157 offset:18432
	ds_read_b128 v[202:205], v157 offset:19456
	ds_read_b128 v[206:209], v157 offset:20480
	ds_read_b128 v[210:213], v157 offset:21504
	ds_read_b128 v[214:217], v157 offset:22528
	ds_read_b128 v[218:221], v157 offset:23552
	global_load_lds_dwordx4 v132, s[42:43]
	s_add_i32 m0, s59, 0x2000
	s_add_u32 s60, s42, 0x40000
	v_lshl_add_u64 v[222:223], s[42:43], 0, v[128:129]
	s_addc_u32 s61, s43, 0
	s_add_i32 s59, s55, s33
	global_load_lds_dwordx4 v128, s[42:43]
	s_mov_b32 m0, s59
	v_lshl_add_u64 v[226:227], s[44:45], 0, v[130:131]
	global_load_lds_dwordx4 v132, s[60:61]
	s_add_i32 m0, s59, 0x2000
	s_nop 0
	global_load_lds_dwordx4 v128, s[60:61]
	v_lshl_add_u64 v[224:225], s[44:45], 0, v[134:135]
	s_mov_b32 m0, s46
	s_nop 0
	global_load_lds_dwordx4 v134, s[44:45]
	s_mov_b32 m0, s47
	s_nop 0
	global_load_lds_dwordx4 v130, s[44:45]
	s_waitcnt vmcnt(8)
	s_waitcnt lgkmcnt(0)
	s_barrier
	s_setprio 0
	s_waitcnt lgkmcnt(0)
	v_mfma_f32_16x16x32_bf16 v[60:63], v[144:147], v[190:193], v[60:63]
	v_mfma_f32_16x16x32_bf16 v[56:59], v[166:169], v[190:193], v[56:59]
	v_mfma_f32_16x16x32_bf16 v[44:47], v[144:147], v[198:201], v[44:47]
	v_mfma_f32_16x16x32_bf16 v[40:43], v[166:169], v[198:201], v[40:43]
	v_mfma_f32_16x16x32_bf16 v[28:31], v[144:147], v[206:209], v[28:31]
	v_mfma_f32_16x16x32_bf16 v[24:27], v[166:169], v[206:209], v[24:27]
	v_mfma_f32_16x16x32_bf16 v[12:15], v[144:147], v[214:217], v[12:15]
	v_mfma_f32_16x16x32_bf16 v[8:11], v[166:169], v[214:217], v[8:11]
	v_mfma_f32_16x16x32_bf16 v[60:63], v[148:151], v[194:197], v[60:63]
	v_mfma_f32_16x16x32_bf16 v[56:59], v[170:173], v[194:197], v[56:59]
	v_mfma_f32_16x16x32_bf16 v[44:47], v[148:151], v[202:205], v[44:47]
	v_mfma_f32_16x16x32_bf16 v[40:43], v[170:173], v[202:205], v[40:43]
	v_mfma_f32_16x16x32_bf16 v[28:31], v[148:151], v[210:213], v[28:31]
	v_mfma_f32_16x16x32_bf16 v[24:27], v[170:173], v[210:213], v[24:27]
	v_mfma_f32_16x16x32_bf16 v[12:15], v[148:151], v[218:221], v[12:15]
	v_mfma_f32_16x16x32_bf16 v[8:11], v[170:173], v[218:221], v[8:11]
	v_mfma_f32_16x16x32_bf16 v[52:55], v[174:177], v[190:193], v[52:55]
	v_mfma_f32_16x16x32_bf16 v[48:51], v[182:185], v[190:193], v[48:51]
	v_mfma_f32_16x16x32_bf16 v[36:39], v[174:177], v[198:201], v[36:39]
	v_mfma_f32_16x16x32_bf16 v[32:35], v[182:185], v[198:201], v[32:35]
	v_mfma_f32_16x16x32_bf16 v[20:23], v[174:177], v[206:209], v[20:23]
	v_mfma_f32_16x16x32_bf16 v[16:19], v[182:185], v[206:209], v[16:19]
	v_mfma_f32_16x16x32_bf16 v[4:7], v[174:177], v[214:217], v[4:7]
	v_mfma_f32_16x16x32_bf16 v[0:3], v[182:185], v[214:217], v[0:3]
	v_mfma_f32_16x16x32_bf16 v[52:55], v[178:181], v[194:197], v[52:55]
	v_mfma_f32_16x16x32_bf16 v[48:51], v[186:189], v[194:197], v[48:51]
	v_mfma_f32_16x16x32_bf16 v[36:39], v[178:181], v[202:205], v[36:39]
	v_mfma_f32_16x16x32_bf16 v[32:35], v[186:189], v[202:205], v[32:35]
	v_mfma_f32_16x16x32_bf16 v[20:23], v[178:181], v[210:213], v[20:23]
	v_mfma_f32_16x16x32_bf16 v[16:19], v[186:189], v[210:213], v[16:19]
	v_mfma_f32_16x16x32_bf16 v[4:7], v[178:181], v[218:221], v[4:7]
	v_mfma_f32_16x16x32_bf16 v[0:3], v[186:189], v[218:221], v[0:3]
	s_setprio 1
	s_barrier
; #define PG8_STAGE(bufoff, gbase, voff) do { _Pragma("unroll") for (int _i = 0; _i < 2; ++_i) \
;         __builtin_amdgcn_global_load_lds((const unsigned*)((const char*)(gbase) + (voff)[_i]), (PG8_LAS unsigned*)(lds + (bufoff) + ldsw + _i * 8192), 16, 0, 0); } while (0)
; #define PG8_LDA(dst, b, h) do { _Pragma("unroll") for (int m = 0; m < 4; ++m) _Pragma("unroll") for (int k = 0; k < 2; ++k) dst[m][k] = *(const PG8_LAS bf16x8*)(lds + PG8_SA(b, h) + aoff + m * 2048 + k * 1024); } while (0)
; #define PG8_LDB(dst, b, h) do { _Pragma("unroll") for (int n = 0; n < 2; ++n) _Pragma("unroll") for (int k = 0; k < 2; ++k) dst[n][k] = *(const PG8_LAS bf16x8*)(lds + PG8_SB(b, h) + boff + n * 2048 + k * 1024); } while (0)
; #define PG8_MMA(ai, bj, At, Bt) do { __builtin_amdgcn_s_setprio(1); _Pragma("unroll") for (int m = 0; m < 4; ++m) _Pragma("unroll") for (int n = 0; n < 2; ++n) _Pragma("unroll") for (int k = 0; k < 2; ++k) \
;         acc[ai][bj][m][n] = __builtin_amdgcn_mfma_f32_16x16x32_bf16(Bt[n][k], At[m][k], acc[ai][bj][m][n], 0, 0, 0); __builtin_amdgcn_s_setprio(0); } while (0)
; #define PG8_WAIT_V(n) asm volatile("s_waitcnt vmcnt(" #n ")" ::: "memory")
; #define PG8_WAIT_L(n) asm volatile("s_waitcnt lgkmcnt(" #n ")" ::: "memory")
; #define PG8_BAR __builtin_amdgcn_s_barrier()
; #define PG8_SCHED __builtin_amdgcn_sched_barrier(0)
; template <class Epi, class Sched, bool ALIGN_EPI = false, bool SP2 = false>
; __device__ __forceinline__ void gemm_phase(PG8_LAS unsigned char* lds, const Gemm g, const Sched& S, const Epi& E) {
;     ...
;         for (int t = 0; t < nt; t += 2) {
;     ...
;             PG8_LDB(B0, 1, 0); PG8_LDB(B1, 1, 1); PG8_SCHED; PG8_LDA(At, 1, 0); PG8_STAGE(PG8_SA(0, 1), a2 + hstepA, voffA);
;             PG8_WAIT_V(8); PG8_WAIT_L(0); PG8_BAR; PG8_MMA(0, 0, At, B0); PG8_MMA(0, 1, At, B1); PG8_BAR; PG8_SCHED;
;             PG8_LDA(At, 1, 1); PG8_STAGE(PG8_SB(1, 0), b3, voffB); PG8_STAGE(PG8_SB(1, 1), b3 + hstepB, voffB); PG8_STAGE(PG8_SA(1, 0), a3, voffA);
;             PG8_WAIT_V(8); PG8_WAIT_L(0); PG8_BAR; PG8_MMA(1, 0, At, B0); PG8_MMA(1, 1, At, B1); PG8_BAR; PG8_SCHED;
	s_add_i32 s59, 0, 0x18000
	v_add_u32_e32 v159, s59, v153
	s_add_i32 s60, 0, 0x1c000
	ds_read_b128 v[144:147], v159
	ds_read_b128 v[148:151], v159 offset:1024
	ds_read_b128 v[166:169], v159 offset:2048
	ds_read_b128 v[170:173], v159 offset:3072
	v_add_u32_e32 v159, s60, v153
	ds_read_b128 v[174:177], v159
	ds_read_b128 v[178:181], v159 offset:1024
	ds_read_b128 v[182:185], v159 offset:2048
	ds_read_b128 v[186:189], v159 offset:3072
	s_add_u32 s44, s44, 0x240000
	s_addc_u32 s45, s45, 0
	s_mov_b32 m0, s48
	ds_read_b128 v[190:193], v157 offset:32768
	ds_read_b128 v[194:197], v157 offset:33792
	ds_read_b128 v[198:201], v157 offset:34816
	ds_read_b128 v[202:205], v157 offset:35840
	ds_read_b128 v[206:209], v157 offset:36864
	ds_read_b128 v[210:213], v157 offset:37888
	ds_read_b128 v[214:217], v157 offset:38912
	ds_read_b128 v[218:221], v157 offset:39936
	global_load_lds_dwordx4 v134, s[44:45]
	s_mov_b32 m0, s49
	s_nop 0
	global_load_lds_dwordx4 v130, s[44:45]
	s_waitcnt vmcnt(8)
	s_waitcnt lgkmcnt(0)
	s_barrier
	s_setprio 0
	s_waitcnt lgkmcnt(0)
	v_mfma_f32_16x16x32_bf16 v[124:127], v[144:147], v[190:193], v[124:127]
	v_mfma_f32_16x16x32_bf16 v[120:123], v[166:169], v[190:193], v[120:123]
	v_mfma_f32_16x16x32_bf16 v[108:111], v[144:147], v[198:201], v[108:111]
	v_mfma_f32_16x16x32_bf16 v[104:107], v[166:169], v[198:201], v[104:107]
	v_mfma_f32_16x16x32_bf16 v[92:95], v[144:147], v[206:209], v[92:95]
	v_mfma_f32_16x16x32_bf16 v[88:91], v[166:169], v[206:209], v[88:91]
	v_mfma_f32_16x16x32_bf16 v[76:79], v[144:147], v[214:217], v[76:79]
	v_mfma_f32_16x16x32_bf16 v[72:75], v[166:169], v[214:217], v[72:75]
	v_mfma_f32_16x16x32_bf16 v[124:127], v[148:151], v[194:197], v[124:127]
	v_mfma_f32_16x16x32_bf16 v[120:123], v[170:173], v[194:197], v[120:123]
	v_mfma_f32_16x16x32_bf16 v[108:111], v[148:151], v[202:205], v[108:111]
	v_mfma_f32_16x16x32_bf16 v[104:107], v[170:173], v[202:205], v[104:107]
	v_mfma_f32_16x16x32_bf16 v[92:95], v[148:151], v[210:213], v[92:95]
	v_mfma_f32_16x16x32_bf16 v[88:91], v[170:173], v[210:213], v[88:91]
	v_mfma_f32_16x16x32_bf16 v[76:79], v[148:151], v[218:221], v[76:79]
	v_mfma_f32_16x16x32_bf16 v[72:75], v[170:173], v[218:221], v[72:75]
	v_mfma_f32_16x16x32_bf16 v[116:119], v[174:177], v[190:193], v[116:119]
	v_mfma_f32_16x16x32_bf16 v[112:115], v[182:185], v[190:193], v[112:115]
	v_mfma_f32_16x16x32_bf16 v[100:103], v[174:177], v[198:201], v[100:103]
	v_mfma_f32_16x16x32_bf16 v[96:99], v[182:185], v[198:201], v[96:99]
	v_mfma_f32_16x16x32_bf16 v[84:87], v[174:177], v[206:209], v[84:87]
	v_mfma_f32_16x16x32_bf16 v[80:83], v[182:185], v[206:209], v[80:83]
	v_mfma_f32_16x16x32_bf16 v[68:71], v[174:177], v[214:217], v[68:71]
	v_mfma_f32_16x16x32_bf16 v[64:67], v[182:185], v[214:217], v[64:67]
	v_mfma_f32_16x16x32_bf16 v[116:119], v[178:181], v[194:197], v[116:119]
	v_mfma_f32_16x16x32_bf16 v[112:115], v[186:189], v[194:197], v[112:115]
	v_mfma_f32_16x16x32_bf16 v[100:103], v[178:181], v[202:205], v[100:103]
	v_mfma_f32_16x16x32_bf16 v[96:99], v[186:189], v[202:205], v[96:99]
	v_mfma_f32_16x16x32_bf16 v[84:87], v[178:181], v[210:213], v[84:87]
	v_mfma_f32_16x16x32_bf16 v[80:83], v[186:189], v[210:213], v[80:83]
	v_mfma_f32_16x16x32_bf16 v[68:71], v[178:181], v[218:221], v[68:71]
	v_mfma_f32_16x16x32_bf16 v[64:67], v[186:189], v[218:221], v[64:67]
	s_setprio 1
	s_barrier
	s_add_i32 s44, s59, s33
	v_lshl_add_u64 v[160:161], v[160:161], 0, s[16:17]
	s_mov_b32 m0, s44
	ds_read_b128 v[190:193], v157 offset:49152
	ds_read_b128 v[194:197], v157 offset:50176
	ds_read_b128 v[198:201], v157 offset:51200
	ds_read_b128 v[202:205], v157 offset:52224
	ds_read_b128 v[206:209], v157 offset:53248
	ds_read_b128 v[210:213], v157 offset:54272
	ds_read_b128 v[214:217], v157 offset:55296
	ds_read_b128 v[218:221], v157 offset:56320
	global_load_lds_dwordx4 v[160:161], off
	s_add_i32 m0, s44, 0x2000
	s_add_u32 s42, s42, 0x40080
	v_lshl_add_u64 v[160:161], v[222:223], 0, s[16:17]
	s_addc_u32 s43, s43, 0
	s_add_i32 s44, s60, s33
	global_load_lds_dwordx4 v[160:161], off
	s_mov_b32 m0, s44
	s_nop 0
	global_load_lds_dwordx4 v132, s[42:43]
	s_add_i32 m0, s44, 0x2000
	s_nop 0
	global_load_lds_dwordx4 v128, s[42:43]
	v_lshl_add_u64 v[160:161], v[224:225], 0, s[16:17]
	s_mov_b32 m0, s52
	s_nop 0
	global_load_lds_dwordx4 v[160:161], off
	v_lshl_add_u64 v[160:161], v[226:227], 0, s[16:17]
	s_mov_b32 m0, s53
	s_nop 0
	global_load_lds_dwordx4 v[160:161], off
	s_waitcnt vmcnt(8)
	s_waitcnt lgkmcnt(0)
	s_barrier
	s_setprio 0
	s_waitcnt lgkmcnt(0)
	v_mfma_f32_16x16x32_bf16 v[60:63], v[144:147], v[190:193], v[60:63]
	v_mfma_f32_16x16x32_bf16 v[56:59], v[166:169], v[190:193], v[56:59]
	v_mfma_f32_16x16x32_bf16 v[44:47], v[144:147], v[198:201], v[44:47]
	v_mfma_f32_16x16x32_bf16 v[40:43], v[166:169], v[198:201], v[40:43]
	v_mfma_f32_16x16x32_bf16 v[28:31], v[144:147], v[206:209], v[28:31]
	v_mfma_f32_16x16x32_bf16 v[24:27], v[166:169], v[206:209], v[24:27]
	v_mfma_f32_16x16x32_bf16 v[12:15], v[144:147], v[214:217], v[12:15]
	v_mfma_f32_16x16x32_bf16 v[8:11], v[166:169], v[214:217], v[8:11]
	v_mfma_f32_16x16x32_bf16 v[60:63], v[148:151], v[194:197], v[60:63]
	v_mfma_f32_16x16x32_bf16 v[56:59], v[170:173], v[194:197], v[56:59]
	v_mfma_f32_16x16x32_bf16 v[44:47], v[148:151], v[202:205], v[44:47]
	v_mfma_f32_16x16x32_bf16 v[40:43], v[170:173], v[202:205], v[40:43]
	v_mfma_f32_16x16x32_bf16 v[28:31], v[148:151], v[210:213], v[28:31]
	v_mfma_f32_16x16x32_bf16 v[24:27], v[170:173], v[210:213], v[24:27]
	v_mfma_f32_16x16x32_bf16 v[12:15], v[148:151], v[218:221], v[12:15]
	v_mfma_f32_16x16x32_bf16 v[8:11], v[170:173], v[218:221], v[8:11]
	v_mfma_f32_16x16x32_bf16 v[52:55], v[174:177], v[190:193], v[52:55]
	v_mfma_f32_16x16x32_bf16 v[48:51], v[182:185], v[190:193], v[48:51]
	v_mfma_f32_16x16x32_bf16 v[36:39], v[174:177], v[198:201], v[36:39]
	v_mfma_f32_16x16x32_bf16 v[32:35], v[182:185], v[198:201], v[32:35]
	v_mfma_f32_16x16x32_bf16 v[20:23], v[174:177], v[206:209], v[20:23]
	v_mfma_f32_16x16x32_bf16 v[16:19], v[182:185], v[206:209], v[16:19]
	v_mfma_f32_16x16x32_bf16 v[4:7], v[174:177], v[214:217], v[4:7]
	v_mfma_f32_16x16x32_bf16 v[0:3], v[182:185], v[214:217], v[0:3]
	v_mfma_f32_16x16x32_bf16 v[52:55], v[178:181], v[194:197], v[52:55]
	v_mfma_f32_16x16x32_bf16 v[48:51], v[186:189], v[194:197], v[48:51]
	v_mfma_f32_16x16x32_bf16 v[36:39], v[178:181], v[202:205], v[36:39]
	v_mfma_f32_16x16x32_bf16 v[32:35], v[186:189], v[202:205], v[32:35]
	v_mfma_f32_16x16x32_bf16 v[20:23], v[178:181], v[210:213], v[20:23]
	v_mfma_f32_16x16x32_bf16 v[16:19], v[186:189], v[210:213], v[16:19]
	v_mfma_f32_16x16x32_bf16 v[4:7], v[178:181], v[218:221], v[4:7]
	v_mfma_f32_16x16x32_bf16 v[0:3], v[186:189], v[218:221], v[0:3]
	s_add_i32 s58, s58, 2
	s_add_u32 s0, s0, 0x100
	s_addc_u32 s1, s1, 0
	s_add_u32 s31, s31, 0x100
	s_addc_u32 s34, s34, 0
	s_cmp_gt_u32 s58, 13
	s_setprio 1
	s_barrier
	s_cbranch_scc0 .LBB0_848
	s_and_b64 vcc, exec, s[18:19]
	s_cbranch_vccz .LBB0_851
	s_barrier

; #define PG8_STAGE(bufoff, gbase, voff) do { _Pragma("unroll") for (int _i = 0; _i < 2; ++_i) \
;         __builtin_amdgcn_global_load_lds((const unsigned*)((const char*)(gbase) + (voff)[_i]), (PG8_LAS unsigned*)(lds + (bufoff) + ldsw + _i * 8192), 16, 0, 0); } while (0)
; #define PG8_LDA(dst, b, h) do { _Pragma("unroll") for (int m = 0; m < 4; ++m) _Pragma("unroll") for (int k = 0; k < 2; ++k) dst[m][k] = *(const PG8_LAS bf16x8*)(lds + PG8_SA(b, h) + aoff + m * 2048 + k * 1024); } while (0)
; #define PG8_LDB(dst, b, h) do { _Pragma("unroll") for (int n = 0; n < 2; ++n) _Pragma("unroll") for (int k = 0; k < 2; ++k) dst[n][k] = *(const PG8_LAS bf16x8*)(lds + PG8_SB(b, h) + boff + n * 2048 + k * 1024); } while (0)
; #define PG8_MMA(ai, bj, At, Bt) do { __builtin_amdgcn_s_setprio(1); _Pragma("unroll") for (int m = 0; m < 4; ++m) _Pragma("unroll") for (int n = 0; n < 2; ++n) _Pragma("unroll") for (int k = 0; k < 2; ++k) \
;         acc[ai][bj][m][n] = __builtin_amdgcn_mfma_f32_16x16x32_bf16(Bt[n][k], At[m][k], acc[ai][bj][m][n], 0, 0, 0); __builtin_amdgcn_s_setprio(0); } while (0)
; #define PG8_WAIT_V(n) asm volatile("s_waitcnt vmcnt(" #n ")" ::: "memory")
; #define PG8_WAIT_L(n) asm volatile("s_waitcnt lgkmcnt(" #n ")" ::: "memory")
; template <class Epi, class Sched, bool ALIGN_EPI = false, bool SP2 = false>
; __device__ __forceinline__ void gemm_phase(PG8_LAS unsigned char* lds, const Gemm g, const Sched& S, const Epi& E) {
;     ...
;             const bool last = (t == nt - 2);
;             const char* a1 = cA + (size_t)(t + 1) * kstep;
;             const char* a2 = last ? nA : cA + (size_t)(t + 2) * kstep; const char* b2 = last ? nB : cB + (size_t)(t + 2) * kstep;
;             const char* a3 = a2 + kstep; const char* b3 = b2 + kstep;
;             if (last && has_next) S.a_ready(nxt);
;             if constexpr (SP2) {
;             PG8_LDB(B0, 0, 0); PG8_LDB(B1, 0, 1); PG8_SCHED; PG8_LDA(At, 0, 0); PG8_STAGE(PG8_SA(1, 1), a1 + hstepA, voffA);
;             PG8_WAIT_V(8); PG8_WAIT_L(0); PG8_BAR; PG8_MMA(0, 0, At, B0); PG8_MMA(0, 1, At, B1); PG8_BAR; PG8_SCHED;
;             PG8_LDA(At, 0, 1); PG8_STAGE(PG8_SB(0, 0), b2, voffB); PG8_STAGE(PG8_SB(0, 1), b2 + hstepB, voffB); PG8_STAGE(PG8_SA(0, 0), a2, voffA);
;             PG8_WAIT_V(8); PG8_WAIT_L(0); PG8_BAR; PG8_MMA(1, 0, At, B0); PG8_MMA(1, 1, At, B1); PG8_BAR; PG8_SCHED;
.LBB0_927:
	ds_read_b128 v[156:159], v153
	ds_read_b128 v[166:169], v153 offset:1024
	ds_read_b128 v[170:173], v153 offset:2048
	ds_read_b128 v[174:177], v153 offset:3072
	ds_read_b128 v[178:181], v154
	ds_read_b128 v[182:185], v154 offset:1024
	ds_read_b128 v[186:189], v154 offset:2048
	ds_read_b128 v[190:193], v154 offset:3072
	s_add_u32 s54, s52, 0xfff80080
	s_addc_u32 s55, s53, -1
	s_cmp_eq_u32 s71, 28
	s_cselect_b32 s57, s45, s55
	s_cselect_b32 s56, s65, s54
	s_cselect_b32 s55, s43, s70
	s_cselect_b32 s54, s68, s69
	s_add_i32 m0, s29, 0xc000
	ds_read_b128 v[194:197], v155
	ds_read_b128 v[198:201], v155 offset:1024
	ds_read_b128 v[202:205], v155 offset:2048
	ds_read_b128 v[206:209], v155 offset:3072
	ds_read_b128 v[210:213], v155 offset:4096
	ds_read_b128 v[214:217], v155 offset:5120
	ds_read_b128 v[218:221], v155 offset:6144
	ds_read_b128 v[222:225], v155 offset:7168
	global_load_lds_dwordx4 v136, s[52:53]
	s_add_i32 m0, s29, 0xe000
	s_nop 0
	global_load_lds_dwordx4 v138, s[52:53]
	s_waitcnt vmcnt(8)
	s_waitcnt lgkmcnt(0)
	s_barrier
	s_setprio 0
	s_waitcnt lgkmcnt(0)
	v_mfma_f32_16x16x32_bf16 v[124:127], v[156:159], v[194:197], v[124:127]
	v_mfma_f32_16x16x32_bf16 v[120:123], v[170:173], v[194:197], v[120:123]
	v_mfma_f32_16x16x32_bf16 v[116:119], v[156:159], v[202:205], v[116:119]
	v_mfma_f32_16x16x32_bf16 v[108:111], v[170:173], v[202:205], v[108:111]
	v_mfma_f32_16x16x32_bf16 v[100:103], v[156:159], v[210:213], v[100:103]
	v_mfma_f32_16x16x32_bf16 v[92:95], v[170:173], v[210:213], v[92:95]
	v_mfma_f32_16x16x32_bf16 v[84:87], v[156:159], v[218:221], v[84:87]
	v_mfma_f32_16x16x32_bf16 v[76:79], v[170:173], v[218:221], v[76:79]
	v_mfma_f32_16x16x32_bf16 v[124:127], v[166:169], v[198:201], v[124:127]
	v_mfma_f32_16x16x32_bf16 v[120:123], v[174:177], v[198:201], v[120:123]
	v_mfma_f32_16x16x32_bf16 v[116:119], v[166:169], v[206:209], v[116:119]
	v_mfma_f32_16x16x32_bf16 v[108:111], v[174:177], v[206:209], v[108:111]
	v_mfma_f32_16x16x32_bf16 v[100:103], v[166:169], v[214:217], v[100:103]
	v_mfma_f32_16x16x32_bf16 v[92:95], v[174:177], v[214:217], v[92:95]
	v_mfma_f32_16x16x32_bf16 v[84:87], v[166:169], v[222:225], v[84:87]
	v_mfma_f32_16x16x32_bf16 v[76:79], v[174:177], v[222:225], v[76:79]
	v_mfma_f32_16x16x32_bf16 v[112:115], v[178:181], v[194:197], v[112:115]
	v_mfma_f32_16x16x32_bf16 v[104:107], v[186:189], v[194:197], v[104:107]
	v_mfma_f32_16x16x32_bf16 v[96:99], v[178:181], v[202:205], v[96:99]
	v_mfma_f32_16x16x32_bf16 v[88:91], v[186:189], v[202:205], v[88:91]
	v_mfma_f32_16x16x32_bf16 v[80:83], v[178:181], v[210:213], v[80:83]
	v_mfma_f32_16x16x32_bf16 v[72:75], v[186:189], v[210:213], v[72:75]
	v_mfma_f32_16x16x32_bf16 v[68:71], v[178:181], v[218:221], v[68:71]
	v_mfma_f32_16x16x32_bf16 v[64:67], v[186:189], v[218:221], v[64:67]
	v_mfma_f32_16x16x32_bf16 v[112:115], v[182:185], v[198:201], v[112:115]
	v_mfma_f32_16x16x32_bf16 v[104:107], v[190:193], v[198:201], v[104:107]
	v_mfma_f32_16x16x32_bf16 v[96:99], v[182:185], v[206:209], v[96:99]
	v_mfma_f32_16x16x32_bf16 v[88:91], v[190:193], v[206:209], v[88:91]
	v_mfma_f32_16x16x32_bf16 v[80:83], v[182:185], v[214:217], v[80:83]
	v_mfma_f32_16x16x32_bf16 v[72:75], v[190:193], v[214:217], v[72:75]
	v_mfma_f32_16x16x32_bf16 v[68:71], v[182:185], v[222:225], v[68:71]
	v_mfma_f32_16x16x32_bf16 v[64:67], v[190:193], v[222:225], v[64:67]
	s_setprio 1
	s_barrier
	s_add_i32 s72, s58, s28
	v_lshl_add_u64 v[144:145], s[54:55], 0, v[130:131]
	s_mov_b32 m0, s72
	ds_read_b128 v[194:197], v155 offset:16384
	ds_read_b128 v[198:201], v155 offset:17408
	ds_read_b128 v[202:205], v155 offset:18432
	ds_read_b128 v[206:209], v155 offset:19456
	ds_read_b128 v[210:213], v155 offset:20480
	ds_read_b128 v[214:217], v155 offset:21504
	ds_read_b128 v[218:221], v155 offset:22528
	ds_read_b128 v[222:225], v155 offset:23552
	global_load_lds_dwordx4 v130, s[54:55]
	s_add_i32 m0, s72, 0x2000
	s_add_u32 s72, s54, 0x80000
	v_lshl_add_u64 v[160:161], s[54:55], 0, v[134:135]
	s_addc_u32 s73, s55, 0
	s_add_i32 s74, s59, s28
	global_load_lds_dwordx4 v134, s[54:55]
	s_mov_b32 m0, s74
	v_lshl_add_u64 v[228:229], s[56:57], 0, v[132:133]
	global_load_lds_dwordx4 v130, s[72:73]
	s_add_i32 m0, s74, 0x2000
	s_nop 0
	global_load_lds_dwordx4 v134, s[72:73]
	v_lshl_add_u64 v[226:227], s[56:57], 0, v[128:129]
	s_mov_b32 m0, s29
	s_nop 0
	global_load_lds_dwordx4 v128, s[56:57]
	s_mov_b32 m0, s30
	s_nop 0
	global_load_lds_dwordx4 v132, s[56:57]
	s_waitcnt vmcnt(8)
	s_waitcnt lgkmcnt(0)
	s_barrier
	s_setprio 0
	s_waitcnt lgkmcnt(0)
	v_mfma_f32_16x16x32_bf16 v[60:63], v[156:159], v[194:197], v[60:63]
	v_mfma_f32_16x16x32_bf16 v[56:59], v[170:173], v[194:197], v[56:59]
	v_mfma_f32_16x16x32_bf16 v[52:55], v[156:159], v[202:205], v[52:55]
	v_mfma_f32_16x16x32_bf16 v[44:47], v[170:173], v[202:205], v[44:47]
	v_mfma_f32_16x16x32_bf16 v[36:39], v[156:159], v[210:213], v[36:39]
	v_mfma_f32_16x16x32_bf16 v[28:31], v[170:173], v[210:213], v[28:31]
	v_mfma_f32_16x16x32_bf16 v[20:23], v[156:159], v[218:221], v[20:23]
	v_mfma_f32_16x16x32_bf16 v[12:15], v[170:173], v[218:221], v[12:15]
	v_mfma_f32_16x16x32_bf16 v[60:63], v[166:169], v[198:201], v[60:63]
	v_mfma_f32_16x16x32_bf16 v[56:59], v[174:177], v[198:201], v[56:59]
	v_mfma_f32_16x16x32_bf16 v[52:55], v[166:169], v[206:209], v[52:55]
	v_mfma_f32_16x16x32_bf16 v[44:47], v[174:177], v[206:209], v[44:47]
	v_mfma_f32_16x16x32_bf16 v[36:39], v[166:169], v[214:217], v[36:39]
	v_mfma_f32_16x16x32_bf16 v[28:31], v[174:177], v[214:217], v[28:31]
	v_mfma_f32_16x16x32_bf16 v[20:23], v[166:169], v[222:225], v[20:23]
	v_mfma_f32_16x16x32_bf16 v[12:15], v[174:177], v[222:225], v[12:15]
	v_mfma_f32_16x16x32_bf16 v[48:51], v[178:181], v[194:197], v[48:51]
	v_mfma_f32_16x16x32_bf16 v[40:43], v[186:189], v[194:197], v[40:43]
	v_mfma_f32_16x16x32_bf16 v[32:35], v[178:181], v[202:205], v[32:35]
	v_mfma_f32_16x16x32_bf16 v[24:27], v[186:189], v[202:205], v[24:27]
	v_mfma_f32_16x16x32_bf16 v[16:19], v[178:181], v[210:213], v[16:19]
	v_mfma_f32_16x16x32_bf16 v[8:11], v[186:189], v[210:213], v[8:11]
	v_mfma_f32_16x16x32_bf16 v[4:7], v[178:181], v[218:221], v[4:7]
	v_mfma_f32_16x16x32_bf16 v[0:3], v[186:189], v[218:221], v[0:3]
	v_mfma_f32_16x16x32_bf16 v[48:51], v[182:185], v[198:201], v[48:51]
	v_mfma_f32_16x16x32_bf16 v[40:43], v[190:193], v[198:201], v[40:43]
	v_mfma_f32_16x16x32_bf16 v[32:35], v[182:185], v[206:209], v[32:35]
	v_mfma_f32_16x16x32_bf16 v[24:27], v[190:193], v[206:209], v[24:27]
	v_mfma_f32_16x16x32_bf16 v[16:19], v[182:185], v[214:217], v[16:19]
	v_mfma_f32_16x16x32_bf16 v[8:11], v[190:193], v[214:217], v[8:11]
	v_mfma_f32_16x16x32_bf16 v[4:7], v[182:185], v[222:225], v[4:7]
	v_mfma_f32_16x16x32_bf16 v[0:3], v[190:193], v[222:225], v[0:3]
	s_setprio 1
	s_barrier
; #define PG8_STAGE(bufoff, gbase, voff) do { _Pragma("unroll") for (int _i = 0; _i < 2; ++_i) \
;         __builtin_amdgcn_global_load_lds((const unsigned*)((const char*)(gbase) + (voff)[_i]), (PG8_LAS unsigned*)(lds + (bufoff) + ldsw + _i * 8192), 16, 0, 0); } while (0)
; #define PG8_LDA(dst, b, h) do { _Pragma("unroll") for (int m = 0; m < 4; ++m) _Pragma("unroll") for (int k = 0; k < 2; ++k) dst[m][k] = *(const PG8_LAS bf16x8*)(lds + PG8_SA(b, h) + aoff + m * 2048 + k * 1024); } while (0)
; #define PG8_LDB(dst, b, h) do { _Pragma("unroll") for (int n = 0; n < 2; ++n) _Pragma("unroll") for (int k = 0; k < 2; ++k) dst[n][k] = *(const PG8_LAS bf16x8*)(lds + PG8_SB(b, h) + boff + n * 2048 + k * 1024); } while (0)
; #define PG8_MMA(ai, bj, At, Bt) do { __builtin_amdgcn_s_setprio(1); _Pragma("unroll") for (int m = 0; m < 4; ++m) _Pragma("unroll") for (int n = 0; n < 2; ++n) _Pragma("unroll") for (int k = 0; k < 2; ++k) \
;         acc[ai][bj][m][n] = __builtin_amdgcn_mfma_f32_16x16x32_bf16(Bt[n][k], At[m][k], acc[ai][bj][m][n], 0, 0, 0); __builtin_amdgcn_s_setprio(0); } while (0)
; #define PG8_WAIT_V(n) asm volatile("s_waitcnt vmcnt(" #n ")" ::: "memory")
; #define PG8_WAIT_L(n) asm volatile("s_waitcnt lgkmcnt(" #n ")" ::: "memory")
; #define PG8_BAR __builtin_amdgcn_s_barrier()
; #define PG8_SCHED __builtin_amdgcn_sched_barrier(0)
; template <class Epi, class Sched, bool ALIGN_EPI = false, bool SP2 = false>
; __device__ __forceinline__ void gemm_phase(PG8_LAS unsigned char* lds, const Gemm g, const Sched& S, const Epi& E) {
;     ...
;         for (int t = 0; t < nt; t += 2) {
;     ...
;             PG8_LDB(B0, 1, 0); PG8_LDB(B1, 1, 1); PG8_SCHED; PG8_LDA(At, 1, 0); PG8_STAGE(PG8_SA(0, 1), a2 + hstepA, voffA);
;             PG8_WAIT_V(8); PG8_WAIT_L(0); PG8_BAR; PG8_MMA(0, 0, At, B0); PG8_MMA(0, 1, At, B1); PG8_BAR; PG8_SCHED;
;             PG8_LDA(At, 1, 1); PG8_STAGE(PG8_SB(1, 0), b3, voffB); PG8_STAGE(PG8_SB(1, 1), b3 + hstepB, voffB); PG8_STAGE(PG8_SA(1, 0), a3, voffA);
;             PG8_WAIT_V(8); PG8_WAIT_L(0); PG8_BAR; PG8_MMA(1, 0, At, B0); PG8_MMA(1, 1, At, B1); PG8_BAR; PG8_SCHED;
	s_add_i32 s72, 0, 0x18000
	v_add_u32_e32 v163, s72, v151
	s_add_i32 s73, 0, 0x1c000
	ds_read_b128 v[156:159], v163
	ds_read_b128 v[166:169], v163 offset:1024
	ds_read_b128 v[170:173], v163 offset:2048
	ds_read_b128 v[174:177], v163 offset:3072
	v_add_u32_e32 v163, s73, v151
	ds_read_b128 v[178:181], v163
	ds_read_b128 v[182:185], v163 offset:1024
	ds_read_b128 v[186:189], v163 offset:2048
	ds_read_b128 v[190:193], v163 offset:3072
	s_add_u32 s56, s56, 0x80000
	s_addc_u32 s57, s57, 0
	s_mov_b32 m0, s31
	ds_read_b128 v[194:197], v155 offset:32768
	ds_read_b128 v[198:201], v155 offset:33792
	ds_read_b128 v[202:205], v155 offset:34816
	ds_read_b128 v[206:209], v155 offset:35840
	ds_read_b128 v[210:213], v155 offset:36864
	ds_read_b128 v[214:217], v155 offset:37888
	ds_read_b128 v[218:221], v155 offset:38912
	ds_read_b128 v[222:225], v155 offset:39936
	global_load_lds_dwordx4 v128, s[56:57]
	s_mov_b32 m0, s33
	s_nop 0
	global_load_lds_dwordx4 v132, s[56:57]
	s_waitcnt vmcnt(8)
	s_waitcnt lgkmcnt(0)
	s_barrier
	s_setprio 0
	s_waitcnt lgkmcnt(0)
	v_mfma_f32_16x16x32_bf16 v[124:127], v[156:159], v[194:197], v[124:127]
	v_mfma_f32_16x16x32_bf16 v[120:123], v[170:173], v[194:197], v[120:123]
	v_mfma_f32_16x16x32_bf16 v[116:119], v[156:159], v[202:205], v[116:119]
	v_mfma_f32_16x16x32_bf16 v[108:111], v[170:173], v[202:205], v[108:111]
	v_mfma_f32_16x16x32_bf16 v[100:103], v[156:159], v[210:213], v[100:103]
	v_mfma_f32_16x16x32_bf16 v[92:95], v[170:173], v[210:213], v[92:95]
	v_mfma_f32_16x16x32_bf16 v[84:87], v[156:159], v[218:221], v[84:87]
	v_mfma_f32_16x16x32_bf16 v[76:79], v[170:173], v[218:221], v[76:79]
	v_mfma_f32_16x16x32_bf16 v[124:127], v[166:169], v[198:201], v[124:127]
	v_mfma_f32_16x16x32_bf16 v[120:123], v[174:177], v[198:201], v[120:123]
	v_mfma_f32_16x16x32_bf16 v[116:119], v[166:169], v[206:209], v[116:119]
	v_mfma_f32_16x16x32_bf16 v[108:111], v[174:177], v[206:209], v[108:111]
	v_mfma_f32_16x16x32_bf16 v[100:103], v[166:169], v[214:217], v[100:103]
	v_mfma_f32_16x16x32_bf16 v[92:95], v[174:177], v[214:217], v[92:95]
	v_mfma_f32_16x16x32_bf16 v[84:87], v[166:169], v[222:225], v[84:87]
	v_mfma_f32_16x16x32_bf16 v[76:79], v[174:177], v[222:225], v[76:79]
	v_mfma_f32_16x16x32_bf16 v[112:115], v[178:181], v[194:197], v[112:115]
	v_mfma_f32_16x16x32_bf16 v[104:107], v[186:189], v[194:197], v[104:107]
	v_mfma_f32_16x16x32_bf16 v[96:99], v[178:181], v[202:205], v[96:99]
	v_mfma_f32_16x16x32_bf16 v[88:91], v[186:189], v[202:205], v[88:91]
	v_mfma_f32_16x16x32_bf16 v[80:83], v[178:181], v[210:213], v[80:83]
	v_mfma_f32_16x16x32_bf16 v[72:75], v[186:189], v[210:213], v[72:75]
	v_mfma_f32_16x16x32_bf16 v[68:71], v[178:181], v[218:221], v[68:71]
	v_mfma_f32_16x16x32_bf16 v[64:67], v[186:189], v[218:221], v[64:67]
	v_mfma_f32_16x16x32_bf16 v[112:115], v[182:185], v[198:201], v[112:115]
	v_mfma_f32_16x16x32_bf16 v[104:107], v[190:193], v[198:201], v[104:107]
	v_mfma_f32_16x16x32_bf16 v[96:99], v[182:185], v[206:209], v[96:99]
	v_mfma_f32_16x16x32_bf16 v[88:91], v[190:193], v[206:209], v[88:91]
	v_mfma_f32_16x16x32_bf16 v[80:83], v[182:185], v[214:217], v[80:83]
	v_mfma_f32_16x16x32_bf16 v[72:75], v[190:193], v[214:217], v[72:75]
	v_mfma_f32_16x16x32_bf16 v[68:71], v[182:185], v[222:225], v[68:71]
	v_mfma_f32_16x16x32_bf16 v[64:67], v[190:193], v[222:225], v[64:67]
	s_setprio 1
	s_barrier
	s_add_i32 s56, s72, s28
	v_lshl_add_u64 v[144:145], v[144:145], 0, s[16:17]
	s_mov_b32 m0, s56
	ds_read_b128 v[194:197], v155 offset:49152
	ds_read_b128 v[198:201], v155 offset:50176
	ds_read_b128 v[202:205], v155 offset:51200
	ds_read_b128 v[206:209], v155 offset:52224
	ds_read_b128 v[210:213], v155 offset:53248
	ds_read_b128 v[214:217], v155 offset:54272
	ds_read_b128 v[218:221], v155 offset:55296
	ds_read_b128 v[222:225], v155 offset:56320
	global_load_lds_dwordx4 v[144:145], off
	s_add_i32 m0, s56, 0x2000
	s_add_u32 s54, s54, 0x80080
	v_lshl_add_u64 v[144:145], v[160:161], 0, s[16:17]
	s_addc_u32 s55, s55, 0
	s_add_i32 s56, s73, s28
	global_load_lds_dwordx4 v[144:145], off
	s_mov_b32 m0, s56
	s_nop 0
	global_load_lds_dwordx4 v130, s[54:55]
	s_add_i32 m0, s56, 0x2000
	s_nop 0
	global_load_lds_dwordx4 v134, s[54:55]
	v_lshl_add_u64 v[144:145], v[226:227], 0, s[16:17]
	s_mov_b32 m0, s35
	s_nop 0
	global_load_lds_dwordx4 v[144:145], off
	v_lshl_add_u64 v[144:145], v[228:229], 0, s[16:17]
	s_mov_b32 m0, s51
	s_nop 0
	global_load_lds_dwordx4 v[144:145], off
	s_waitcnt vmcnt(8)
	s_waitcnt lgkmcnt(0)
	s_barrier
	s_setprio 0
	s_waitcnt lgkmcnt(0)
	v_mfma_f32_16x16x32_bf16 v[60:63], v[156:159], v[194:197], v[60:63]
	v_mfma_f32_16x16x32_bf16 v[56:59], v[170:173], v[194:197], v[56:59]
	v_mfma_f32_16x16x32_bf16 v[52:55], v[156:159], v[202:205], v[52:55]
	v_mfma_f32_16x16x32_bf16 v[44:47], v[170:173], v[202:205], v[44:47]
	v_mfma_f32_16x16x32_bf16 v[36:39], v[156:159], v[210:213], v[36:39]
	v_mfma_f32_16x16x32_bf16 v[28:31], v[170:173], v[210:213], v[28:31]
	v_mfma_f32_16x16x32_bf16 v[20:23], v[156:159], v[218:221], v[20:23]
	v_mfma_f32_16x16x32_bf16 v[12:15], v[170:173], v[218:221], v[12:15]
	v_mfma_f32_16x16x32_bf16 v[60:63], v[166:169], v[198:201], v[60:63]
	v_mfma_f32_16x16x32_bf16 v[56:59], v[174:177], v[198:201], v[56:59]
	v_mfma_f32_16x16x32_bf16 v[52:55], v[166:169], v[206:209], v[52:55]
	v_mfma_f32_16x16x32_bf16 v[44:47], v[174:177], v[206:209], v[44:47]
	v_mfma_f32_16x16x32_bf16 v[36:39], v[166:169], v[214:217], v[36:39]
	v_mfma_f32_16x16x32_bf16 v[28:31], v[174:177], v[214:217], v[28:31]
	v_mfma_f32_16x16x32_bf16 v[20:23], v[166:169], v[222:225], v[20:23]
	v_mfma_f32_16x16x32_bf16 v[12:15], v[174:177], v[222:225], v[12:15]
	v_mfma_f32_16x16x32_bf16 v[48:51], v[178:181], v[194:197], v[48:51]
	v_mfma_f32_16x16x32_bf16 v[40:43], v[186:189], v[194:197], v[40:43]
	v_mfma_f32_16x16x32_bf16 v[32:35], v[178:181], v[202:205], v[32:35]
	v_mfma_f32_16x16x32_bf16 v[24:27], v[186:189], v[202:205], v[24:27]
	v_mfma_f32_16x16x32_bf16 v[16:19], v[178:181], v[210:213], v[16:19]
	v_mfma_f32_16x16x32_bf16 v[8:11], v[186:189], v[210:213], v[8:11]
	v_mfma_f32_16x16x32_bf16 v[4:7], v[178:181], v[218:221], v[4:7]
	v_mfma_f32_16x16x32_bf16 v[0:3], v[186:189], v[218:221], v[0:3]
	v_mfma_f32_16x16x32_bf16 v[48:51], v[182:185], v[198:201], v[48:51]
	v_mfma_f32_16x16x32_bf16 v[40:43], v[190:193], v[198:201], v[40:43]
	v_mfma_f32_16x16x32_bf16 v[32:35], v[182:185], v[206:209], v[32:35]
	v_mfma_f32_16x16x32_bf16 v[24:27], v[190:193], v[206:209], v[24:27]
	v_mfma_f32_16x16x32_bf16 v[16:19], v[182:185], v[214:217], v[16:19]
	v_mfma_f32_16x16x32_bf16 v[8:11], v[190:193], v[214:217], v[8:11]
	v_mfma_f32_16x16x32_bf16 v[4:7], v[182:185], v[222:225], v[4:7]
	v_mfma_f32_16x16x32_bf16 v[0:3], v[190:193], v[222:225], v[0:3]
	s_add_i32 s71, s71, 2
	s_add_u32 s52, s52, 0x100
	s_addc_u32 s53, s53, 0
	s_add_u32 s69, s69, 0x100
	s_addc_u32 s70, s70, 0
	s_cmp_gt_u32 s71, 29
	s_setprio 1
	s_barrier
	s_cbranch_scc0 .LBB0_927
	s_and_b64 vcc, exec, s[18:19]
	s_cbranch_vccz .LBB0_930
	s_barrier

; #define PG8_STAGE(bufoff, gbase, voff) do { _Pragma("unroll") for (int _i = 0; _i < 2; ++_i) \
;         __builtin_amdgcn_global_load_lds((const unsigned*)((const char*)(gbase) + (voff)[_i]), (PG8_LAS unsigned*)(lds + (bufoff) + ldsw + _i * 8192), 16, 0, 0); } while (0)
; #define PG8_LDA(dst, b, h) do { _Pragma("unroll") for (int m = 0; m < 4; ++m) _Pragma("unroll") for (int k = 0; k < 2; ++k) dst[m][k] = *(const PG8_LAS bf16x8*)(lds + PG8_SA(b, h) + aoff + m * 2048 + k * 1024); } while (0)
; #define PG8_LDB(dst, b, h) do { _Pragma("unroll") for (int n = 0; n < 2; ++n) _Pragma("unroll") for (int k = 0; k < 2; ++k) dst[n][k] = *(const PG8_LAS bf16x8*)(lds + PG8_SB(b, h) + boff + n * 2048 + k * 1024); } while (0)
; #define PG8_MMA(ai, bj, At, Bt) do { __builtin_amdgcn_s_setprio(1); _Pragma("unroll") for (int m = 0; m < 4; ++m) _Pragma("unroll") for (int n = 0; n < 2; ++n) _Pragma("unroll") for (int k = 0; k < 2; ++k) \
;         acc[ai][bj][m][n] = __builtin_amdgcn_mfma_f32_16x16x32_bf16(Bt[n][k], At[m][k], acc[ai][bj][m][n], 0, 0, 0); __builtin_amdgcn_s_setprio(0); } while (0)
; #define PG8_WAIT_V(n) asm volatile("s_waitcnt vmcnt(" #n ")" ::: "memory")
; #define PG8_WAIT_L(n) asm volatile("s_waitcnt lgkmcnt(" #n ")" ::: "memory")
; template <class Epi, class Sched, bool ALIGN_EPI = false, bool SP2 = false>
; __device__ __forceinline__ void gemm_phase(PG8_LAS unsigned char* lds, const Gemm g, const Sched& S, const Epi& E) {
;     ...
;             const bool last = (t == nt - 2);
;             const char* a1 = cA + (size_t)(t + 1) * kstep;
;             const char* a2 = last ? nA : cA + (size_t)(t + 2) * kstep; const char* b2 = last ? nB : cB + (size_t)(t + 2) * kstep;
;             const char* a3 = a2 + kstep; const char* b3 = b2 + kstep;
;             if (last && has_next) S.a_ready(nxt);
;             if constexpr (SP2) {
;             PG8_LDB(B0, 0, 0); PG8_LDB(B1, 0, 1); PG8_SCHED; PG8_LDA(At, 0, 0); PG8_STAGE(PG8_SA(1, 1), a1 + hstepA, voffA);
;             PG8_WAIT_V(8); PG8_WAIT_L(0); PG8_BAR; PG8_MMA(0, 0, At, B0); PG8_MMA(0, 1, At, B1); PG8_BAR; PG8_SCHED;
;             PG8_LDA(At, 0, 1); PG8_STAGE(PG8_SB(0, 0), b2, voffB); PG8_STAGE(PG8_SB(0, 1), b2 + hstepB, voffB); PG8_STAGE(PG8_SA(0, 0), a2, voffA);
;             PG8_WAIT_V(8); PG8_WAIT_L(0); PG8_BAR; PG8_MMA(1, 0, At, B0); PG8_MMA(1, 1, At, B1); PG8_BAR; PG8_SCHED;
.LBB0_1082:
	ds_read_b128 v[150:153], v147
	ds_read_b128 v[154:157], v147 offset:1024
	ds_read_b128 v[158:161], v147 offset:2048
	ds_read_b128 v[166:169], v147 offset:3072
	ds_read_b128 v[170:173], v148
	ds_read_b128 v[174:177], v148 offset:1024
	ds_read_b128 v[178:181], v148 offset:2048
	ds_read_b128 v[182:185], v148 offset:3072
	s_add_u32 s50, s48, 0xfff80080
	s_addc_u32 s51, s49, -1
	s_cmp_eq_u32 s66, 28
	s_cselect_b32 s53, s41, s51
	s_cselect_b32 s52, s62, s50
	s_cselect_b32 s51, s39, s65
	s_cselect_b32 s50, s63, s64
	s_add_i32 m0, s30, 0xc000
	ds_read_b128 v[186:189], v149
	ds_read_b128 v[190:193], v149 offset:1024
	ds_read_b128 v[194:197], v149 offset:2048
	ds_read_b128 v[198:201], v149 offset:3072
	ds_read_b128 v[202:205], v149 offset:4096
	ds_read_b128 v[206:209], v149 offset:5120
	ds_read_b128 v[210:213], v149 offset:6144
	ds_read_b128 v[214:217], v149 offset:7168
	global_load_lds_dwordx4 v136, s[48:49]
	s_add_i32 m0, s30, 0xe000
	s_nop 0
	global_load_lds_dwordx4 v138, s[48:49]
	s_waitcnt vmcnt(8)
	s_waitcnt lgkmcnt(0)
	s_barrier
	s_setprio 0
	s_waitcnt lgkmcnt(0)
	v_mfma_f32_16x16x32_bf16 v[124:127], v[150:153], v[186:189], v[124:127]
	v_mfma_f32_16x16x32_bf16 v[120:123], v[158:161], v[186:189], v[120:123]
	v_mfma_f32_16x16x32_bf16 v[112:115], v[150:153], v[194:197], v[112:115]
	v_mfma_f32_16x16x32_bf16 v[104:107], v[158:161], v[194:197], v[104:107]
	v_mfma_f32_16x16x32_bf16 v[96:99], v[150:153], v[202:205], v[96:99]
	v_mfma_f32_16x16x32_bf16 v[88:91], v[158:161], v[202:205], v[88:91]
	v_mfma_f32_16x16x32_bf16 v[80:83], v[150:153], v[210:213], v[80:83]
	v_mfma_f32_16x16x32_bf16 v[72:75], v[158:161], v[210:213], v[72:75]
	v_mfma_f32_16x16x32_bf16 v[124:127], v[154:157], v[190:193], v[124:127]
	v_mfma_f32_16x16x32_bf16 v[120:123], v[166:169], v[190:193], v[120:123]
	v_mfma_f32_16x16x32_bf16 v[112:115], v[154:157], v[198:201], v[112:115]
	v_mfma_f32_16x16x32_bf16 v[104:107], v[166:169], v[198:201], v[104:107]
	v_mfma_f32_16x16x32_bf16 v[96:99], v[154:157], v[206:209], v[96:99]
	v_mfma_f32_16x16x32_bf16 v[88:91], v[166:169], v[206:209], v[88:91]
	v_mfma_f32_16x16x32_bf16 v[80:83], v[154:157], v[214:217], v[80:83]
	v_mfma_f32_16x16x32_bf16 v[72:75], v[166:169], v[214:217], v[72:75]
	v_mfma_f32_16x16x32_bf16 v[116:119], v[170:173], v[186:189], v[116:119]
	v_mfma_f32_16x16x32_bf16 v[108:111], v[178:181], v[186:189], v[108:111]
	v_mfma_f32_16x16x32_bf16 v[100:103], v[170:173], v[194:197], v[100:103]
	v_mfma_f32_16x16x32_bf16 v[92:95], v[178:181], v[194:197], v[92:95]
	v_mfma_f32_16x16x32_bf16 v[84:87], v[170:173], v[202:205], v[84:87]
	v_mfma_f32_16x16x32_bf16 v[76:79], v[178:181], v[202:205], v[76:79]
	v_mfma_f32_16x16x32_bf16 v[68:71], v[170:173], v[210:213], v[68:71]
	v_mfma_f32_16x16x32_bf16 v[64:67], v[178:181], v[210:213], v[64:67]
	v_mfma_f32_16x16x32_bf16 v[116:119], v[174:177], v[190:193], v[116:119]
	v_mfma_f32_16x16x32_bf16 v[108:111], v[182:185], v[190:193], v[108:111]
	v_mfma_f32_16x16x32_bf16 v[100:103], v[174:177], v[198:201], v[100:103]
	v_mfma_f32_16x16x32_bf16 v[92:95], v[182:185], v[198:201], v[92:95]
	v_mfma_f32_16x16x32_bf16 v[84:87], v[174:177], v[206:209], v[84:87]
	v_mfma_f32_16x16x32_bf16 v[76:79], v[182:185], v[206:209], v[76:79]
	v_mfma_f32_16x16x32_bf16 v[68:71], v[174:177], v[214:217], v[68:71]
	v_mfma_f32_16x16x32_bf16 v[64:67], v[182:185], v[214:217], v[64:67]
	s_setprio 1
	s_barrier
	s_add_i32 s67, s55, s28
	v_lshl_add_u64 v[218:219], s[50:51], 0, v[132:133]
	s_mov_b32 m0, s67
	ds_read_b128 v[186:189], v149 offset:16384
	ds_read_b128 v[190:193], v149 offset:17408
	ds_read_b128 v[194:197], v149 offset:18432
	ds_read_b128 v[198:201], v149 offset:19456
	ds_read_b128 v[202:205], v149 offset:20480
	ds_read_b128 v[206:209], v149 offset:21504
	ds_read_b128 v[210:213], v149 offset:22528
	ds_read_b128 v[214:217], v149 offset:23552
	global_load_lds_dwordx4 v132, s[50:51]
	s_add_i32 m0, s67, 0x2000
	s_add_u32 s68, s50, 0x80000
	v_lshl_add_u64 v[220:221], s[50:51], 0, v[128:129]
	s_addc_u32 s69, s51, 0
	s_add_i32 s67, s56, s28
	global_load_lds_dwordx4 v128, s[50:51]
	s_mov_b32 m0, s67
	v_lshl_add_u64 v[224:225], s[52:53], 0, v[130:131]
	global_load_lds_dwordx4 v132, s[68:69]
	s_add_i32 m0, s67, 0x2000
	s_nop 0
	global_load_lds_dwordx4 v128, s[68:69]
	v_lshl_add_u64 v[222:223], s[52:53], 0, v[134:135]
	s_mov_b32 m0, s30
	s_nop 0
	global_load_lds_dwordx4 v134, s[52:53]
	s_mov_b32 m0, s31
	s_nop 0
	global_load_lds_dwordx4 v130, s[52:53]
	s_waitcnt vmcnt(8)
	s_waitcnt lgkmcnt(0)
	s_barrier
	s_setprio 0
	s_waitcnt lgkmcnt(0)
	v_mfma_f32_16x16x32_bf16 v[60:63], v[150:153], v[186:189], v[60:63]
	v_mfma_f32_16x16x32_bf16 v[56:59], v[158:161], v[186:189], v[56:59]
	v_mfma_f32_16x16x32_bf16 v[48:51], v[150:153], v[194:197], v[48:51]
	v_mfma_f32_16x16x32_bf16 v[40:43], v[158:161], v[194:197], v[40:43]
	v_mfma_f32_16x16x32_bf16 v[32:35], v[150:153], v[202:205], v[32:35]
	v_mfma_f32_16x16x32_bf16 v[24:27], v[158:161], v[202:205], v[24:27]
	v_mfma_f32_16x16x32_bf16 v[16:19], v[150:153], v[210:213], v[16:19]
	v_mfma_f32_16x16x32_bf16 v[8:11], v[158:161], v[210:213], v[8:11]
	v_mfma_f32_16x16x32_bf16 v[60:63], v[154:157], v[190:193], v[60:63]
	v_mfma_f32_16x16x32_bf16 v[56:59], v[166:169], v[190:193], v[56:59]
	v_mfma_f32_16x16x32_bf16 v[48:51], v[154:157], v[198:201], v[48:51]
	v_mfma_f32_16x16x32_bf16 v[40:43], v[166:169], v[198:201], v[40:43]
	v_mfma_f32_16x16x32_bf16 v[32:35], v[154:157], v[206:209], v[32:35]
	v_mfma_f32_16x16x32_bf16 v[24:27], v[166:169], v[206:209], v[24:27]
	v_mfma_f32_16x16x32_bf16 v[16:19], v[154:157], v[214:217], v[16:19]
	v_mfma_f32_16x16x32_bf16 v[8:11], v[166:169], v[214:217], v[8:11]
	v_mfma_f32_16x16x32_bf16 v[52:55], v[170:173], v[186:189], v[52:55]
	v_mfma_f32_16x16x32_bf16 v[44:47], v[178:181], v[186:189], v[44:47]
	v_mfma_f32_16x16x32_bf16 v[36:39], v[170:173], v[194:197], v[36:39]
	v_mfma_f32_16x16x32_bf16 v[28:31], v[178:181], v[194:197], v[28:31]
	v_mfma_f32_16x16x32_bf16 v[20:23], v[170:173], v[202:205], v[20:23]
	v_mfma_f32_16x16x32_bf16 v[12:15], v[178:181], v[202:205], v[12:15]
	v_mfma_f32_16x16x32_bf16 v[4:7], v[170:173], v[210:213], v[4:7]
	v_mfma_f32_16x16x32_bf16 v[0:3], v[178:181], v[210:213], v[0:3]
	v_mfma_f32_16x16x32_bf16 v[52:55], v[174:177], v[190:193], v[52:55]
	v_mfma_f32_16x16x32_bf16 v[44:47], v[182:185], v[190:193], v[44:47]
	v_mfma_f32_16x16x32_bf16 v[36:39], v[174:177], v[198:201], v[36:39]
	v_mfma_f32_16x16x32_bf16 v[28:31], v[182:185], v[198:201], v[28:31]
	v_mfma_f32_16x16x32_bf16 v[20:23], v[174:177], v[206:209], v[20:23]
	v_mfma_f32_16x16x32_bf16 v[12:15], v[182:185], v[206:209], v[12:15]
	v_mfma_f32_16x16x32_bf16 v[4:7], v[174:177], v[214:217], v[4:7]
	v_mfma_f32_16x16x32_bf16 v[0:3], v[182:185], v[214:217], v[0:3]
	s_setprio 1
	s_barrier
; #define PG8_STAGE(bufoff, gbase, voff) do { _Pragma("unroll") for (int _i = 0; _i < 2; ++_i) \
;         __builtin_amdgcn_global_load_lds((const unsigned*)((const char*)(gbase) + (voff)[_i]), (PG8_LAS unsigned*)(lds + (bufoff) + ldsw + _i * 8192), 16, 0, 0); } while (0)
; #define PG8_LDA(dst, b, h) do { _Pragma("unroll") for (int m = 0; m < 4; ++m) _Pragma("unroll") for (int k = 0; k < 2; ++k) dst[m][k] = *(const PG8_LAS bf16x8*)(lds + PG8_SA(b, h) + aoff + m * 2048 + k * 1024); } while (0)
; #define PG8_LDB(dst, b, h) do { _Pragma("unroll") for (int n = 0; n < 2; ++n) _Pragma("unroll") for (int k = 0; k < 2; ++k) dst[n][k] = *(const PG8_LAS bf16x8*)(lds + PG8_SB(b, h) + boff + n * 2048 + k * 1024); } while (0)
; #define PG8_MMA(ai, bj, At, Bt) do { __builtin_amdgcn_s_setprio(1); _Pragma("unroll") for (int m = 0; m < 4; ++m) _Pragma("unroll") for (int n = 0; n < 2; ++n) _Pragma("unroll") for (int k = 0; k < 2; ++k) \
;         acc[ai][bj][m][n] = __builtin_amdgcn_mfma_f32_16x16x32_bf16(Bt[n][k], At[m][k], acc[ai][bj][m][n], 0, 0, 0); __builtin_amdgcn_s_setprio(0); } while (0)
; #define PG8_WAIT_V(n) asm volatile("s_waitcnt vmcnt(" #n ")" ::: "memory")
; #define PG8_WAIT_L(n) asm volatile("s_waitcnt lgkmcnt(" #n ")" ::: "memory")
; #define PG8_BAR __builtin_amdgcn_s_barrier()
; #define PG8_SCHED __builtin_amdgcn_sched_barrier(0)
; template <class Epi, class Sched, bool ALIGN_EPI = false, bool SP2 = false>
; __device__ __forceinline__ void gemm_phase(PG8_LAS unsigned char* lds, const Gemm g, const Sched& S, const Epi& E) {
;     ...
;         for (int t = 0; t < nt; t += 2) {
;     ...
;             PG8_LDB(B0, 1, 0); PG8_LDB(B1, 1, 1); PG8_SCHED; PG8_LDA(At, 1, 0); PG8_STAGE(PG8_SA(0, 1), a2 + hstepA, voffA);
;             PG8_WAIT_V(8); PG8_WAIT_L(0); PG8_BAR; PG8_MMA(0, 0, At, B0); PG8_MMA(0, 1, At, B1); PG8_BAR; PG8_SCHED;
;             PG8_LDA(At, 1, 1); PG8_STAGE(PG8_SB(1, 0), b3, voffB); PG8_STAGE(PG8_SB(1, 1), b3 + hstepB, voffB); PG8_STAGE(PG8_SA(1, 0), a3, voffA);
;             PG8_WAIT_V(8); PG8_WAIT_L(0); PG8_BAR; PG8_MMA(1, 0, At, B0); PG8_MMA(1, 1, At, B1); PG8_BAR; PG8_SCHED;
	s_add_i32 s67, 0, 0x18000
	v_add_u32_e32 v163, s67, v145
	s_add_i32 s68, 0, 0x1c000
	ds_read_b128 v[150:153], v163
	ds_read_b128 v[154:157], v163 offset:1024
	ds_read_b128 v[158:161], v163 offset:2048
	ds_read_b128 v[166:169], v163 offset:3072
	v_add_u32_e32 v163, s68, v145
	ds_read_b128 v[170:173], v163
	ds_read_b128 v[174:177], v163 offset:1024
	ds_read_b128 v[178:181], v163 offset:2048
	ds_read_b128 v[182:185], v163 offset:3072
	s_add_u32 s52, s52, 0x80000
	s_addc_u32 s53, s53, 0
	s_mov_b32 m0, s33
	ds_read_b128 v[186:189], v149 offset:32768
	ds_read_b128 v[190:193], v149 offset:33792
	ds_read_b128 v[194:197], v149 offset:34816
	ds_read_b128 v[198:201], v149 offset:35840
	ds_read_b128 v[202:205], v149 offset:36864
	ds_read_b128 v[206:209], v149 offset:37888
	ds_read_b128 v[210:213], v149 offset:38912
	ds_read_b128 v[214:217], v149 offset:39936
	global_load_lds_dwordx4 v134, s[52:53]
	s_mov_b32 m0, s34
	s_nop 0
	global_load_lds_dwordx4 v130, s[52:53]
	s_waitcnt vmcnt(8)
	s_waitcnt lgkmcnt(0)
	s_barrier
	s_setprio 0
	s_waitcnt lgkmcnt(0)
	v_mfma_f32_16x16x32_bf16 v[124:127], v[150:153], v[186:189], v[124:127]
	v_mfma_f32_16x16x32_bf16 v[120:123], v[158:161], v[186:189], v[120:123]
	v_mfma_f32_16x16x32_bf16 v[112:115], v[150:153], v[194:197], v[112:115]
	v_mfma_f32_16x16x32_bf16 v[104:107], v[158:161], v[194:197], v[104:107]
	v_mfma_f32_16x16x32_bf16 v[96:99], v[150:153], v[202:205], v[96:99]
	v_mfma_f32_16x16x32_bf16 v[88:91], v[158:161], v[202:205], v[88:91]
	v_mfma_f32_16x16x32_bf16 v[80:83], v[150:153], v[210:213], v[80:83]
	v_mfma_f32_16x16x32_bf16 v[72:75], v[158:161], v[210:213], v[72:75]
	v_mfma_f32_16x16x32_bf16 v[124:127], v[154:157], v[190:193], v[124:127]
	v_mfma_f32_16x16x32_bf16 v[120:123], v[166:169], v[190:193], v[120:123]
	v_mfma_f32_16x16x32_bf16 v[112:115], v[154:157], v[198:201], v[112:115]
	v_mfma_f32_16x16x32_bf16 v[104:107], v[166:169], v[198:201], v[104:107]
	v_mfma_f32_16x16x32_bf16 v[96:99], v[154:157], v[206:209], v[96:99]
	v_mfma_f32_16x16x32_bf16 v[88:91], v[166:169], v[206:209], v[88:91]
	v_mfma_f32_16x16x32_bf16 v[80:83], v[154:157], v[214:217], v[80:83]
	v_mfma_f32_16x16x32_bf16 v[72:75], v[166:169], v[214:217], v[72:75]
	v_mfma_f32_16x16x32_bf16 v[116:119], v[170:173], v[186:189], v[116:119]
	v_mfma_f32_16x16x32_bf16 v[108:111], v[178:181], v[186:189], v[108:111]
	v_mfma_f32_16x16x32_bf16 v[100:103], v[170:173], v[194:197], v[100:103]
	v_mfma_f32_16x16x32_bf16 v[92:95], v[178:181], v[194:197], v[92:95]
	v_mfma_f32_16x16x32_bf16 v[84:87], v[170:173], v[202:205], v[84:87]
	v_mfma_f32_16x16x32_bf16 v[76:79], v[178:181], v[202:205], v[76:79]
	v_mfma_f32_16x16x32_bf16 v[68:71], v[170:173], v[210:213], v[68:71]
	v_mfma_f32_16x16x32_bf16 v[64:67], v[178:181], v[210:213], v[64:67]
	v_mfma_f32_16x16x32_bf16 v[116:119], v[174:177], v[190:193], v[116:119]
	v_mfma_f32_16x16x32_bf16 v[108:111], v[182:185], v[190:193], v[108:111]
	v_mfma_f32_16x16x32_bf16 v[100:103], v[174:177], v[198:201], v[100:103]
	v_mfma_f32_16x16x32_bf16 v[92:95], v[182:185], v[198:201], v[92:95]
	v_mfma_f32_16x16x32_bf16 v[84:87], v[174:177], v[206:209], v[84:87]
	v_mfma_f32_16x16x32_bf16 v[76:79], v[182:185], v[206:209], v[76:79]
	v_mfma_f32_16x16x32_bf16 v[68:71], v[174:177], v[214:217], v[68:71]
	v_mfma_f32_16x16x32_bf16 v[64:67], v[182:185], v[214:217], v[64:67]
	s_setprio 1
	s_barrier
	s_add_i32 s52, s67, s28
	v_lshl_add_u64 v[218:219], v[218:219], 0, s[10:11]
	s_mov_b32 m0, s52
	ds_read_b128 v[186:189], v149 offset:49152
	ds_read_b128 v[190:193], v149 offset:50176
	ds_read_b128 v[194:197], v149 offset:51200
	ds_read_b128 v[198:201], v149 offset:52224
	ds_read_b128 v[202:205], v149 offset:53248
	ds_read_b128 v[206:209], v149 offset:54272
	ds_read_b128 v[210:213], v149 offset:55296
	ds_read_b128 v[214:217], v149 offset:56320
	global_load_lds_dwordx4 v[218:219], off
	s_add_i32 m0, s52, 0x2000
	s_add_u32 s50, s50, 0x80080
	v_lshl_add_u64 v[218:219], v[220:221], 0, s[10:11]
	s_addc_u32 s51, s51, 0
	s_add_i32 s52, s68, s28
	global_load_lds_dwordx4 v[218:219], off
	s_mov_b32 m0, s52
	s_nop 0
	global_load_lds_dwordx4 v132, s[50:51]
	s_add_i32 m0, s52, 0x2000
	s_nop 0
	global_load_lds_dwordx4 v128, s[50:51]
	v_lshl_add_u64 v[218:219], v[222:223], 0, s[10:11]
	s_mov_b32 m0, s47
	s_nop 0
	global_load_lds_dwordx4 v[218:219], off
	v_lshl_add_u64 v[218:219], v[224:225], 0, s[10:11]
	s_mov_b32 m0, s54
	s_nop 0
	global_load_lds_dwordx4 v[218:219], off
	s_waitcnt vmcnt(8)
	s_waitcnt lgkmcnt(0)
	s_barrier
	s_setprio 0
	s_waitcnt lgkmcnt(0)
	v_mfma_f32_16x16x32_bf16 v[60:63], v[150:153], v[186:189], v[60:63]
	v_mfma_f32_16x16x32_bf16 v[56:59], v[158:161], v[186:189], v[56:59]
	v_mfma_f32_16x16x32_bf16 v[48:51], v[150:153], v[194:197], v[48:51]
	v_mfma_f32_16x16x32_bf16 v[40:43], v[158:161], v[194:197], v[40:43]
	v_mfma_f32_16x16x32_bf16 v[32:35], v[150:153], v[202:205], v[32:35]
	v_mfma_f32_16x16x32_bf16 v[24:27], v[158:161], v[202:205], v[24:27]
	v_mfma_f32_16x16x32_bf16 v[16:19], v[150:153], v[210:213], v[16:19]
	v_mfma_f32_16x16x32_bf16 v[8:11], v[158:161], v[210:213], v[8:11]
	v_mfma_f32_16x16x32_bf16 v[60:63], v[154:157], v[190:193], v[60:63]
	v_mfma_f32_16x16x32_bf16 v[56:59], v[166:169], v[190:193], v[56:59]
	v_mfma_f32_16x16x32_bf16 v[48:51], v[154:157], v[198:201], v[48:51]
	v_mfma_f32_16x16x32_bf16 v[40:43], v[166:169], v[198:201], v[40:43]
	v_mfma_f32_16x16x32_bf16 v[32:35], v[154:157], v[206:209], v[32:35]
	v_mfma_f32_16x16x32_bf16 v[24:27], v[166:169], v[206:209], v[24:27]
	v_mfma_f32_16x16x32_bf16 v[16:19], v[154:157], v[214:217], v[16:19]
	v_mfma_f32_16x16x32_bf16 v[8:11], v[166:169], v[214:217], v[8:11]
	v_mfma_f32_16x16x32_bf16 v[52:55], v[170:173], v[186:189], v[52:55]
	v_mfma_f32_16x16x32_bf16 v[44:47], v[178:181], v[186:189], v[44:47]
	v_mfma_f32_16x16x32_bf16 v[36:39], v[170:173], v[194:197], v[36:39]
	v_mfma_f32_16x16x32_bf16 v[28:31], v[178:181], v[194:197], v[28:31]
	v_mfma_f32_16x16x32_bf16 v[20:23], v[170:173], v[202:205], v[20:23]
	v_mfma_f32_16x16x32_bf16 v[12:15], v[178:181], v[202:205], v[12:15]
	v_mfma_f32_16x16x32_bf16 v[4:7], v[170:173], v[210:213], v[4:7]
	v_mfma_f32_16x16x32_bf16 v[0:3], v[178:181], v[210:213], v[0:3]
	v_mfma_f32_16x16x32_bf16 v[52:55], v[174:177], v[190:193], v[52:55]
	v_mfma_f32_16x16x32_bf16 v[44:47], v[182:185], v[190:193], v[44:47]
	v_mfma_f32_16x16x32_bf16 v[36:39], v[174:177], v[198:201], v[36:39]
	v_mfma_f32_16x16x32_bf16 v[28:31], v[182:185], v[198:201], v[28:31]
	v_mfma_f32_16x16x32_bf16 v[20:23], v[174:177], v[206:209], v[20:23]
	v_mfma_f32_16x16x32_bf16 v[12:15], v[182:185], v[206:209], v[12:15]
	v_mfma_f32_16x16x32_bf16 v[4:7], v[174:177], v[214:217], v[4:7]
	v_mfma_f32_16x16x32_bf16 v[0:3], v[182:185], v[214:217], v[0:3]
	s_add_i32 s66, s66, 2
	s_add_u32 s48, s48, 0x100
	s_addc_u32 s49, s49, 0
	s_add_u32 s64, s64, 0x100
	s_addc_u32 s65, s65, 0
	s_cmp_gt_u32 s66, 29
	s_setprio 1
	s_barrier
	s_cbranch_scc0 .LBB0_1082
	s_and_b64 vcc, exec, s[16:17]
	s_cbranch_vccz .LBB0_1085
	s_barrier

; #define PG8_STAGE(bufoff, gbase, voff) do { _Pragma("unroll") for (int _i = 0; _i < 2; ++_i) \
;         __builtin_amdgcn_global_load_lds((const unsigned*)((const char*)(gbase) + (voff)[_i]), (PG8_LAS unsigned*)(lds + (bufoff) + ldsw + _i * 8192), 16, 0, 0); } while (0)
; #define PG8_LDA(dst, b, h) do { _Pragma("unroll") for (int m = 0; m < 4; ++m) _Pragma("unroll") for (int k = 0; k < 2; ++k) dst[m][k] = *(const PG8_LAS bf16x8*)(lds + PG8_SA(b, h) + aoff + m * 2048 + k * 1024); } while (0)
; #define PG8_LDB(dst, b, h) do { _Pragma("unroll") for (int n = 0; n < 2; ++n) _Pragma("unroll") for (int k = 0; k < 2; ++k) dst[n][k] = *(const PG8_LAS bf16x8*)(lds + PG8_SB(b, h) + boff + n * 2048 + k * 1024); } while (0)
; #define PG8_MMA(ai, bj, At, Bt) do { __builtin_amdgcn_s_setprio(1); _Pragma("unroll") for (int m = 0; m < 4; ++m) _Pragma("unroll") for (int n = 0; n < 2; ++n) _Pragma("unroll") for (int k = 0; k < 2; ++k) \
;         acc[ai][bj][m][n] = __builtin_amdgcn_mfma_f32_16x16x32_bf16(Bt[n][k], At[m][k], acc[ai][bj][m][n], 0, 0, 0); __builtin_amdgcn_s_setprio(0); } while (0)
; #define PG8_WAIT_V(n) asm volatile("s_waitcnt vmcnt(" #n ")" ::: "memory")
; #define PG8_WAIT_L(n) asm volatile("s_waitcnt lgkmcnt(" #n ")" ::: "memory")
; template <class Epi, class Sched, bool ALIGN_EPI = false, bool SP2 = false>
; __device__ __forceinline__ void gemm_phase(PG8_LAS unsigned char* lds, const Gemm g, const Sched& S, const Epi& E) {
;     ...
;             const bool last = (t == nt - 2);
;             const char* a1 = cA + (size_t)(t + 1) * kstep;
;             const char* a2 = last ? nA : cA + (size_t)(t + 2) * kstep; const char* b2 = last ? nB : cB + (size_t)(t + 2) * kstep;
;             const char* a3 = a2 + kstep; const char* b3 = b2 + kstep;
;             if (last && has_next) S.a_ready(nxt);
;             if constexpr (SP2) {
;             PG8_LDB(B0, 0, 0); PG8_LDB(B1, 0, 1); PG8_SCHED; PG8_LDA(At, 0, 0); PG8_STAGE(PG8_SA(1, 1), a1 + hstepA, voffA);
;             PG8_WAIT_V(8); PG8_WAIT_L(0); PG8_BAR; PG8_MMA(0, 0, At, B0); PG8_MMA(0, 1, At, B1); PG8_BAR; PG8_SCHED;
;             PG8_LDA(At, 0, 1); PG8_STAGE(PG8_SB(0, 0), b2, voffB); PG8_STAGE(PG8_SB(0, 1), b2 + hstepB, voffB); PG8_STAGE(PG8_SA(0, 0), a2, voffA);
;             PG8_WAIT_V(8); PG8_WAIT_L(0); PG8_BAR; PG8_MMA(1, 0, At, B0); PG8_MMA(1, 1, At, B1); PG8_BAR; PG8_SCHED;
.LBB0_1161:
	ds_read_b128 v[166:169], v157
	ds_read_b128 v[170:173], v157 offset:1024
	ds_read_b128 v[174:177], v157 offset:2048
	ds_read_b128 v[178:181], v157 offset:3072
	ds_read_b128 v[182:185], v158
	ds_read_b128 v[186:189], v158 offset:1024
	ds_read_b128 v[190:193], v158 offset:2048
	ds_read_b128 v[194:197], v158 offset:3072
	s_add_u32 s50, s48, 0xffe00080
	s_addc_u32 s51, s49, -1
	s_cmpk_eq_i32 s65, 0x7c
	s_cselect_b32 s53, s41, s51
	s_cselect_b32 s52, s61, s50
	s_cselect_b32 s51, s39, s64
	s_cselect_b32 s50, s62, s63
	s_add_i32 m0, s29, 0xc000
	ds_read_b128 v[198:201], v159
	ds_read_b128 v[202:205], v159 offset:1024
	ds_read_b128 v[206:209], v159 offset:2048
	ds_read_b128 v[210:213], v159 offset:3072
	ds_read_b128 v[214:217], v159 offset:4096
	ds_read_b128 v[218:221], v159 offset:5120
	ds_read_b128 v[222:225], v159 offset:6144
	ds_read_b128 v[226:229], v159 offset:7168
	global_load_lds_dwordx4 v136, s[48:49]
	s_add_i32 m0, s29, 0xe000
	s_nop 0
	global_load_lds_dwordx4 v138, s[48:49]
	s_waitcnt vmcnt(8)
	s_waitcnt lgkmcnt(0)
	s_barrier
	s_setprio 0
	s_waitcnt lgkmcnt(0)
	v_mfma_f32_16x16x32_bf16 v[124:127], v[166:169], v[198:201], v[124:127]
	v_mfma_f32_16x16x32_bf16 v[120:123], v[174:177], v[198:201], v[120:123]
	v_mfma_f32_16x16x32_bf16 v[116:119], v[166:169], v[206:209], v[116:119]
	v_mfma_f32_16x16x32_bf16 v[108:111], v[174:177], v[206:209], v[108:111]
	v_mfma_f32_16x16x32_bf16 v[100:103], v[166:169], v[214:217], v[100:103]
	v_mfma_f32_16x16x32_bf16 v[92:95], v[174:177], v[214:217], v[92:95]
	v_mfma_f32_16x16x32_bf16 v[80:83], v[166:169], v[222:225], v[80:83]
	v_mfma_f32_16x16x32_bf16 v[72:75], v[174:177], v[222:225], v[72:75]
	v_mfma_f32_16x16x32_bf16 v[124:127], v[170:173], v[202:205], v[124:127]
	v_mfma_f32_16x16x32_bf16 v[120:123], v[178:181], v[202:205], v[120:123]
	v_mfma_f32_16x16x32_bf16 v[116:119], v[170:173], v[210:213], v[116:119]
	v_mfma_f32_16x16x32_bf16 v[108:111], v[178:181], v[210:213], v[108:111]
	v_mfma_f32_16x16x32_bf16 v[100:103], v[170:173], v[218:221], v[100:103]
	v_mfma_f32_16x16x32_bf16 v[92:95], v[178:181], v[218:221], v[92:95]
	v_mfma_f32_16x16x32_bf16 v[80:83], v[170:173], v[226:229], v[80:83]
	v_mfma_f32_16x16x32_bf16 v[72:75], v[178:181], v[226:229], v[72:75]
	v_mfma_f32_16x16x32_bf16 v[112:115], v[182:185], v[198:201], v[112:115]
	v_mfma_f32_16x16x32_bf16 v[104:107], v[190:193], v[198:201], v[104:107]
	v_mfma_f32_16x16x32_bf16 v[96:99], v[182:185], v[206:209], v[96:99]
	v_mfma_f32_16x16x32_bf16 v[88:91], v[190:193], v[206:209], v[88:91]
	v_mfma_f32_16x16x32_bf16 v[84:87], v[182:185], v[214:217], v[84:87]
	v_mfma_f32_16x16x32_bf16 v[76:79], v[190:193], v[214:217], v[76:79]
	v_mfma_f32_16x16x32_bf16 v[68:71], v[182:185], v[222:225], v[68:71]
	v_mfma_f32_16x16x32_bf16 v[64:67], v[190:193], v[222:225], v[64:67]
	v_mfma_f32_16x16x32_bf16 v[112:115], v[186:189], v[202:205], v[112:115]
	v_mfma_f32_16x16x32_bf16 v[104:107], v[194:197], v[202:205], v[104:107]
	v_mfma_f32_16x16x32_bf16 v[96:99], v[186:189], v[210:213], v[96:99]
	v_mfma_f32_16x16x32_bf16 v[88:91], v[194:197], v[210:213], v[88:91]
	v_mfma_f32_16x16x32_bf16 v[84:87], v[186:189], v[218:221], v[84:87]
	v_mfma_f32_16x16x32_bf16 v[76:79], v[194:197], v[218:221], v[76:79]
	v_mfma_f32_16x16x32_bf16 v[68:71], v[186:189], v[226:229], v[68:71]
	v_mfma_f32_16x16x32_bf16 v[64:67], v[194:197], v[226:229], v[64:67]
	s_setprio 1
	s_barrier
	s_add_i32 s66, s54, s28
	v_lshl_add_u64 v[144:145], s[50:51], 0, v[130:131]
	s_mov_b32 m0, s66
	ds_read_b128 v[198:201], v159 offset:16384
	ds_read_b128 v[202:205], v159 offset:17408
	ds_read_b128 v[206:209], v159 offset:18432
	ds_read_b128 v[210:213], v159 offset:19456
	ds_read_b128 v[214:217], v159 offset:20480
	ds_read_b128 v[218:221], v159 offset:21504
	ds_read_b128 v[222:225], v159 offset:22528
	ds_read_b128 v[226:229], v159 offset:23552
	global_load_lds_dwordx4 v130, s[50:51]
	s_add_i32 m0, s66, 0x2000
	s_add_u32 s66, s50, 0x200000
	v_lshl_add_u64 v[160:161], s[50:51], 0, v[134:135]
	s_addc_u32 s67, s51, 0
	s_add_i32 s68, s55, s28
	global_load_lds_dwordx4 v134, s[50:51]
	s_mov_b32 m0, s68
	v_lshl_add_u64 v[232:233], s[52:53], 0, v[132:133]
	global_load_lds_dwordx4 v130, s[66:67]
	s_add_i32 m0, s68, 0x2000
	s_nop 0
	global_load_lds_dwordx4 v134, s[66:67]
	v_lshl_add_u64 v[230:231], s[52:53], 0, v[128:129]
	s_mov_b32 m0, s29
	s_nop 0
	global_load_lds_dwordx4 v128, s[52:53]
	s_mov_b32 m0, s30
	s_nop 0
	global_load_lds_dwordx4 v132, s[52:53]
	s_waitcnt vmcnt(8)
	s_waitcnt lgkmcnt(0)
	s_barrier
	s_setprio 0
	s_waitcnt lgkmcnt(0)
	v_mfma_f32_16x16x32_bf16 v[60:63], v[166:169], v[198:201], v[60:63]
	v_mfma_f32_16x16x32_bf16 v[56:59], v[174:177], v[198:201], v[56:59]
	v_mfma_f32_16x16x32_bf16 v[52:55], v[166:169], v[206:209], v[52:55]
	v_mfma_f32_16x16x32_bf16 v[44:47], v[174:177], v[206:209], v[44:47]
	v_mfma_f32_16x16x32_bf16 v[36:39], v[166:169], v[214:217], v[36:39]
	v_mfma_f32_16x16x32_bf16 v[28:31], v[174:177], v[214:217], v[28:31]
	v_mfma_f32_16x16x32_bf16 v[20:23], v[166:169], v[222:225], v[20:23]
	v_mfma_f32_16x16x32_bf16 v[12:15], v[174:177], v[222:225], v[12:15]
	v_mfma_f32_16x16x32_bf16 v[60:63], v[170:173], v[202:205], v[60:63]
	v_mfma_f32_16x16x32_bf16 v[56:59], v[178:181], v[202:205], v[56:59]
	v_mfma_f32_16x16x32_bf16 v[52:55], v[170:173], v[210:213], v[52:55]
	v_mfma_f32_16x16x32_bf16 v[44:47], v[178:181], v[210:213], v[44:47]
	v_mfma_f32_16x16x32_bf16 v[36:39], v[170:173], v[218:221], v[36:39]
	v_mfma_f32_16x16x32_bf16 v[28:31], v[178:181], v[218:221], v[28:31]
	v_mfma_f32_16x16x32_bf16 v[20:23], v[170:173], v[226:229], v[20:23]
	v_mfma_f32_16x16x32_bf16 v[12:15], v[178:181], v[226:229], v[12:15]
	v_mfma_f32_16x16x32_bf16 v[48:51], v[182:185], v[198:201], v[48:51]
	v_mfma_f32_16x16x32_bf16 v[40:43], v[190:193], v[198:201], v[40:43]
	v_mfma_f32_16x16x32_bf16 v[32:35], v[182:185], v[206:209], v[32:35]
	v_mfma_f32_16x16x32_bf16 v[24:27], v[190:193], v[206:209], v[24:27]
	v_mfma_f32_16x16x32_bf16 v[16:19], v[182:185], v[214:217], v[16:19]
	v_mfma_f32_16x16x32_bf16 v[8:11], v[190:193], v[214:217], v[8:11]
	v_mfma_f32_16x16x32_bf16 v[4:7], v[182:185], v[222:225], v[4:7]
	v_mfma_f32_16x16x32_bf16 v[0:3], v[190:193], v[222:225], v[0:3]
	v_mfma_f32_16x16x32_bf16 v[48:51], v[186:189], v[202:205], v[48:51]
	v_mfma_f32_16x16x32_bf16 v[40:43], v[194:197], v[202:205], v[40:43]
	v_mfma_f32_16x16x32_bf16 v[32:35], v[186:189], v[210:213], v[32:35]
	v_mfma_f32_16x16x32_bf16 v[24:27], v[194:197], v[210:213], v[24:27]
	v_mfma_f32_16x16x32_bf16 v[16:19], v[186:189], v[218:221], v[16:19]
	v_mfma_f32_16x16x32_bf16 v[8:11], v[194:197], v[218:221], v[8:11]
	v_mfma_f32_16x16x32_bf16 v[4:7], v[186:189], v[226:229], v[4:7]
	v_mfma_f32_16x16x32_bf16 v[0:3], v[194:197], v[226:229], v[0:3]
	s_setprio 1
	s_barrier
; #define PG8_STAGE(bufoff, gbase, voff) do { _Pragma("unroll") for (int _i = 0; _i < 2; ++_i) \
;         __builtin_amdgcn_global_load_lds((const unsigned*)((const char*)(gbase) + (voff)[_i]), (PG8_LAS unsigned*)(lds + (bufoff) + ldsw + _i * 8192), 16, 0, 0); } while (0)
; #define PG8_LDA(dst, b, h) do { _Pragma("unroll") for (int m = 0; m < 4; ++m) _Pragma("unroll") for (int k = 0; k < 2; ++k) dst[m][k] = *(const PG8_LAS bf16x8*)(lds + PG8_SA(b, h) + aoff + m * 2048 + k * 1024); } while (0)
; #define PG8_LDB(dst, b, h) do { _Pragma("unroll") for (int n = 0; n < 2; ++n) _Pragma("unroll") for (int k = 0; k < 2; ++k) dst[n][k] = *(const PG8_LAS bf16x8*)(lds + PG8_SB(b, h) + boff + n * 2048 + k * 1024); } while (0)
; #define PG8_MMA(ai, bj, At, Bt) do { __builtin_amdgcn_s_setprio(1); _Pragma("unroll") for (int m = 0; m < 4; ++m) _Pragma("unroll") for (int n = 0; n < 2; ++n) _Pragma("unroll") for (int k = 0; k < 2; ++k) \
;         acc[ai][bj][m][n] = __builtin_amdgcn_mfma_f32_16x16x32_bf16(Bt[n][k], At[m][k], acc[ai][bj][m][n], 0, 0, 0); __builtin_amdgcn_s_setprio(0); } while (0)
; #define PG8_WAIT_V(n) asm volatile("s_waitcnt vmcnt(" #n ")" ::: "memory")
; #define PG8_WAIT_L(n) asm volatile("s_waitcnt lgkmcnt(" #n ")" ::: "memory")
; #define PG8_BAR __builtin_amdgcn_s_barrier()
; #define PG8_SCHED __builtin_amdgcn_sched_barrier(0)
; template <class Epi, class Sched, bool ALIGN_EPI = false, bool SP2 = false>
; __device__ __forceinline__ void gemm_phase(PG8_LAS unsigned char* lds, const Gemm g, const Sched& S, const Epi& E) {
;     ...
;         for (int t = 0; t < nt; t += 2) {
;     ...
;             PG8_LDB(B0, 1, 0); PG8_LDB(B1, 1, 1); PG8_SCHED; PG8_LDA(At, 1, 0); PG8_STAGE(PG8_SA(0, 1), a2 + hstepA, voffA);
;             PG8_WAIT_V(8); PG8_WAIT_L(0); PG8_BAR; PG8_MMA(0, 0, At, B0); PG8_MMA(0, 1, At, B1); PG8_BAR; PG8_SCHED;
;             PG8_LDA(At, 1, 1); PG8_STAGE(PG8_SB(1, 0), b3, voffB); PG8_STAGE(PG8_SB(1, 1), b3 + hstepB, voffB); PG8_STAGE(PG8_SA(1, 0), a3, voffA);
;             PG8_WAIT_V(8); PG8_WAIT_L(0); PG8_BAR; PG8_MMA(1, 0, At, B0); PG8_MMA(1, 1, At, B1); PG8_BAR; PG8_SCHED;
	s_add_i32 s66, 0, 0x18000
	v_add_u32_e32 v163, s66, v155
	s_add_i32 s67, 0, 0x1c000
	ds_read_b128 v[166:169], v163
	ds_read_b128 v[170:173], v163 offset:1024
	ds_read_b128 v[174:177], v163 offset:2048
	ds_read_b128 v[178:181], v163 offset:3072
	v_add_u32_e32 v163, s67, v155
	ds_read_b128 v[182:185], v163
	ds_read_b128 v[186:189], v163 offset:1024
	ds_read_b128 v[190:193], v163 offset:2048
	ds_read_b128 v[194:197], v163 offset:3072
	s_add_u32 s52, s52, 0x200000
	s_addc_u32 s53, s53, 0
	s_mov_b32 m0, s31
	ds_read_b128 v[198:201], v159 offset:32768
	ds_read_b128 v[202:205], v159 offset:33792
	ds_read_b128 v[206:209], v159 offset:34816
	ds_read_b128 v[210:213], v159 offset:35840
	ds_read_b128 v[214:217], v159 offset:36864
	ds_read_b128 v[218:221], v159 offset:37888
	ds_read_b128 v[222:225], v159 offset:38912
	ds_read_b128 v[226:229], v159 offset:39936
	global_load_lds_dwordx4 v128, s[52:53]
	s_mov_b32 m0, s33
	s_nop 0
	global_load_lds_dwordx4 v132, s[52:53]
	s_waitcnt vmcnt(8)
	s_waitcnt lgkmcnt(0)
	s_barrier
	s_setprio 0
	s_waitcnt lgkmcnt(0)
	v_mfma_f32_16x16x32_bf16 v[124:127], v[166:169], v[198:201], v[124:127]
	v_mfma_f32_16x16x32_bf16 v[120:123], v[174:177], v[198:201], v[120:123]
	v_mfma_f32_16x16x32_bf16 v[116:119], v[166:169], v[206:209], v[116:119]
	v_mfma_f32_16x16x32_bf16 v[108:111], v[174:177], v[206:209], v[108:111]
	v_mfma_f32_16x16x32_bf16 v[100:103], v[166:169], v[214:217], v[100:103]
	v_mfma_f32_16x16x32_bf16 v[92:95], v[174:177], v[214:217], v[92:95]
	v_mfma_f32_16x16x32_bf16 v[80:83], v[166:169], v[222:225], v[80:83]
	v_mfma_f32_16x16x32_bf16 v[72:75], v[174:177], v[222:225], v[72:75]
	v_mfma_f32_16x16x32_bf16 v[124:127], v[170:173], v[202:205], v[124:127]
	v_mfma_f32_16x16x32_bf16 v[120:123], v[178:181], v[202:205], v[120:123]
	v_mfma_f32_16x16x32_bf16 v[116:119], v[170:173], v[210:213], v[116:119]
	v_mfma_f32_16x16x32_bf16 v[108:111], v[178:181], v[210:213], v[108:111]
	v_mfma_f32_16x16x32_bf16 v[100:103], v[170:173], v[218:221], v[100:103]
	v_mfma_f32_16x16x32_bf16 v[92:95], v[178:181], v[218:221], v[92:95]
	v_mfma_f32_16x16x32_bf16 v[80:83], v[170:173], v[226:229], v[80:83]
	v_mfma_f32_16x16x32_bf16 v[72:75], v[178:181], v[226:229], v[72:75]
	v_mfma_f32_16x16x32_bf16 v[112:115], v[182:185], v[198:201], v[112:115]
	v_mfma_f32_16x16x32_bf16 v[104:107], v[190:193], v[198:201], v[104:107]
	v_mfma_f32_16x16x32_bf16 v[96:99], v[182:185], v[206:209], v[96:99]
	v_mfma_f32_16x16x32_bf16 v[88:91], v[190:193], v[206:209], v[88:91]
	v_mfma_f32_16x16x32_bf16 v[84:87], v[182:185], v[214:217], v[84:87]
	v_mfma_f32_16x16x32_bf16 v[76:79], v[190:193], v[214:217], v[76:79]
	v_mfma_f32_16x16x32_bf16 v[68:71], v[182:185], v[222:225], v[68:71]
	v_mfma_f32_16x16x32_bf16 v[64:67], v[190:193], v[222:225], v[64:67]
	v_mfma_f32_16x16x32_bf16 v[112:115], v[186:189], v[202:205], v[112:115]
	v_mfma_f32_16x16x32_bf16 v[104:107], v[194:197], v[202:205], v[104:107]
	v_mfma_f32_16x16x32_bf16 v[96:99], v[186:189], v[210:213], v[96:99]
	v_mfma_f32_16x16x32_bf16 v[88:91], v[194:197], v[210:213], v[88:91]
	v_mfma_f32_16x16x32_bf16 v[84:87], v[186:189], v[218:221], v[84:87]
	v_mfma_f32_16x16x32_bf16 v[76:79], v[194:197], v[218:221], v[76:79]
	v_mfma_f32_16x16x32_bf16 v[68:71], v[186:189], v[226:229], v[68:71]
	v_mfma_f32_16x16x32_bf16 v[64:67], v[194:197], v[226:229], v[64:67]
	s_setprio 1
	s_barrier
	s_add_i32 s52, s66, s28
	v_lshl_add_u64 v[144:145], v[144:145], 0, s[10:11]
	s_mov_b32 m0, s52
	ds_read_b128 v[198:201], v159 offset:49152
	ds_read_b128 v[202:205], v159 offset:50176
	ds_read_b128 v[206:209], v159 offset:51200
	ds_read_b128 v[210:213], v159 offset:52224
	ds_read_b128 v[214:217], v159 offset:53248
	ds_read_b128 v[218:221], v159 offset:54272
	ds_read_b128 v[222:225], v159 offset:55296
	ds_read_b128 v[226:229], v159 offset:56320
	global_load_lds_dwordx4 v[144:145], off
	s_add_i32 m0, s52, 0x2000
	s_add_u32 s50, s50, 0x200080
	v_lshl_add_u64 v[144:145], v[160:161], 0, s[10:11]
	s_addc_u32 s51, s51, 0
	s_add_i32 s52, s67, s28
	global_load_lds_dwordx4 v[144:145], off
	s_mov_b32 m0, s52
	s_nop 0
	global_load_lds_dwordx4 v130, s[50:51]
	s_add_i32 m0, s52, 0x2000
	s_nop 0
	global_load_lds_dwordx4 v134, s[50:51]
	v_lshl_add_u64 v[144:145], v[230:231], 0, s[10:11]
	s_mov_b32 m0, s35
	s_nop 0
	global_load_lds_dwordx4 v[144:145], off
	v_lshl_add_u64 v[144:145], v[232:233], 0, s[10:11]
	s_mov_b32 m0, s47
	s_nop 0
	global_load_lds_dwordx4 v[144:145], off
	s_waitcnt vmcnt(8)
	s_waitcnt lgkmcnt(0)
	s_barrier
	s_setprio 0
	s_waitcnt lgkmcnt(0)
	v_mfma_f32_16x16x32_bf16 v[60:63], v[166:169], v[198:201], v[60:63]
	v_mfma_f32_16x16x32_bf16 v[56:59], v[174:177], v[198:201], v[56:59]
	v_mfma_f32_16x16x32_bf16 v[52:55], v[166:169], v[206:209], v[52:55]
	v_mfma_f32_16x16x32_bf16 v[44:47], v[174:177], v[206:209], v[44:47]
	v_mfma_f32_16x16x32_bf16 v[36:39], v[166:169], v[214:217], v[36:39]
	v_mfma_f32_16x16x32_bf16 v[28:31], v[174:177], v[214:217], v[28:31]
	v_mfma_f32_16x16x32_bf16 v[20:23], v[166:169], v[222:225], v[20:23]
	v_mfma_f32_16x16x32_bf16 v[12:15], v[174:177], v[222:225], v[12:15]
	v_mfma_f32_16x16x32_bf16 v[60:63], v[170:173], v[202:205], v[60:63]
	v_mfma_f32_16x16x32_bf16 v[56:59], v[178:181], v[202:205], v[56:59]
	v_mfma_f32_16x16x32_bf16 v[52:55], v[170:173], v[210:213], v[52:55]
	v_mfma_f32_16x16x32_bf16 v[44:47], v[178:181], v[210:213], v[44:47]
	v_mfma_f32_16x16x32_bf16 v[36:39], v[170:173], v[218:221], v[36:39]
	v_mfma_f32_16x16x32_bf16 v[28:31], v[178:181], v[218:221], v[28:31]
	v_mfma_f32_16x16x32_bf16 v[20:23], v[170:173], v[226:229], v[20:23]
	v_mfma_f32_16x16x32_bf16 v[12:15], v[178:181], v[226:229], v[12:15]
	v_mfma_f32_16x16x32_bf16 v[48:51], v[182:185], v[198:201], v[48:51]
	v_mfma_f32_16x16x32_bf16 v[40:43], v[190:193], v[198:201], v[40:43]
	v_mfma_f32_16x16x32_bf16 v[32:35], v[182:185], v[206:209], v[32:35]
	v_mfma_f32_16x16x32_bf16 v[24:27], v[190:193], v[206:209], v[24:27]
	v_mfma_f32_16x16x32_bf16 v[16:19], v[182:185], v[214:217], v[16:19]
	v_mfma_f32_16x16x32_bf16 v[8:11], v[190:193], v[214:217], v[8:11]
	v_mfma_f32_16x16x32_bf16 v[4:7], v[182:185], v[222:225], v[4:7]
	v_mfma_f32_16x16x32_bf16 v[0:3], v[190:193], v[222:225], v[0:3]
	v_mfma_f32_16x16x32_bf16 v[48:51], v[186:189], v[202:205], v[48:51]
	v_mfma_f32_16x16x32_bf16 v[40:43], v[194:197], v[202:205], v[40:43]
	v_mfma_f32_16x16x32_bf16 v[32:35], v[186:189], v[210:213], v[32:35]
	v_mfma_f32_16x16x32_bf16 v[24:27], v[194:197], v[210:213], v[24:27]
	v_mfma_f32_16x16x32_bf16 v[16:19], v[186:189], v[218:221], v[16:19]
	v_mfma_f32_16x16x32_bf16 v[8:11], v[194:197], v[218:221], v[8:11]
	v_mfma_f32_16x16x32_bf16 v[4:7], v[186:189], v[226:229], v[4:7]
	v_mfma_f32_16x16x32_bf16 v[0:3], v[194:197], v[226:229], v[0:3]
	s_add_i32 s65, s65, 2
	s_add_u32 s48, s48, 0x100
	s_addc_u32 s49, s49, 0
	s_add_u32 s63, s63, 0x100
	s_addc_u32 s64, s64, 0
	s_cmpk_gt_u32 s65, 0x7d
	s_setprio 1
	s_barrier
	s_cbranch_scc0 .LBB0_1161
	s_and_b64 vcc, exec, s[16:17]
	s_cbranch_vccz .LBB0_1164
	s_barrier

; #define PG8_STAGE(bufoff, gbase, voff) do { _Pragma("unroll") for (int _i = 0; _i < 2; ++_i) \
;         __builtin_amdgcn_global_load_lds((const unsigned*)((const char*)(gbase) + (voff)[_i]), (PG8_LAS unsigned*)(lds + (bufoff) + ldsw + _i * 8192), 16, 0, 0); } while (0)
; #define PG8_LDA(dst, b, h) do { _Pragma("unroll") for (int m = 0; m < 4; ++m) _Pragma("unroll") for (int k = 0; k < 2; ++k) dst[m][k] = *(const PG8_LAS bf16x8*)(lds + PG8_SA(b, h) + aoff + m * 2048 + k * 1024); } while (0)
; #define PG8_LDB(dst, b, h) do { _Pragma("unroll") for (int n = 0; n < 2; ++n) _Pragma("unroll") for (int k = 0; k < 2; ++k) dst[n][k] = *(const PG8_LAS bf16x8*)(lds + PG8_SB(b, h) + boff + n * 2048 + k * 1024); } while (0)
; #define PG8_MMA(ai, bj, At, Bt) do { __builtin_amdgcn_s_setprio(1); _Pragma("unroll") for (int m = 0; m < 4; ++m) _Pragma("unroll") for (int n = 0; n < 2; ++n) _Pragma("unroll") for (int k = 0; k < 2; ++k) \
;         acc[ai][bj][m][n] = __builtin_amdgcn_mfma_f32_16x16x32_bf16(Bt[n][k], At[m][k], acc[ai][bj][m][n], 0, 0, 0); __builtin_amdgcn_s_setprio(0); } while (0)
; #define PG8_WAIT_V(n) asm volatile("s_waitcnt vmcnt(" #n ")" ::: "memory")
; #define PG8_WAIT_L(n) asm volatile("s_waitcnt lgkmcnt(" #n ")" ::: "memory")
; template <class Epi, class Sched, bool ALIGN_EPI = false, bool SP2 = false>
; __device__ __forceinline__ void gemm_phase(PG8_LAS unsigned char* lds, const Gemm g, const Sched& S, const Epi& E) {
;     ...
;             const bool last = (t == nt - 2);
;             const char* a1 = cA + (size_t)(t + 1) * kstep;
;             const char* a2 = last ? nA : cA + (size_t)(t + 2) * kstep; const char* b2 = last ? nB : cB + (size_t)(t + 2) * kstep;
;             const char* a3 = a2 + kstep; const char* b3 = b2 + kstep;
;             if (last && has_next) S.a_ready(nxt);
;             if constexpr (SP2) {
;             PG8_LDB(B0, 0, 0); PG8_LDB(B1, 0, 1); PG8_SCHED; PG8_LDA(At, 0, 0); PG8_STAGE(PG8_SA(1, 1), a1 + hstepA, voffA);
;             PG8_WAIT_V(8); PG8_WAIT_L(0); PG8_BAR; PG8_MMA(0, 0, At, B0); PG8_MMA(0, 1, At, B1); PG8_BAR; PG8_SCHED;
;             PG8_LDA(At, 0, 1); PG8_STAGE(PG8_SB(0, 0), b2, voffB); PG8_STAGE(PG8_SB(0, 1), b2 + hstepB, voffB); PG8_STAGE(PG8_SA(0, 0), a2, voffA);
;             PG8_WAIT_V(8); PG8_WAIT_L(0); PG8_BAR; PG8_MMA(1, 0, At, B0); PG8_MMA(1, 1, At, B1); PG8_BAR; PG8_SCHED;
.LBB0_1181:
	ds_read_b128 v[150:153], v146
	ds_read_b128 v[154:157], v146 offset:1024
	ds_read_b128 v[158:161], v146 offset:2048
	ds_read_b128 v[166:169], v146 offset:3072
	ds_read_b128 v[170:173], v147
	ds_read_b128 v[174:177], v147 offset:1024
	ds_read_b128 v[178:181], v147 offset:2048
	ds_read_b128 v[182:185], v147 offset:3072
	s_add_u32 s43, s46, 0xffe00080
	s_addc_u32 s48, s47, -1
	s_cmp_eq_u32 s41, 12
	s_cselect_b32 s51, s1, s48
	s_cselect_b32 s50, s0, s43
	s_cselect_b32 s49, s45, s39
	s_cselect_b32 s48, s44, s19
	s_mov_b32 m0, s55
	ds_read_b128 v[186:189], v148
	ds_read_b128 v[190:193], v148 offset:1024
	ds_read_b128 v[194:197], v148 offset:2048
	ds_read_b128 v[198:201], v148 offset:3072
	ds_read_b128 v[202:205], v148 offset:4096
	ds_read_b128 v[206:209], v148 offset:5120
	ds_read_b128 v[210:213], v148 offset:6144
	ds_read_b128 v[214:217], v148 offset:7168
	global_load_lds_dwordx4 v136, s[46:47]
	s_mov_b32 m0, s56
	s_nop 0
	global_load_lds_dwordx4 v138, s[46:47]
	s_waitcnt vmcnt(8)
	s_waitcnt lgkmcnt(0)
	s_barrier
	s_setprio 0
	s_waitcnt lgkmcnt(0)
	v_mfma_f32_16x16x32_bf16 v[124:127], v[150:153], v[186:189], v[124:127]
	v_mfma_f32_16x16x32_bf16 v[120:123], v[158:161], v[186:189], v[120:123]
	v_mfma_f32_16x16x32_bf16 v[116:119], v[150:153], v[194:197], v[116:119]
	v_mfma_f32_16x16x32_bf16 v[112:115], v[158:161], v[194:197], v[112:115]
	v_mfma_f32_16x16x32_bf16 v[100:103], v[150:153], v[202:205], v[100:103]
	v_mfma_f32_16x16x32_bf16 v[96:99], v[158:161], v[202:205], v[96:99]
	v_mfma_f32_16x16x32_bf16 v[84:87], v[150:153], v[210:213], v[84:87]
	v_mfma_f32_16x16x32_bf16 v[80:83], v[158:161], v[210:213], v[80:83]
	v_mfma_f32_16x16x32_bf16 v[124:127], v[154:157], v[190:193], v[124:127]
	v_mfma_f32_16x16x32_bf16 v[120:123], v[166:169], v[190:193], v[120:123]
	v_mfma_f32_16x16x32_bf16 v[116:119], v[154:157], v[198:201], v[116:119]
	v_mfma_f32_16x16x32_bf16 v[112:115], v[166:169], v[198:201], v[112:115]
	v_mfma_f32_16x16x32_bf16 v[100:103], v[154:157], v[206:209], v[100:103]
	v_mfma_f32_16x16x32_bf16 v[96:99], v[166:169], v[206:209], v[96:99]
	v_mfma_f32_16x16x32_bf16 v[84:87], v[154:157], v[214:217], v[84:87]
	v_mfma_f32_16x16x32_bf16 v[80:83], v[166:169], v[214:217], v[80:83]
	v_mfma_f32_16x16x32_bf16 v[108:111], v[170:173], v[186:189], v[108:111]
	v_mfma_f32_16x16x32_bf16 v[104:107], v[178:181], v[186:189], v[104:107]
	v_mfma_f32_16x16x32_bf16 v[92:95], v[170:173], v[194:197], v[92:95]
	v_mfma_f32_16x16x32_bf16 v[88:91], v[178:181], v[194:197], v[88:91]
	v_mfma_f32_16x16x32_bf16 v[76:79], v[170:173], v[202:205], v[76:79]
	v_mfma_f32_16x16x32_bf16 v[72:75], v[178:181], v[202:205], v[72:75]
	v_mfma_f32_16x16x32_bf16 v[68:71], v[170:173], v[210:213], v[68:71]
	v_mfma_f32_16x16x32_bf16 v[64:67], v[178:181], v[210:213], v[64:67]
	v_mfma_f32_16x16x32_bf16 v[108:111], v[174:177], v[190:193], v[108:111]
	v_mfma_f32_16x16x32_bf16 v[104:107], v[182:185], v[190:193], v[104:107]
	v_mfma_f32_16x16x32_bf16 v[92:95], v[174:177], v[198:201], v[92:95]
	v_mfma_f32_16x16x32_bf16 v[88:91], v[182:185], v[198:201], v[88:91]
	v_mfma_f32_16x16x32_bf16 v[76:79], v[174:177], v[206:209], v[76:79]
	v_mfma_f32_16x16x32_bf16 v[72:75], v[182:185], v[206:209], v[72:75]
	v_mfma_f32_16x16x32_bf16 v[68:71], v[174:177], v[214:217], v[68:71]
	v_mfma_f32_16x16x32_bf16 v[64:67], v[182:185], v[214:217], v[64:67]
	s_setprio 1
	s_barrier
	s_add_i32 s43, s53, s30
	v_lshl_add_u64 v[218:219], s[48:49], 0, v[130:131]
	s_mov_b32 m0, s43
	ds_read_b128 v[186:189], v148 offset:16384
	ds_read_b128 v[190:193], v148 offset:17408
	ds_read_b128 v[194:197], v148 offset:18432
	ds_read_b128 v[198:201], v148 offset:19456
	ds_read_b128 v[202:205], v148 offset:20480
	ds_read_b128 v[206:209], v148 offset:21504
	ds_read_b128 v[210:213], v148 offset:22528
	ds_read_b128 v[214:217], v148 offset:23552
	global_load_lds_dwordx4 v130, s[48:49]
	s_add_i32 m0, s43, 0x2000
	s_add_u32 s58, s48, 0x200000
	v_lshl_add_u64 v[220:221], s[48:49], 0, v[134:135]
	s_addc_u32 s59, s49, 0
	s_add_i32 s43, s54, s30
	global_load_lds_dwordx4 v134, s[48:49]
	s_mov_b32 m0, s43
	v_lshl_add_u64 v[224:225], s[50:51], 0, v[132:133]
	global_load_lds_dwordx4 v130, s[58:59]
	s_add_i32 m0, s43, 0x2000
	s_nop 0
	global_load_lds_dwordx4 v134, s[58:59]
	v_lshl_add_u64 v[222:223], s[50:51], 0, v[128:129]
	s_mov_b32 m0, s21
	s_nop 0
	global_load_lds_dwordx4 v128, s[50:51]
	s_mov_b32 m0, s23
	s_nop 0
	global_load_lds_dwordx4 v132, s[50:51]
	s_waitcnt vmcnt(8)
	s_waitcnt lgkmcnt(0)
	s_barrier
	s_setprio 0
	s_waitcnt lgkmcnt(0)
	v_mfma_f32_16x16x32_bf16 v[60:63], v[150:153], v[186:189], v[60:63]
	v_mfma_f32_16x16x32_bf16 v[56:59], v[158:161], v[186:189], v[56:59]
	v_mfma_f32_16x16x32_bf16 v[52:55], v[150:153], v[194:197], v[52:55]
	v_mfma_f32_16x16x32_bf16 v[48:51], v[158:161], v[194:197], v[48:51]
	v_mfma_f32_16x16x32_bf16 v[36:39], v[150:153], v[202:205], v[36:39]
	v_mfma_f32_16x16x32_bf16 v[32:35], v[158:161], v[202:205], v[32:35]
	v_mfma_f32_16x16x32_bf16 v[20:23], v[150:153], v[210:213], v[20:23]
	v_mfma_f32_16x16x32_bf16 v[16:19], v[158:161], v[210:213], v[16:19]
	v_mfma_f32_16x16x32_bf16 v[60:63], v[154:157], v[190:193], v[60:63]
	v_mfma_f32_16x16x32_bf16 v[56:59], v[166:169], v[190:193], v[56:59]
	v_mfma_f32_16x16x32_bf16 v[52:55], v[154:157], v[198:201], v[52:55]
	v_mfma_f32_16x16x32_bf16 v[48:51], v[166:169], v[198:201], v[48:51]
	v_mfma_f32_16x16x32_bf16 v[36:39], v[154:157], v[206:209], v[36:39]
	v_mfma_f32_16x16x32_bf16 v[32:35], v[166:169], v[206:209], v[32:35]
	v_mfma_f32_16x16x32_bf16 v[20:23], v[154:157], v[214:217], v[20:23]
	v_mfma_f32_16x16x32_bf16 v[16:19], v[166:169], v[214:217], v[16:19]
	v_mfma_f32_16x16x32_bf16 v[44:47], v[170:173], v[186:189], v[44:47]
	v_mfma_f32_16x16x32_bf16 v[40:43], v[178:181], v[186:189], v[40:43]
	v_mfma_f32_16x16x32_bf16 v[28:31], v[170:173], v[194:197], v[28:31]
	v_mfma_f32_16x16x32_bf16 v[24:27], v[178:181], v[194:197], v[24:27]
	v_mfma_f32_16x16x32_bf16 v[12:15], v[170:173], v[202:205], v[12:15]
	v_mfma_f32_16x16x32_bf16 v[8:11], v[178:181], v[202:205], v[8:11]
	v_mfma_f32_16x16x32_bf16 v[4:7], v[170:173], v[210:213], v[4:7]
	v_mfma_f32_16x16x32_bf16 v[0:3], v[178:181], v[210:213], v[0:3]
	v_mfma_f32_16x16x32_bf16 v[44:47], v[174:177], v[190:193], v[44:47]
	v_mfma_f32_16x16x32_bf16 v[40:43], v[182:185], v[190:193], v[40:43]
	v_mfma_f32_16x16x32_bf16 v[28:31], v[174:177], v[198:201], v[28:31]
	v_mfma_f32_16x16x32_bf16 v[24:27], v[182:185], v[198:201], v[24:27]
	v_mfma_f32_16x16x32_bf16 v[12:15], v[174:177], v[206:209], v[12:15]
	v_mfma_f32_16x16x32_bf16 v[8:11], v[182:185], v[206:209], v[8:11]
	v_mfma_f32_16x16x32_bf16 v[4:7], v[174:177], v[214:217], v[4:7]
	v_mfma_f32_16x16x32_bf16 v[0:3], v[182:185], v[214:217], v[0:3]
	s_setprio 1
	s_barrier
; #define PG8_STAGE(bufoff, gbase, voff) do { _Pragma("unroll") for (int _i = 0; _i < 2; ++_i) \
;         __builtin_amdgcn_global_load_lds((const unsigned*)((const char*)(gbase) + (voff)[_i]), (PG8_LAS unsigned*)(lds + (bufoff) + ldsw + _i * 8192), 16, 0, 0); } while (0)
; #define PG8_LDA(dst, b, h) do { _Pragma("unroll") for (int m = 0; m < 4; ++m) _Pragma("unroll") for (int k = 0; k < 2; ++k) dst[m][k] = *(const PG8_LAS bf16x8*)(lds + PG8_SA(b, h) + aoff + m * 2048 + k * 1024); } while (0)
; #define PG8_LDB(dst, b, h) do { _Pragma("unroll") for (int n = 0; n < 2; ++n) _Pragma("unroll") for (int k = 0; k < 2; ++k) dst[n][k] = *(const PG8_LAS bf16x8*)(lds + PG8_SB(b, h) + boff + n * 2048 + k * 1024); } while (0)
; #define PG8_MMA(ai, bj, At, Bt) do { __builtin_amdgcn_s_setprio(1); _Pragma("unroll") for (int m = 0; m < 4; ++m) _Pragma("unroll") for (int n = 0; n < 2; ++n) _Pragma("unroll") for (int k = 0; k < 2; ++k) \
;         acc[ai][bj][m][n] = __builtin_amdgcn_mfma_f32_16x16x32_bf16(Bt[n][k], At[m][k], acc[ai][bj][m][n], 0, 0, 0); __builtin_amdgcn_s_setprio(0); } while (0)
; #define PG8_WAIT_V(n) asm volatile("s_waitcnt vmcnt(" #n ")" ::: "memory")
; #define PG8_WAIT_L(n) asm volatile("s_waitcnt lgkmcnt(" #n ")" ::: "memory")
; #define PG8_BAR __builtin_amdgcn_s_barrier()
; #define PG8_SCHED __builtin_amdgcn_sched_barrier(0)
; template <class Epi, class Sched, bool ALIGN_EPI = false, bool SP2 = false>
; __device__ __forceinline__ void gemm_phase(PG8_LAS unsigned char* lds, const Gemm g, const Sched& S, const Epi& E) {
;     ...
;         for (int t = 0; t < nt; t += 2) {
;     ...
;             PG8_LDB(B0, 1, 0); PG8_LDB(B1, 1, 1); PG8_SCHED; PG8_LDA(At, 1, 0); PG8_STAGE(PG8_SA(0, 1), a2 + hstepA, voffA);
;             PG8_WAIT_V(8); PG8_WAIT_L(0); PG8_BAR; PG8_MMA(0, 0, At, B0); PG8_MMA(0, 1, At, B1); PG8_BAR; PG8_SCHED;
;             PG8_LDA(At, 1, 1); PG8_STAGE(PG8_SB(1, 0), b3, voffB); PG8_STAGE(PG8_SB(1, 1), b3 + hstepB, voffB); PG8_STAGE(PG8_SA(1, 0), a3, voffA);
;             PG8_WAIT_V(8); PG8_WAIT_L(0); PG8_BAR; PG8_MMA(1, 0, At, B0); PG8_MMA(1, 1, At, B1); PG8_BAR; PG8_SCHED;
	s_add_i32 s43, 0, 0x18000
	v_add_u32_e32 v163, s43, v145
	s_add_i32 s57, 0, 0x1c000
	ds_read_b128 v[150:153], v163
	ds_read_b128 v[154:157], v163 offset:1024
	ds_read_b128 v[158:161], v163 offset:2048
	ds_read_b128 v[166:169], v163 offset:3072
	v_add_u32_e32 v163, s57, v145
	ds_read_b128 v[170:173], v163
	ds_read_b128 v[174:177], v163 offset:1024
	ds_read_b128 v[178:181], v163 offset:2048
	ds_read_b128 v[182:185], v163 offset:3072
	s_add_u32 s50, s50, 0x200000
	s_addc_u32 s51, s51, 0
	s_mov_b32 m0, s31
	ds_read_b128 v[186:189], v148 offset:32768
	ds_read_b128 v[190:193], v148 offset:33792
	ds_read_b128 v[194:197], v148 offset:34816
	ds_read_b128 v[198:201], v148 offset:35840
	ds_read_b128 v[202:205], v148 offset:36864
	ds_read_b128 v[206:209], v148 offset:37888
	ds_read_b128 v[210:213], v148 offset:38912
	ds_read_b128 v[214:217], v148 offset:39936
	global_load_lds_dwordx4 v128, s[50:51]
	s_mov_b32 m0, s33
	s_nop 0
	global_load_lds_dwordx4 v132, s[50:51]
	s_waitcnt vmcnt(8)
	s_waitcnt lgkmcnt(0)
	s_barrier
	s_setprio 0
	s_waitcnt lgkmcnt(0)
	v_mfma_f32_16x16x32_bf16 v[124:127], v[150:153], v[186:189], v[124:127]
	v_mfma_f32_16x16x32_bf16 v[120:123], v[158:161], v[186:189], v[120:123]
	v_mfma_f32_16x16x32_bf16 v[116:119], v[150:153], v[194:197], v[116:119]
	v_mfma_f32_16x16x32_bf16 v[112:115], v[158:161], v[194:197], v[112:115]
	v_mfma_f32_16x16x32_bf16 v[100:103], v[150:153], v[202:205], v[100:103]
	v_mfma_f32_16x16x32_bf16 v[96:99], v[158:161], v[202:205], v[96:99]
	v_mfma_f32_16x16x32_bf16 v[84:87], v[150:153], v[210:213], v[84:87]
	v_mfma_f32_16x16x32_bf16 v[80:83], v[158:161], v[210:213], v[80:83]
	v_mfma_f32_16x16x32_bf16 v[124:127], v[154:157], v[190:193], v[124:127]
	v_mfma_f32_16x16x32_bf16 v[120:123], v[166:169], v[190:193], v[120:123]
	v_mfma_f32_16x16x32_bf16 v[116:119], v[154:157], v[198:201], v[116:119]
	v_mfma_f32_16x16x32_bf16 v[112:115], v[166:169], v[198:201], v[112:115]
	v_mfma_f32_16x16x32_bf16 v[100:103], v[154:157], v[206:209], v[100:103]
	v_mfma_f32_16x16x32_bf16 v[96:99], v[166:169], v[206:209], v[96:99]
	v_mfma_f32_16x16x32_bf16 v[84:87], v[154:157], v[214:217], v[84:87]
	v_mfma_f32_16x16x32_bf16 v[80:83], v[166:169], v[214:217], v[80:83]
	v_mfma_f32_16x16x32_bf16 v[108:111], v[170:173], v[186:189], v[108:111]
	v_mfma_f32_16x16x32_bf16 v[104:107], v[178:181], v[186:189], v[104:107]
	v_mfma_f32_16x16x32_bf16 v[92:95], v[170:173], v[194:197], v[92:95]
	v_mfma_f32_16x16x32_bf16 v[88:91], v[178:181], v[194:197], v[88:91]
	v_mfma_f32_16x16x32_bf16 v[76:79], v[170:173], v[202:205], v[76:79]
	v_mfma_f32_16x16x32_bf16 v[72:75], v[178:181], v[202:205], v[72:75]
	v_mfma_f32_16x16x32_bf16 v[68:71], v[170:173], v[210:213], v[68:71]
	v_mfma_f32_16x16x32_bf16 v[64:67], v[178:181], v[210:213], v[64:67]
	v_mfma_f32_16x16x32_bf16 v[108:111], v[174:177], v[190:193], v[108:111]
	v_mfma_f32_16x16x32_bf16 v[104:107], v[182:185], v[190:193], v[104:107]
	v_mfma_f32_16x16x32_bf16 v[92:95], v[174:177], v[198:201], v[92:95]
	v_mfma_f32_16x16x32_bf16 v[88:91], v[182:185], v[198:201], v[88:91]
	v_mfma_f32_16x16x32_bf16 v[76:79], v[174:177], v[206:209], v[76:79]
	v_mfma_f32_16x16x32_bf16 v[72:75], v[182:185], v[206:209], v[72:75]
	v_mfma_f32_16x16x32_bf16 v[68:71], v[174:177], v[214:217], v[68:71]
	v_mfma_f32_16x16x32_bf16 v[64:67], v[182:185], v[214:217], v[64:67]
	s_setprio 1
	s_barrier
	s_add_i32 s43, s43, s30
	v_lshl_add_u64 v[218:219], v[218:219], 0, s[16:17]
	s_mov_b32 m0, s43
	ds_read_b128 v[186:189], v148 offset:49152
	ds_read_b128 v[190:193], v148 offset:50176
	ds_read_b128 v[194:197], v148 offset:51200
	ds_read_b128 v[198:201], v148 offset:52224
	ds_read_b128 v[202:205], v148 offset:53248
	ds_read_b128 v[206:209], v148 offset:54272
	ds_read_b128 v[210:213], v148 offset:55296
	ds_read_b128 v[214:217], v148 offset:56320
	global_load_lds_dwordx4 v[218:219], off
	s_add_i32 m0, s43, 0x2000
	s_add_u32 s48, s48, 0x200080
	v_lshl_add_u64 v[218:219], v[220:221], 0, s[16:17]
	s_addc_u32 s49, s49, 0
	s_add_i32 s43, s57, s30
	global_load_lds_dwordx4 v[218:219], off
	s_mov_b32 m0, s43
	s_nop 0
	global_load_lds_dwordx4 v130, s[48:49]
	s_add_i32 m0, s43, 0x2000
	s_nop 0
	global_load_lds_dwordx4 v134, s[48:49]
	v_lshl_add_u64 v[218:219], v[222:223], 0, s[16:17]
	s_mov_b32 m0, s35
	s_nop 0
	global_load_lds_dwordx4 v[218:219], off
	v_lshl_add_u64 v[218:219], v[224:225], 0, s[16:17]
	s_mov_b32 m0, s52
	s_nop 0
	global_load_lds_dwordx4 v[218:219], off
	s_waitcnt vmcnt(8)
	s_waitcnt lgkmcnt(0)
	s_barrier
	s_setprio 0
	s_waitcnt lgkmcnt(0)
	v_mfma_f32_16x16x32_bf16 v[60:63], v[150:153], v[186:189], v[60:63]
	v_mfma_f32_16x16x32_bf16 v[56:59], v[158:161], v[186:189], v[56:59]
	v_mfma_f32_16x16x32_bf16 v[52:55], v[150:153], v[194:197], v[52:55]
	v_mfma_f32_16x16x32_bf16 v[48:51], v[158:161], v[194:197], v[48:51]
	v_mfma_f32_16x16x32_bf16 v[36:39], v[150:153], v[202:205], v[36:39]
	v_mfma_f32_16x16x32_bf16 v[32:35], v[158:161], v[202:205], v[32:35]
	v_mfma_f32_16x16x32_bf16 v[20:23], v[150:153], v[210:213], v[20:23]
	v_mfma_f32_16x16x32_bf16 v[16:19], v[158:161], v[210:213], v[16:19]
	v_mfma_f32_16x16x32_bf16 v[60:63], v[154:157], v[190:193], v[60:63]
	v_mfma_f32_16x16x32_bf16 v[56:59], v[166:169], v[190:193], v[56:59]
	v_mfma_f32_16x16x32_bf16 v[52:55], v[154:157], v[198:201], v[52:55]
	v_mfma_f32_16x16x32_bf16 v[48:51], v[166:169], v[198:201], v[48:51]
	v_mfma_f32_16x16x32_bf16 v[36:39], v[154:157], v[206:209], v[36:39]
	v_mfma_f32_16x16x32_bf16 v[32:35], v[166:169], v[206:209], v[32:35]
	v_mfma_f32_16x16x32_bf16 v[20:23], v[154:157], v[214:217], v[20:23]
	v_mfma_f32_16x16x32_bf16 v[16:19], v[166:169], v[214:217], v[16:19]
	v_mfma_f32_16x16x32_bf16 v[44:47], v[170:173], v[186:189], v[44:47]
	v_mfma_f32_16x16x32_bf16 v[40:43], v[178:181], v[186:189], v[40:43]
	v_mfma_f32_16x16x32_bf16 v[28:31], v[170:173], v[194:197], v[28:31]
	v_mfma_f32_16x16x32_bf16 v[24:27], v[178:181], v[194:197], v[24:27]
	v_mfma_f32_16x16x32_bf16 v[12:15], v[170:173], v[202:205], v[12:15]
	v_mfma_f32_16x16x32_bf16 v[8:11], v[178:181], v[202:205], v[8:11]
	v_mfma_f32_16x16x32_bf16 v[4:7], v[170:173], v[210:213], v[4:7]
	v_mfma_f32_16x16x32_bf16 v[0:3], v[178:181], v[210:213], v[0:3]
	v_mfma_f32_16x16x32_bf16 v[44:47], v[174:177], v[190:193], v[44:47]
	v_mfma_f32_16x16x32_bf16 v[40:43], v[182:185], v[190:193], v[40:43]
	v_mfma_f32_16x16x32_bf16 v[28:31], v[174:177], v[198:201], v[28:31]
	v_mfma_f32_16x16x32_bf16 v[24:27], v[182:185], v[198:201], v[24:27]
	v_mfma_f32_16x16x32_bf16 v[12:15], v[174:177], v[206:209], v[12:15]
	v_mfma_f32_16x16x32_bf16 v[8:11], v[182:185], v[206:209], v[8:11]
	v_mfma_f32_16x16x32_bf16 v[4:7], v[174:177], v[214:217], v[4:7]
	v_mfma_f32_16x16x32_bf16 v[0:3], v[182:185], v[214:217], v[0:3]
	s_add_i32 s41, s41, 2
	s_add_u32 s46, s46, 0x100
	s_addc_u32 s47, s47, 0
	s_add_u32 s19, s19, 0x100
	s_addc_u32 s39, s39, 0
	s_cmp_gt_u32 s41, 13
	s_setprio 1
	s_barrier
	s_cbranch_scc0 .LBB0_1181
	s_and_b64 vcc, exec, s[36:37]
	s_cbranch_vccz .LBB0_1184
	s_barrier

; #define PG8_STAGE(bufoff, gbase, voff) do { _Pragma("unroll") for (int _i = 0; _i < 2; ++_i) \
;         __builtin_amdgcn_global_load_lds((const unsigned*)((const char*)(gbase) + (voff)[_i]), (PG8_LAS unsigned*)(lds + (bufoff) + ldsw + _i * 8192), 16, 0, 0); } while (0)
; #define PG8_LDA(dst, b, h) do { _Pragma("unroll") for (int m = 0; m < 4; ++m) _Pragma("unroll") for (int k = 0; k < 2; ++k) dst[m][k] = *(const PG8_LAS bf16x8*)(lds + PG8_SA(b, h) + aoff + m * 2048 + k * 1024); } while (0)
; #define PG8_LDB(dst, b, h) do { _Pragma("unroll") for (int n = 0; n < 2; ++n) _Pragma("unroll") for (int k = 0; k < 2; ++k) dst[n][k] = *(const PG8_LAS bf16x8*)(lds + PG8_SB(b, h) + boff + n * 2048 + k * 1024); } while (0)
; #define PG8_MMA(ai, bj, At, Bt) do { __builtin_amdgcn_s_setprio(1); _Pragma("unroll") for (int m = 0; m < 4; ++m) _Pragma("unroll") for (int n = 0; n < 2; ++n) _Pragma("unroll") for (int k = 0; k < 2; ++k) \
;         acc[ai][bj][m][n] = __builtin_amdgcn_mfma_f32_16x16x32_bf16(Bt[n][k], At[m][k], acc[ai][bj][m][n], 0, 0, 0); __builtin_amdgcn_s_setprio(0); } while (0)
; #define PG8_WAIT_V(n) asm volatile("s_waitcnt vmcnt(" #n ")" ::: "memory")
; #define PG8_WAIT_L(n) asm volatile("s_waitcnt lgkmcnt(" #n ")" ::: "memory")
; #define PG8_BAR __builtin_amdgcn_s_barrier()
; #define PG8_SCHED __builtin_amdgcn_sched_barrier(0)
; template <class Epi, class Sched, bool ALIGN_EPI = false, bool SP2 = false>
; __device__ __forceinline__ void gemm_phase(PG8_LAS unsigned char* lds, const Gemm g, const Sched& S, const Epi& E) {
;     ...
;             PG8_LDB(B0, 0, 0); PG8_LDB(B1, 0, 1); PG8_SCHED; PG8_LDA(At, 0, 0); PG8_STAGE(PG8_SA(1, 1), a1 + hstepA, voffA);
;             PG8_WAIT_V(8); PG8_WAIT_L(0); PG8_BAR; PG8_MMA(0, 0, At, B0); PG8_MMA(0, 1, At, B1); PG8_BAR; PG8_SCHED;
;             PG8_LDA(At, 0, 1); PG8_STAGE(PG8_SB(0, 0), b2, voffB); PG8_STAGE(PG8_SB(0, 1), b2 + hstepB, voffB); PG8_STAGE(PG8_SA(0, 0), a2, voffA);
;             PG8_WAIT_V(8); PG8_WAIT_L(0); PG8_BAR; PG8_MMA(1, 0, At, B0); PG8_MMA(1, 1, At, B1); PG8_BAR; PG8_SCHED;
.LBB0_1333:
	ds_read_b128 v[144:147], v153
	ds_read_b128 v[156:159], v153 offset:1024
	ds_read_b128 v[166:169], v153 offset:2048
	ds_read_b128 v[170:173], v153 offset:3072
	ds_read_b128 v[174:177], v154
	ds_read_b128 v[178:181], v154 offset:1024
	ds_read_b128 v[182:185], v154 offset:2048
	ds_read_b128 v[186:189], v154 offset:3072
	s_add_u32 s46, s44, 0xfff80080
	s_addc_u32 s47, s45, -1
	s_cmp_eq_u32 s62, 28
	s_cselect_b32 s49, s37, s47
	s_cselect_b32 s48, s58, s46
	s_cselect_b32 s47, s23, s61
	s_cselect_b32 s46, s59, s60
	s_add_i32 m0, s30, 0xc000
	ds_read_b128 v[190:193], v155
	ds_read_b128 v[194:197], v155 offset:1024
	ds_read_b128 v[198:201], v155 offset:2048
	ds_read_b128 v[202:205], v155 offset:3072
	ds_read_b128 v[206:209], v155 offset:4096
	ds_read_b128 v[210:213], v155 offset:5120
	ds_read_b128 v[214:217], v155 offset:6144
	ds_read_b128 v[218:221], v155 offset:7168
	global_load_lds_dwordx4 v136, s[44:45]
	s_add_i32 m0, s30, 0xe000
	s_nop 0
	global_load_lds_dwordx4 v138, s[44:45]
	s_waitcnt vmcnt(8)
	s_waitcnt lgkmcnt(0)
	s_barrier
	s_setprio 0
	s_waitcnt lgkmcnt(0)
	v_mfma_f32_16x16x32_bf16 v[124:127], v[144:147], v[190:193], v[124:127]
	v_mfma_f32_16x16x32_bf16 v[120:123], v[166:169], v[190:193], v[120:123]
	v_mfma_f32_16x16x32_bf16 v[108:111], v[144:147], v[198:201], v[108:111]
	v_mfma_f32_16x16x32_bf16 v[104:107], v[166:169], v[198:201], v[104:107]
	v_mfma_f32_16x16x32_bf16 v[92:95], v[144:147], v[206:209], v[92:95]
	v_mfma_f32_16x16x32_bf16 v[88:91], v[166:169], v[206:209], v[88:91]
	v_mfma_f32_16x16x32_bf16 v[76:79], v[144:147], v[214:217], v[76:79]
	v_mfma_f32_16x16x32_bf16 v[72:75], v[166:169], v[214:217], v[72:75]
	v_mfma_f32_16x16x32_bf16 v[124:127], v[156:159], v[194:197], v[124:127]
	v_mfma_f32_16x16x32_bf16 v[120:123], v[170:173], v[194:197], v[120:123]
	v_mfma_f32_16x16x32_bf16 v[108:111], v[156:159], v[202:205], v[108:111]
	v_mfma_f32_16x16x32_bf16 v[104:107], v[170:173], v[202:205], v[104:107]
	v_mfma_f32_16x16x32_bf16 v[92:95], v[156:159], v[210:213], v[92:95]
	v_mfma_f32_16x16x32_bf16 v[88:91], v[170:173], v[210:213], v[88:91]
	v_mfma_f32_16x16x32_bf16 v[76:79], v[156:159], v[218:221], v[76:79]
	v_mfma_f32_16x16x32_bf16 v[72:75], v[170:173], v[218:221], v[72:75]
	v_mfma_f32_16x16x32_bf16 v[116:119], v[174:177], v[190:193], v[116:119]
	v_mfma_f32_16x16x32_bf16 v[112:115], v[182:185], v[190:193], v[112:115]
	v_mfma_f32_16x16x32_bf16 v[100:103], v[174:177], v[198:201], v[100:103]
	v_mfma_f32_16x16x32_bf16 v[96:99], v[182:185], v[198:201], v[96:99]
	v_mfma_f32_16x16x32_bf16 v[84:87], v[174:177], v[206:209], v[84:87]
	v_mfma_f32_16x16x32_bf16 v[80:83], v[182:185], v[206:209], v[80:83]
	v_mfma_f32_16x16x32_bf16 v[68:71], v[174:177], v[214:217], v[68:71]
	v_mfma_f32_16x16x32_bf16 v[64:67], v[182:185], v[214:217], v[64:67]
	v_mfma_f32_16x16x32_bf16 v[116:119], v[178:181], v[194:197], v[116:119]
	v_mfma_f32_16x16x32_bf16 v[112:115], v[186:189], v[194:197], v[112:115]
	v_mfma_f32_16x16x32_bf16 v[100:103], v[178:181], v[202:205], v[100:103]
	v_mfma_f32_16x16x32_bf16 v[96:99], v[186:189], v[202:205], v[96:99]
	v_mfma_f32_16x16x32_bf16 v[84:87], v[178:181], v[210:213], v[84:87]
	v_mfma_f32_16x16x32_bf16 v[80:83], v[186:189], v[210:213], v[80:83]
	v_mfma_f32_16x16x32_bf16 v[68:71], v[178:181], v[218:221], v[68:71]
	v_mfma_f32_16x16x32_bf16 v[64:67], v[186:189], v[218:221], v[64:67]
	s_setprio 1
	s_barrier
	s_add_i32 s63, s51, s28
	v_lshl_add_u64 v[148:149], s[46:47], 0, v[132:133]
	s_mov_b32 m0, s63
	ds_read_b128 v[190:193], v155 offset:16384
	ds_read_b128 v[194:197], v155 offset:17408
	ds_read_b128 v[198:201], v155 offset:18432
	ds_read_b128 v[202:205], v155 offset:19456
	ds_read_b128 v[206:209], v155 offset:20480
	ds_read_b128 v[210:213], v155 offset:21504
	ds_read_b128 v[214:217], v155 offset:22528
	ds_read_b128 v[218:221], v155 offset:23552
	global_load_lds_dwordx4 v132, s[46:47]
	s_add_i32 m0, s63, 0x2000
	s_add_u32 s64, s46, 0x80000
	v_lshl_add_u64 v[160:161], s[46:47], 0, v[128:129]
	s_addc_u32 s65, s47, 0
	s_add_i32 s63, s52, s28
	global_load_lds_dwordx4 v128, s[46:47]
	s_mov_b32 m0, s63
	v_lshl_add_u64 v[224:225], s[48:49], 0, v[130:131]
	global_load_lds_dwordx4 v132, s[64:65]
	s_add_i32 m0, s63, 0x2000
	s_nop 0
	global_load_lds_dwordx4 v128, s[64:65]
	v_lshl_add_u64 v[222:223], s[48:49], 0, v[134:135]
	s_mov_b32 m0, s30
	s_nop 0
	global_load_lds_dwordx4 v134, s[48:49]
	s_mov_b32 m0, s31
	s_nop 0
	global_load_lds_dwordx4 v130, s[48:49]
	s_waitcnt vmcnt(8)
	s_waitcnt lgkmcnt(0)
	s_barrier
	s_setprio 0
	s_waitcnt lgkmcnt(0)
	v_mfma_f32_16x16x32_bf16 v[60:63], v[144:147], v[190:193], v[60:63]
	v_mfma_f32_16x16x32_bf16 v[56:59], v[166:169], v[190:193], v[56:59]
	v_mfma_f32_16x16x32_bf16 v[44:47], v[144:147], v[198:201], v[44:47]
	v_mfma_f32_16x16x32_bf16 v[40:43], v[166:169], v[198:201], v[40:43]
	v_mfma_f32_16x16x32_bf16 v[28:31], v[144:147], v[206:209], v[28:31]
	v_mfma_f32_16x16x32_bf16 v[24:27], v[166:169], v[206:209], v[24:27]
	v_mfma_f32_16x16x32_bf16 v[12:15], v[144:147], v[214:217], v[12:15]
	v_mfma_f32_16x16x32_bf16 v[8:11], v[166:169], v[214:217], v[8:11]
	v_mfma_f32_16x16x32_bf16 v[60:63], v[156:159], v[194:197], v[60:63]
	v_mfma_f32_16x16x32_bf16 v[56:59], v[170:173], v[194:197], v[56:59]
	v_mfma_f32_16x16x32_bf16 v[44:47], v[156:159], v[202:205], v[44:47]
	v_mfma_f32_16x16x32_bf16 v[40:43], v[170:173], v[202:205], v[40:43]
	v_mfma_f32_16x16x32_bf16 v[28:31], v[156:159], v[210:213], v[28:31]
	v_mfma_f32_16x16x32_bf16 v[24:27], v[170:173], v[210:213], v[24:27]
	v_mfma_f32_16x16x32_bf16 v[12:15], v[156:159], v[218:221], v[12:15]
	v_mfma_f32_16x16x32_bf16 v[8:11], v[170:173], v[218:221], v[8:11]
	v_mfma_f32_16x16x32_bf16 v[52:55], v[174:177], v[190:193], v[52:55]
	v_mfma_f32_16x16x32_bf16 v[48:51], v[182:185], v[190:193], v[48:51]
	v_mfma_f32_16x16x32_bf16 v[36:39], v[174:177], v[198:201], v[36:39]
	v_mfma_f32_16x16x32_bf16 v[32:35], v[182:185], v[198:201], v[32:35]
	v_mfma_f32_16x16x32_bf16 v[20:23], v[174:177], v[206:209], v[20:23]
	v_mfma_f32_16x16x32_bf16 v[16:19], v[182:185], v[206:209], v[16:19]
	v_mfma_f32_16x16x32_bf16 v[4:7], v[174:177], v[214:217], v[4:7]
	v_mfma_f32_16x16x32_bf16 v[0:3], v[182:185], v[214:217], v[0:3]
	v_mfma_f32_16x16x32_bf16 v[52:55], v[178:181], v[194:197], v[52:55]
	v_mfma_f32_16x16x32_bf16 v[48:51], v[186:189], v[194:197], v[48:51]
	v_mfma_f32_16x16x32_bf16 v[36:39], v[178:181], v[202:205], v[36:39]
	v_mfma_f32_16x16x32_bf16 v[32:35], v[186:189], v[202:205], v[32:35]
	v_mfma_f32_16x16x32_bf16 v[20:23], v[178:181], v[210:213], v[20:23]
	v_mfma_f32_16x16x32_bf16 v[16:19], v[186:189], v[210:213], v[16:19]
	v_mfma_f32_16x16x32_bf16 v[4:7], v[178:181], v[218:221], v[4:7]
	v_mfma_f32_16x16x32_bf16 v[0:3], v[186:189], v[218:221], v[0:3]
	s_setprio 1
	s_barrier
; #define PG8_STAGE(bufoff, gbase, voff) do { _Pragma("unroll") for (int _i = 0; _i < 2; ++_i) \
;         __builtin_amdgcn_global_load_lds((const unsigned*)((const char*)(gbase) + (voff)[_i]), (PG8_LAS unsigned*)(lds + (bufoff) + ldsw + _i * 8192), 16, 0, 0); } while (0)
; #define PG8_LDA(dst, b, h) do { _Pragma("unroll") for (int m = 0; m < 4; ++m) _Pragma("unroll") for (int k = 0; k < 2; ++k) dst[m][k] = *(const PG8_LAS bf16x8*)(lds + PG8_SA(b, h) + aoff + m * 2048 + k * 1024); } while (0)
; #define PG8_LDB(dst, b, h) do { _Pragma("unroll") for (int n = 0; n < 2; ++n) _Pragma("unroll") for (int k = 0; k < 2; ++k) dst[n][k] = *(const PG8_LAS bf16x8*)(lds + PG8_SB(b, h) + boff + n * 2048 + k * 1024); } while (0)
; #define PG8_MMA(ai, bj, At, Bt) do { __builtin_amdgcn_s_setprio(1); _Pragma("unroll") for (int m = 0; m < 4; ++m) _Pragma("unroll") for (int n = 0; n < 2; ++n) _Pragma("unroll") for (int k = 0; k < 2; ++k) \
;         acc[ai][bj][m][n] = __builtin_amdgcn_mfma_f32_16x16x32_bf16(Bt[n][k], At[m][k], acc[ai][bj][m][n], 0, 0, 0); __builtin_amdgcn_s_setprio(0); } while (0)
; #define PG8_WAIT_V(n) asm volatile("s_waitcnt vmcnt(" #n ")" ::: "memory")
; #define PG8_WAIT_L(n) asm volatile("s_waitcnt lgkmcnt(" #n ")" ::: "memory")
; #define PG8_BAR __builtin_amdgcn_s_barrier()
; #define PG8_SCHED __builtin_amdgcn_sched_barrier(0)
; template <class Epi, class Sched, bool ALIGN_EPI = false, bool SP2 = false>
; __device__ __forceinline__ void gemm_phase(PG8_LAS unsigned char* lds, const Gemm g, const Sched& S, const Epi& E) {
;     ...
;             PG8_LDB(B0, 1, 0); PG8_LDB(B1, 1, 1); PG8_SCHED; PG8_LDA(At, 1, 0); PG8_STAGE(PG8_SA(0, 1), a2 + hstepA, voffA);
;             PG8_WAIT_V(8); PG8_WAIT_L(0); PG8_BAR; PG8_MMA(0, 0, At, B0); PG8_MMA(0, 1, At, B1); PG8_BAR; PG8_SCHED;
;             PG8_LDA(At, 1, 1); PG8_STAGE(PG8_SB(1, 0), b3, voffB); PG8_STAGE(PG8_SB(1, 1), b3 + hstepB, voffB); PG8_STAGE(PG8_SA(1, 0), a3, voffA);
;             PG8_WAIT_V(8); PG8_WAIT_L(0); PG8_BAR; PG8_MMA(1, 0, At, B0); PG8_MMA(1, 1, At, B1); PG8_BAR; PG8_SCHED;
	s_add_i32 s63, 0, 0x18000
	v_add_u32_e32 v163, s63, v151
	s_add_i32 s64, 0, 0x1c000
	ds_read_b128 v[144:147], v163
	ds_read_b128 v[156:159], v163 offset:1024
	ds_read_b128 v[166:169], v163 offset:2048
	ds_read_b128 v[170:173], v163 offset:3072
	v_add_u32_e32 v163, s64, v151
	ds_read_b128 v[174:177], v163
	ds_read_b128 v[178:181], v163 offset:1024
	ds_read_b128 v[182:185], v163 offset:2048
	ds_read_b128 v[186:189], v163 offset:3072
	s_add_u32 s48, s48, 0x80000
	s_addc_u32 s49, s49, 0
	s_mov_b32 m0, s33
	ds_read_b128 v[190:193], v155 offset:32768
	ds_read_b128 v[194:197], v155 offset:33792
	ds_read_b128 v[198:201], v155 offset:34816
	ds_read_b128 v[202:205], v155 offset:35840
	ds_read_b128 v[206:209], v155 offset:36864
	ds_read_b128 v[210:213], v155 offset:37888
	ds_read_b128 v[214:217], v155 offset:38912
	ds_read_b128 v[218:221], v155 offset:39936
	global_load_lds_dwordx4 v134, s[48:49]
	s_mov_b32 m0, s34
	s_nop 0
	global_load_lds_dwordx4 v130, s[48:49]
	s_waitcnt vmcnt(8)
	s_waitcnt lgkmcnt(0)
	s_barrier
	s_setprio 0
	s_waitcnt lgkmcnt(0)
	v_mfma_f32_16x16x32_bf16 v[124:127], v[144:147], v[190:193], v[124:127]
	v_mfma_f32_16x16x32_bf16 v[120:123], v[166:169], v[190:193], v[120:123]
	v_mfma_f32_16x16x32_bf16 v[108:111], v[144:147], v[198:201], v[108:111]
	v_mfma_f32_16x16x32_bf16 v[104:107], v[166:169], v[198:201], v[104:107]
	v_mfma_f32_16x16x32_bf16 v[92:95], v[144:147], v[206:209], v[92:95]
	v_mfma_f32_16x16x32_bf16 v[88:91], v[166:169], v[206:209], v[88:91]
	v_mfma_f32_16x16x32_bf16 v[76:79], v[144:147], v[214:217], v[76:79]
	v_mfma_f32_16x16x32_bf16 v[72:75], v[166:169], v[214:217], v[72:75]
	v_mfma_f32_16x16x32_bf16 v[124:127], v[156:159], v[194:197], v[124:127]
	v_mfma_f32_16x16x32_bf16 v[120:123], v[170:173], v[194:197], v[120:123]
	v_mfma_f32_16x16x32_bf16 v[108:111], v[156:159], v[202:205], v[108:111]
	v_mfma_f32_16x16x32_bf16 v[104:107], v[170:173], v[202:205], v[104:107]
	v_mfma_f32_16x16x32_bf16 v[92:95], v[156:159], v[210:213], v[92:95]
	v_mfma_f32_16x16x32_bf16 v[88:91], v[170:173], v[210:213], v[88:91]
	v_mfma_f32_16x16x32_bf16 v[76:79], v[156:159], v[218:221], v[76:79]
	v_mfma_f32_16x16x32_bf16 v[72:75], v[170:173], v[218:221], v[72:75]
	v_mfma_f32_16x16x32_bf16 v[116:119], v[174:177], v[190:193], v[116:119]
	v_mfma_f32_16x16x32_bf16 v[112:115], v[182:185], v[190:193], v[112:115]
	v_mfma_f32_16x16x32_bf16 v[100:103], v[174:177], v[198:201], v[100:103]
	v_mfma_f32_16x16x32_bf16 v[96:99], v[182:185], v[198:201], v[96:99]
	v_mfma_f32_16x16x32_bf16 v[84:87], v[174:177], v[206:209], v[84:87]
	v_mfma_f32_16x16x32_bf16 v[80:83], v[182:185], v[206:209], v[80:83]
	v_mfma_f32_16x16x32_bf16 v[68:71], v[174:177], v[214:217], v[68:71]
	v_mfma_f32_16x16x32_bf16 v[64:67], v[182:185], v[214:217], v[64:67]
	v_mfma_f32_16x16x32_bf16 v[116:119], v[178:181], v[194:197], v[116:119]
	v_mfma_f32_16x16x32_bf16 v[112:115], v[186:189], v[194:197], v[112:115]
	v_mfma_f32_16x16x32_bf16 v[100:103], v[178:181], v[202:205], v[100:103]
	v_mfma_f32_16x16x32_bf16 v[96:99], v[186:189], v[202:205], v[96:99]
	v_mfma_f32_16x16x32_bf16 v[84:87], v[178:181], v[210:213], v[84:87]
	v_mfma_f32_16x16x32_bf16 v[80:83], v[186:189], v[210:213], v[80:83]
	v_mfma_f32_16x16x32_bf16 v[68:71], v[178:181], v[218:221], v[68:71]
	v_mfma_f32_16x16x32_bf16 v[64:67], v[186:189], v[218:221], v[64:67]
	s_setprio 1
	s_barrier
	s_add_i32 s48, s63, s28
	v_lshl_add_u64 v[148:149], v[148:149], 0, s[10:11]
	s_mov_b32 m0, s48
	ds_read_b128 v[190:193], v155 offset:49152
	ds_read_b128 v[194:197], v155 offset:50176
	ds_read_b128 v[198:201], v155 offset:51200
	ds_read_b128 v[202:205], v155 offset:52224
	ds_read_b128 v[206:209], v155 offset:53248
	ds_read_b128 v[210:213], v155 offset:54272
	ds_read_b128 v[214:217], v155 offset:55296
	ds_read_b128 v[218:221], v155 offset:56320
	global_load_lds_dwordx4 v[148:149], off
	s_add_i32 m0, s48, 0x2000
	s_add_u32 s46, s46, 0x80080
	v_lshl_add_u64 v[148:149], v[160:161], 0, s[10:11]
	s_addc_u32 s47, s47, 0
	s_add_i32 s48, s64, s28
	global_load_lds_dwordx4 v[148:149], off
	s_mov_b32 m0, s48
	s_nop 0
	global_load_lds_dwordx4 v132, s[46:47]
	s_add_i32 m0, s48, 0x2000
	s_nop 0
	global_load_lds_dwordx4 v128, s[46:47]
	v_lshl_add_u64 v[148:149], v[222:223], 0, s[10:11]
	s_mov_b32 m0, s43
	s_nop 0
	global_load_lds_dwordx4 v[148:149], off
	v_lshl_add_u64 v[148:149], v[224:225], 0, s[10:11]
	s_mov_b32 m0, s50
	s_nop 0
	global_load_lds_dwordx4 v[148:149], off
	s_waitcnt vmcnt(8)
	s_waitcnt lgkmcnt(0)
	s_barrier
	s_setprio 0
	s_waitcnt lgkmcnt(0)
	v_mfma_f32_16x16x32_bf16 v[60:63], v[144:147], v[190:193], v[60:63]
	v_mfma_f32_16x16x32_bf16 v[56:59], v[166:169], v[190:193], v[56:59]
	v_mfma_f32_16x16x32_bf16 v[44:47], v[144:147], v[198:201], v[44:47]
	v_mfma_f32_16x16x32_bf16 v[40:43], v[166:169], v[198:201], v[40:43]
	v_mfma_f32_16x16x32_bf16 v[28:31], v[144:147], v[206:209], v[28:31]
	v_mfma_f32_16x16x32_bf16 v[24:27], v[166:169], v[206:209], v[24:27]
	v_mfma_f32_16x16x32_bf16 v[12:15], v[144:147], v[214:217], v[12:15]
	v_mfma_f32_16x16x32_bf16 v[8:11], v[166:169], v[214:217], v[8:11]
	v_mfma_f32_16x16x32_bf16 v[60:63], v[156:159], v[194:197], v[60:63]
	v_mfma_f32_16x16x32_bf16 v[56:59], v[170:173], v[194:197], v[56:59]
	v_mfma_f32_16x16x32_bf16 v[44:47], v[156:159], v[202:205], v[44:47]
	v_mfma_f32_16x16x32_bf16 v[40:43], v[170:173], v[202:205], v[40:43]
	v_mfma_f32_16x16x32_bf16 v[28:31], v[156:159], v[210:213], v[28:31]
	v_mfma_f32_16x16x32_bf16 v[24:27], v[170:173], v[210:213], v[24:27]
	v_mfma_f32_16x16x32_bf16 v[12:15], v[156:159], v[218:221], v[12:15]
	v_mfma_f32_16x16x32_bf16 v[8:11], v[170:173], v[218:221], v[8:11]
	v_mfma_f32_16x16x32_bf16 v[52:55], v[174:177], v[190:193], v[52:55]
	v_mfma_f32_16x16x32_bf16 v[48:51], v[182:185], v[190:193], v[48:51]
	v_mfma_f32_16x16x32_bf16 v[36:39], v[174:177], v[198:201], v[36:39]
	v_mfma_f32_16x16x32_bf16 v[32:35], v[182:185], v[198:201], v[32:35]
	v_mfma_f32_16x16x32_bf16 v[20:23], v[174:177], v[206:209], v[20:23]
	v_mfma_f32_16x16x32_bf16 v[16:19], v[182:185], v[206:209], v[16:19]
	v_mfma_f32_16x16x32_bf16 v[4:7], v[174:177], v[214:217], v[4:7]
	v_mfma_f32_16x16x32_bf16 v[0:3], v[182:185], v[214:217], v[0:3]
	v_mfma_f32_16x16x32_bf16 v[52:55], v[178:181], v[194:197], v[52:55]
	v_mfma_f32_16x16x32_bf16 v[48:51], v[186:189], v[194:197], v[48:51]
	v_mfma_f32_16x16x32_bf16 v[36:39], v[178:181], v[202:205], v[36:39]
	v_mfma_f32_16x16x32_bf16 v[32:35], v[186:189], v[202:205], v[32:35]
	v_mfma_f32_16x16x32_bf16 v[20:23], v[178:181], v[210:213], v[20:23]
	v_mfma_f32_16x16x32_bf16 v[16:19], v[186:189], v[210:213], v[16:19]
	v_mfma_f32_16x16x32_bf16 v[4:7], v[178:181], v[218:221], v[4:7]
	v_mfma_f32_16x16x32_bf16 v[0:3], v[186:189], v[218:221], v[0:3]
	s_add_i32 s62, s62, 2
	s_add_u32 s44, s44, 0x100
	s_addc_u32 s45, s45, 0
	s_add_u32 s60, s60, 0x100
	s_addc_u32 s61, s61, 0
	s_cmp_gt_u32 s62, 29
	s_setprio 1
	s_barrier
	s_cbranch_scc0 .LBB0_1333
	s_and_b64 vcc, exec, s[14:15]
	s_cbranch_vccz .LBB0_1336
	s_barrier
